# residual epilogue software-pipelined: next pass residual tile prefetched into a second register set, pass-0 loads issued before setup/barrier
# speedup vs baseline: 1.0102x; 1.0102x over previous
; #define GA_LOAD(pr_) do { _Pragma("unroll") for (int i = 0; i < 4; ++i) ra[i] = *(const u32x4*)(Ab + (i * 32) * lda + (pr_) * 64); } while (0)
; #define GB_LOAD(kt_) do { const bfr* bk_ = Bb + (kt_) * NB * 32; \
;     _Pragma("unroll") for (int i = 0; i < 4; ++i) rb[i] = *(const u32x4*)(bk_ + (i * 64) * 32); } while (0)
; #define G_STORE(kt_) do { bfr* as_ = S0 + ((kt_) & 1) * GSTAGE; bfr* bs_ = as_ + 128 * 40; \
;     if (apar == ((kt_) & 1)) { _Pragma("unroll") for (int i = 0; i < 4; ++i) *(u32x4*)(as_ + asoff + i * 32 * 40) = ra[i]; } \
;     _Pragma("unroll") for (int i = 0; i < 4; ++i) *(u32x4*)(bs_ + bsoff + i * 64 * 40) = rb[i]; } while (0)
; template <int lda>
; DI void gemm_mainloop(const bfr* __restrict__ A, const bfr* __restrict__ Bt, int NB, int K, int m0, int n0, char* smem, f32x16 (&acc)[2][4]) {
;   bfr* S0 = (bfr*)smem;
;   int tid = threadIdx.x;
;   asm volatile("" : "+v"(tid));
;   const int lane = tid & 63, wid = tid >> 6, wr = wid >> 1, wc = wid & 1;
;   const int r = lane & 31, hl = lane >> 5;
; #pragma unroll
;   for (int i = 0; i < 2; ++i)
; #pragma unroll
;     for (int j = 0; j < 4; ++j)
; #pragma unroll
;       for (int q = 0; q < 16; ++q) acc[i][j][q] = 0.f;
;   u32x4 ra[4], rb[4];
;   const int nk = K >> 5;
;   const int arow = tid >> 3, ac8 = tid & 7, apar = ac8 >> 2;
;   const bfr* Ab = A + (m0 + arow) * lda + ac8 * 8;
;   const int asoff = arow * 40 + (ac8 & 3) * 8;
;   const int brow = tid >> 2, bc4 = tid & 3;
;   const bfr* Bb = Bt + (n0 + brow) * 32 + bc4 * 8;
;   const int bsoff = brow * 40 + bc4 * 8;
;     ...
;   GA_LOAD(0);
;   GB_LOAD(0);
;   G_STORE(0);
;   GB_LOAD(1);
;   __syncthreads();
; template <bool FIRST, bool HAS_H>
; DI void phase_gemm_resid(const Params& p, const bfr* A, const bfr* Wt, const float* gnext, float* ss, char* smem) {
;     ...
;   for (int t0 = blockIdx.x; t0 < 128 * 4; t0 += gridDim.x) {
;     const int t = ((gridDim.x & 7) == 0) ? xcd_tile(t0, 4) : t0;
;     const int mt = t >> 2, nt = t & 3, m0 = mt * 128, n0 = nt * 256;
;     f32x16 acc[2][4];
;     gemm_mainloop<1024>(A, Wt, 1024, 1024, m0, n0, smem, acc);
.LBB0_843:
	s_lshl_b32 s5, s4, 5
	s_and_b32 s40, s5, 0xffffff80
	s_lshl_b32 s4, s4, 8
	s_and_b32 s39, s4, 0x300
	s_mov_b32 s41, 0
	s_mov_b64 s[24:25], 0
	s_lshl_b32 s98, s40, 11
	s_add_u32 s98, s12, s98
	s_addc_u32 s99, s13, 0
	s_lshl_b32 s100, s39, 6
	s_add_u32 s100, s6, s100
	s_addc_u32 s101, s7, 0
	v_writelane_b32 v207, s64, 0
	v_writelane_b32 v207, s65, 1
	v_writelane_b32 v207, s66, 2
	v_writelane_b32 v207, s67, 3
	v_writelane_b32 v207, s68, 4
	v_writelane_b32 v207, s69, 5
	v_writelane_b32 v207, s70, 6
	v_writelane_b32 v207, s71, 7
	v_writelane_b32 v207, s72, 8
	v_writelane_b32 v207, s73, 9
	v_writelane_b32 v207, s74, 10
	v_writelane_b32 v207, s75, 11
	v_writelane_b32 v207, s76, 12
	v_writelane_b32 v207, s77, 13
	v_writelane_b32 v207, s78, 14
	v_writelane_b32 v207, s79, 15
	s_mov_b32 s77, s40
	s_mov_b32 s78, s39
	v_lshrrev_b32_e32 v208, 6, v196
	v_and_b32_e32 v209, 63, v196
	v_readfirstlane_b32 s73, v208
	v_lshrrev_b32_e32 v210, 2, v209
	v_bfe_u32 v211, v209, 4, 2
	v_and_b32_e32 v208, 3, v209
	v_xor_b32_e32 v208, v208, v211
	v_lshlrev_b32_e32 v208, 4, v208
	v_lshl_add_u32 v188, v210, 11, v208
	v_add_u32_e32 v190, 0x8000, v188
	v_lshl_add_u32 v191, v210, 6, v208
	v_and_b32_e32 v210, 31, v209
	v_lshrrev_b32_e32 v211, 5, v209
	v_bfe_u32 v208, v209, 2, 2
	v_xor_b32_e32 v208, v208, v211
	v_lshlrev_b32_e32 v208, 4, v208
	v_lshl_add_u32 v192, v210, 6, v208
	s_lshr_b32 s74, s73, 1
	s_lshl_b32 s74, s74, 12
	s_and_b32 s75, s73, 1
	s_lshl_b32 s75, s75, 13
	v_add_u32_e32 v194, s75, v192
	v_add_u32_e32 v192, s74, v192
	v_xor_b32_e32 v198, 32, v194
	v_xor_b32_e32 v193, 32, v192
	s_lshl_b32 s74, s73, 16
	s_add_u32 s64, s98, s74
	s_addc_u32 s65, s99, 0
	s_lshl_b32 s74, s73, 12
	s_add_u32 s66, s100, s74
	s_addc_u32 s67, s101, 0
	s_lshl_b32 s68, s73, 11
	s_lshl_b32 s69, s73, 12
	s_mov_b32 s70, 0
	s_mov_b32 s71, 0
	s_mov_b32 s72, 0
	s_waitcnt lgkmcnt(0)
	s_barrier
	s_mul_i32 s74, s70, 0x6000
	s_add_u32 s75, s74, s68
	s_mov_b32 m0, s75
	s_add_u32 s76, s74, 0x2000
	s_cmp_eq_u32 s70, 2
	s_cselect_b32 s76, 0x10000, s76
	global_load_lds_dwordx4 v188, s[64:65]
	s_add_u32 m0, s75, 0x400
	s_add_u32 s76, s76, s69
	global_load_lds_dwordx4 v190, s[64:65]
	s_mov_b32 m0, s76
	s_add_u32 s64, s64, 64
	s_addc_u32 s65, s65, 0
	global_load_lds_dwordx4 v191, s[66:67]
	global_load_lds_dwordx4 v191, s[66:67] offset:1024
	global_load_lds_dwordx4 v191, s[66:67] offset:2048
	global_load_lds_dwordx4 v191, s[66:67] offset:3072
	s_add_u32 s66, s66, 0x10000
	s_addc_u32 s67, s67, 0
	s_add_u32 s70, s70, 1
	s_cmp_eq_u32 s70, 3
	s_cselect_b32 s70, 0, s70
	s_mul_i32 s74, s70, 0x6000
	s_add_u32 s75, s74, s68
	s_mov_b32 m0, s75
	s_add_u32 s76, s74, 0x2000
	s_cmp_eq_u32 s70, 2
	s_cselect_b32 s76, 0x10000, s76
	global_load_lds_dwordx4 v188, s[64:65]
	s_add_u32 m0, s75, 0x400
	s_add_u32 s76, s76, s69
	global_load_lds_dwordx4 v190, s[64:65]
	s_mov_b32 m0, s76
	s_add_u32 s64, s64, 64
	s_addc_u32 s65, s65, 0
	global_load_lds_dwordx4 v191, s[66:67]
	global_load_lds_dwordx4 v191, s[66:67] offset:1024
	global_load_lds_dwordx4 v191, s[66:67] offset:2048
	global_load_lds_dwordx4 v191, s[66:67] offset:3072
	s_add_u32 s66, s66, 0x10000
	s_addc_u32 s67, s67, 0
	s_add_u32 s70, s70, 1
	s_cmp_eq_u32 s70, 3
	s_cselect_b32 s70, 0, s70
	s_cmp_lt_u32 s46, 0x100
	s_cbranch_scc1 .Lp6_nostag
	s_sleep 8

; #define MFMA32(a, b, c) __builtin_amdgcn_mfma_f32_32x32x16_bf16((a), (b), (c), 0, 0, 0)
; #define GA_LOAD(pr_) do { _Pragma("unroll") for (int i = 0; i < 4; ++i) ra[i] = *(const u32x4*)(Ab + (i * 32) * lda + (pr_) * 64); } while (0)
; #define GB_LOAD(kt_) do { const bfr* bk_ = Bb + (kt_) * NB * 32; \
;     _Pragma("unroll") for (int i = 0; i < 4; ++i) rb[i] = *(const u32x4*)(bk_ + (i * 64) * 32); } while (0)
; #define G_STORE(kt_) do { bfr* as_ = S0 + ((kt_) & 1) * GSTAGE; bfr* bs_ = as_ + 128 * 40; \
;     if (apar == ((kt_) & 1)) { _Pragma("unroll") for (int i = 0; i < 4; ++i) *(u32x4*)(as_ + asoff + i * 32 * 40) = ra[i]; } \
;     _Pragma("unroll") for (int i = 0; i < 4; ++i) *(u32x4*)(bs_ + bsoff + i * 64 * 40) = rb[i]; } while (0)
; template <int lda>
; DI void gemm_mainloop(const bfr* __restrict__ A, const bfr* __restrict__ Bt, int NB, int K, int m0, int n0, char* smem, f32x16 (&acc)[2][4]) {
;     ...
;   for (int kt = 0; kt < nk; ++kt) {
;     if (kt + 1 < nk) G_STORE(kt + 1);
;     if (kt + 2 < nk) {
;       GB_LOAD(kt + 2);
;       if ((kt & 1) == 0) GA_LOAD((kt >> 1) + 1);
;     }
;     const bfr* As = S0 + (kt & 1) * GSTAGE;
;     const bfr* Bs = As + 128 * 40;
; #pragma unroll
;     for (int ks = 0; ks < 2; ++ks) {
;       bf16x8 af[2], bfg[4];
; #pragma unroll
;       for (int i = 0; i < 2; ++i) af[i] = *(const bf16x8*)(As + (wr * 64 + i * 32 + r) * 40 + ks * 16 + hl * 8);
; #pragma unroll
;       for (int j = 0; j < 4; ++j) bfg[j] = *(const bf16x8*)(Bs + (wc * 128 + j * 32 + r) * 40 + ks * 16 + hl * 8);
; #pragma unroll
;       for (int i = 0; i < 2; ++i)
; #pragma unroll
;         for (int j = 0; j < 4; ++j) acc[i][j] = MFMA32(af[i], bfg[j], acc[i][j]);
;     }
;     __syncthreads();
;   }
.Lp6_loop:
	s_waitcnt vmcnt(6)
	s_barrier
	s_mul_i32 s74, s71, 0x6000
	s_add_u32 s75, s74, 0x2000
	s_cmp_eq_u32 s71, 2
	s_cselect_b32 s75, 0x10000, s75
	v_add_u32_e32 v199, s74, v192
	v_add_u32_e32 v205, s75, v194
	v_add_u32_e32 v204, s74, v193
	v_add_u32_e32 v206, s75, v198
	ds_read_b128 v[128:131], v199
	ds_read_b128 v[144:147], v205
	ds_read_b128 v[148:151], v205 offset:2048
	ds_read_b128 v[152:155], v205 offset:4096
	ds_read_b128 v[156:159], v205 offset:6144
	ds_read_b128 v[132:135], v199 offset:2048
	ds_read_b128 v[136:139], v204
	ds_read_b128 v[160:163], v206
	ds_read_b128 v[164:167], v206 offset:2048
	ds_read_b128 v[168:171], v206 offset:4096
	ds_read_b128 v[172:175], v206 offset:6144
	ds_read_b128 v[140:143], v204 offset:2048
	s_add_u32 s71, s71, 1
	s_cmp_eq_u32 s71, 3
	s_cselect_b32 s71, 0, s71
	s_waitcnt lgkmcnt(10)
	v_mfma_f32_32x32x16_bf16 v[112:127], v[144:147], v[128:131], v[112:127]
	s_mul_i32 s74, s70, 0x6000
	s_add_u32 s75, s74, s68
	s_mov_b32 m0, s75
	s_add_u32 s76, s74, 0x2000
	s_cmp_eq_u32 s70, 2
	s_cselect_b32 s76, 0x10000, s76
	global_load_lds_dwordx4 v188, s[64:65]
	s_waitcnt lgkmcnt(9)
	v_mfma_f32_32x32x16_bf16 v[96:111], v[148:151], v[128:131], v[96:111]
	s_add_u32 m0, s75, 0x400
	s_add_u32 s76, s76, s69
	global_load_lds_dwordx4 v190, s[64:65]
	s_waitcnt lgkmcnt(8)
	v_mfma_f32_32x32x16_bf16 v[80:95], v[152:155], v[128:131], v[80:95]
	s_mov_b32 m0, s76
	s_add_u32 s64, s64, 64
	s_addc_u32 s65, s65, 0
	global_load_lds_dwordx4 v191, s[66:67]
	s_waitcnt lgkmcnt(7)
	v_mfma_f32_32x32x16_bf16 v[64:79], v[156:159], v[128:131], v[64:79]
	global_load_lds_dwordx4 v191, s[66:67] offset:1024
	s_waitcnt lgkmcnt(6)
	v_mfma_f32_32x32x16_bf16 v[48:63], v[144:147], v[132:135], v[48:63]
	global_load_lds_dwordx4 v191, s[66:67] offset:2048
	v_mfma_f32_32x32x16_bf16 v[32:47], v[148:151], v[132:135], v[32:47]
	global_load_lds_dwordx4 v191, s[66:67] offset:3072
	s_add_u32 s66, s66, 0x10000
	s_addc_u32 s67, s67, 0
	v_mfma_f32_32x32x16_bf16 v[16:31], v[152:155], v[132:135], v[16:31]
	s_add_u32 s70, s70, 1
	s_cmp_eq_u32 s70, 3
	s_cselect_b32 s70, 0, s70
	v_mfma_f32_32x32x16_bf16 v[0:15], v[156:159], v[132:135], v[0:15]
	s_waitcnt lgkmcnt(4)
	v_mfma_f32_32x32x16_bf16 v[112:127], v[160:163], v[136:139], v[112:127]
	s_waitcnt lgkmcnt(3)
	v_mfma_f32_32x32x16_bf16 v[96:111], v[164:167], v[136:139], v[96:111]
	s_waitcnt lgkmcnt(2)
	v_mfma_f32_32x32x16_bf16 v[80:95], v[168:171], v[136:139], v[80:95]
	s_waitcnt lgkmcnt(1)
	v_mfma_f32_32x32x16_bf16 v[64:79], v[172:175], v[136:139], v[64:79]
	s_waitcnt lgkmcnt(0)
	v_mfma_f32_32x32x16_bf16 v[48:63], v[160:163], v[140:143], v[48:63]
	v_mfma_f32_32x32x16_bf16 v[32:47], v[164:167], v[140:143], v[32:47]
	v_mfma_f32_32x32x16_bf16 v[16:31], v[168:171], v[140:143], v[16:31]
	v_mfma_f32_32x32x16_bf16 v[0:15], v[172:175], v[140:143], v[0:15]
	s_add_u32 s72, s72, 1
	s_cmp_lt_u32 s72, 30
	s_cbranch_scc1 .Lp6_loop
	s_waitcnt vmcnt(6)
	s_barrier
	s_mul_i32 s74, s71, 0x6000
	s_add_u32 s75, s74, 0x2000
	s_cmp_eq_u32 s71, 2
	s_cselect_b32 s75, 0x10000, s75
	v_add_u32_e32 v199, s74, v192
	v_add_u32_e32 v205, s75, v194
	v_add_u32_e32 v204, s74, v193
	v_add_u32_e32 v206, s75, v198
	ds_read_b128 v[128:131], v199
	ds_read_b128 v[144:147], v205
	ds_read_b128 v[148:151], v205 offset:2048
	ds_read_b128 v[152:155], v205 offset:4096
	ds_read_b128 v[156:159], v205 offset:6144
	ds_read_b128 v[132:135], v199 offset:2048
	ds_read_b128 v[136:139], v204
	ds_read_b128 v[160:163], v206
	ds_read_b128 v[164:167], v206 offset:2048
	ds_read_b128 v[168:171], v206 offset:4096
	ds_read_b128 v[172:175], v206 offset:6144
	ds_read_b128 v[140:143], v204 offset:2048
	s_add_u32 s71, s71, 1
	s_cmp_eq_u32 s71, 3
	s_cselect_b32 s71, 0, s71
	s_waitcnt lgkmcnt(10)
	v_mfma_f32_32x32x16_bf16 v[112:127], v[144:147], v[128:131], v[112:127]
	s_waitcnt lgkmcnt(9)
	v_mfma_f32_32x32x16_bf16 v[96:111], v[148:151], v[128:131], v[96:111]
	s_waitcnt lgkmcnt(8)
	v_mfma_f32_32x32x16_bf16 v[80:95], v[152:155], v[128:131], v[80:95]
	s_waitcnt lgkmcnt(7)
	v_mfma_f32_32x32x16_bf16 v[64:79], v[156:159], v[128:131], v[64:79]
	s_waitcnt lgkmcnt(6)
	v_mfma_f32_32x32x16_bf16 v[48:63], v[144:147], v[132:135], v[48:63]
	v_mfma_f32_32x32x16_bf16 v[32:47], v[148:151], v[132:135], v[32:47]
	v_mfma_f32_32x32x16_bf16 v[16:31], v[152:155], v[132:135], v[16:31]
	v_mfma_f32_32x32x16_bf16 v[0:15], v[156:159], v[132:135], v[0:15]
	s_waitcnt lgkmcnt(4)
	v_mfma_f32_32x32x16_bf16 v[112:127], v[160:163], v[136:139], v[112:127]
	s_waitcnt lgkmcnt(3)
	v_mfma_f32_32x32x16_bf16 v[96:111], v[164:167], v[136:139], v[96:111]
	s_waitcnt lgkmcnt(2)
	v_mfma_f32_32x32x16_bf16 v[80:95], v[168:171], v[136:139], v[80:95]
	s_waitcnt lgkmcnt(1)
	v_mfma_f32_32x32x16_bf16 v[64:79], v[172:175], v[136:139], v[64:79]
	s_waitcnt lgkmcnt(0)
	v_mfma_f32_32x32x16_bf16 v[48:63], v[160:163], v[140:143], v[48:63]
	v_mfma_f32_32x32x16_bf16 v[32:47], v[164:167], v[140:143], v[32:47]
	v_mfma_f32_32x32x16_bf16 v[16:31], v[168:171], v[140:143], v[16:31]
	v_mfma_f32_32x32x16_bf16 v[0:15], v[172:175], v[140:143], v[0:15]
	s_waitcnt vmcnt(0)
	s_barrier
; #define MFMA32(a, b, c) __builtin_amdgcn_mfma_f32_32x32x16_bf16((a), (b), (c), 0, 0, 0)
; #define GA_LOAD(pr_) do { _Pragma("unroll") for (int i = 0; i < 4; ++i) ra[i] = *(const u32x4*)(Ab + (i * 32) * lda + (pr_) * 64); } while (0)
; #define GB_LOAD(kt_) do { const bfr* bk_ = Bb + (kt_) * NB * 32; \
;     _Pragma("unroll") for (int i = 0; i < 4; ++i) rb[i] = *(const u32x4*)(bk_ + (i * 64) * 32); } while (0)
; #define G_STORE(kt_) do { bfr* as_ = S0 + ((kt_) & 1) * GSTAGE; bfr* bs_ = as_ + 128 * 40; \
;     if (apar == ((kt_) & 1)) { _Pragma("unroll") for (int i = 0; i < 4; ++i) *(u32x4*)(as_ + asoff + i * 32 * 40) = ra[i]; } \
;     _Pragma("unroll") for (int i = 0; i < 4; ++i) *(u32x4*)(bs_ + bsoff + i * 64 * 40) = rb[i]; } while (0)
; template <int lda>
; DI void gemm_mainloop(const bfr* __restrict__ A, const bfr* __restrict__ Bt, int NB, int K, int m0, int n0, char* smem, f32x16 (&acc)[2][4]) {
;     ...
;   for (int kt = 0; kt < nk; ++kt) {
;     if (kt + 1 < nk) G_STORE(kt + 1);
;     if (kt + 2 < nk) {
;       GB_LOAD(kt + 2);
;       if ((kt & 1) == 0) GA_LOAD((kt >> 1) + 1);
;     }
;     const bfr* As = S0 + (kt & 1) * GSTAGE;
;     const bfr* Bs = As + 128 * 40;
; #pragma unroll
;     for (int ks = 0; ks < 2; ++ks) {
;       bf16x8 af[2], bfg[4];
; #pragma unroll
;       for (int i = 0; i < 2; ++i) af[i] = *(const bf16x8*)(As + (wr * 64 + i * 32 + r) * 40 + ks * 16 + hl * 8);
; #pragma unroll
;       for (int j = 0; j < 4; ++j) bfg[j] = *(const bf16x8*)(Bs + (wc * 128 + j * 32 + r) * 40 + ks * 16 + hl * 8);
; #pragma unroll
;       for (int i = 0; i < 2; ++i)
; #pragma unroll
;         for (int j = 0; j < 4; ++j) acc[i][j] = MFMA32(af[i], bfg[j], acc[i][j]);
;     }
;     __syncthreads();
;   }
; template <bool FIRST, bool HAS_H>
; DI void phase_gemm_resid(const Params& p, const bfr* A, const bfr* Wt, const float* gnext, float* ss, char* smem) {
;     ...
;     int tid2 = threadIdx.x;
;     asm volatile("" : "+v"(tid2));
;     const int lane = tid2 & 63, wid = tid2 >> 6, wr = wid >> 1, wc = wid & 1, r = lane & 31, hl = lane >> 5;
;     const float* xsrc = FIRST ? p.x_prompt : X;
;     const int rbase = m0 + wr * 64 + 4 * hl, cbase = n0 + wc * 128 + r;
	s_mul_i32 s74, s71, 0x6000
	s_add_u32 s75, s74, 0x2000
	s_cmp_eq_u32 s71, 2
	s_cselect_b32 s75, 0x10000, s75
	v_add_u32_e32 v199, s74, v192
	v_add_u32_e32 v205, s75, v194
	v_add_u32_e32 v204, s74, v193
	v_add_u32_e32 v206, s75, v198
	ds_read_b128 v[128:131], v199
	ds_read_b128 v[144:147], v205
	ds_read_b128 v[148:151], v205 offset:2048
	ds_read_b128 v[152:155], v205 offset:4096
	ds_read_b128 v[156:159], v205 offset:6144
	ds_read_b128 v[132:135], v199 offset:2048
	ds_read_b128 v[136:139], v204
	ds_read_b128 v[160:163], v206
	ds_read_b128 v[164:167], v206 offset:2048
	ds_read_b128 v[168:171], v206 offset:4096
	ds_read_b128 v[172:175], v206 offset:6144
	ds_read_b128 v[140:143], v204 offset:2048
	s_add_u32 s71, s71, 1
	s_cmp_eq_u32 s71, 3
	s_cselect_b32 s71, 0, s71
	s_waitcnt lgkmcnt(10)
	v_mfma_f32_32x32x16_bf16 v[112:127], v[144:147], v[128:131], v[112:127]
	s_waitcnt lgkmcnt(9)
	v_mfma_f32_32x32x16_bf16 v[96:111], v[148:151], v[128:131], v[96:111]
	s_waitcnt lgkmcnt(8)
	v_mfma_f32_32x32x16_bf16 v[80:95], v[152:155], v[128:131], v[80:95]
	s_waitcnt lgkmcnt(7)
	v_mfma_f32_32x32x16_bf16 v[64:79], v[156:159], v[128:131], v[64:79]
	s_waitcnt lgkmcnt(6)
	v_mfma_f32_32x32x16_bf16 v[48:63], v[144:147], v[132:135], v[48:63]
	v_mfma_f32_32x32x16_bf16 v[32:47], v[148:151], v[132:135], v[32:47]
	v_mfma_f32_32x32x16_bf16 v[16:31], v[152:155], v[132:135], v[16:31]
	v_mfma_f32_32x32x16_bf16 v[0:15], v[156:159], v[132:135], v[0:15]
	s_waitcnt lgkmcnt(4)
	v_mfma_f32_32x32x16_bf16 v[112:127], v[160:163], v[136:139], v[112:127]
	s_waitcnt lgkmcnt(3)
	v_mfma_f32_32x32x16_bf16 v[96:111], v[164:167], v[136:139], v[96:111]
	s_waitcnt lgkmcnt(2)
	v_mfma_f32_32x32x16_bf16 v[80:95], v[168:171], v[136:139], v[80:95]
	s_waitcnt lgkmcnt(1)
	v_mfma_f32_32x32x16_bf16 v[64:79], v[172:175], v[136:139], v[64:79]
	s_waitcnt lgkmcnt(0)
	v_mfma_f32_32x32x16_bf16 v[48:63], v[160:163], v[140:143], v[48:63]
	v_mfma_f32_32x32x16_bf16 v[32:47], v[164:167], v[140:143], v[32:47]
	v_mfma_f32_32x32x16_bf16 v[16:31], v[168:171], v[140:143], v[16:31]
	v_mfma_f32_32x32x16_bf16 v[0:15], v[172:175], v[140:143], v[0:15]
	s_nop 7
	s_nop 3
	s_load_dwordx2 s[64:65], s[92:93], 0x0
	s_load_dwordx2 s[66:67], s[92:93], 0x100
	s_load_dwordx2 s[68:69], s[92:93], 0x148
	s_load_dwordx2 s[70:71], s[92:93], 0x50
	s_mul_i32 s76, s73, 8704
	s_lshr_b32 s74, s73, 1
	s_lshl_b32 s74, s74, 6
	s_add_u32 s74, s74, s77
	s_and_b32 s75, s73, 1
	s_lshl_b32 s75, s75, 7
	s_add_u32 s75, s75, s78
	v_and_b32_e32 v208, 31, v196
	v_bfe_u32 v209, v196, 5, 1
	v_mul_u32_u24_e32 v210, 272, v208
	v_add_u32_e32 v210, s76, v210
	v_lshl_add_u32 v188, v209, 4, v210
	v_lshl_add_u32 v190, v209, 3, v210
	v_lshlrev_b32_e32 v210, 2, v209
	v_add_lshl_u32 v198, v210, s75, 2
	v_add_lshl_u32 v205, v208, s74, 2
	v_and_b32_e32 v210, 63, v196
	v_xor_b32_e32 v210, 32, v210
	v_lshlrev_b32_e32 v206, 2, v210
	v_bfe_u32 v208, v196, 4, 2
	v_and_b32_e32 v209, 15, v196
	v_mul_u32_u24_e32 v210, 272, v208
	v_lshl_add_u32 v210, v209, 4, v210
	v_add_u32_e32 v191, s76, v210
	v_add_u32_e32 v210, s74, v208
	v_lshlrev_b32_e32 v210, 10, v210
	v_lshl_add_u32 v210, v209, 2, v210
	v_add_lshl_u32 v193, v210, s75, 2
	s_mov_b32 s79, s74
	s_mov_b32 s72, s75
	s_waitcnt lgkmcnt(0)
	s_add_u32 s74, s64, 0x0
	s_addc_u32 s75, s65, 0
	global_load_dwordx4 v[128:131], v193, s[74:75]
	s_add_u32 s74, s64, 0x4000
	s_addc_u32 s75, s65, 0
	global_load_dwordx4 v[132:135], v193, s[74:75]
	s_add_u32 s74, s64, 0x8000
	s_addc_u32 s75, s65, 0
	global_load_dwordx4 v[136:139], v193, s[74:75]
	s_add_u32 s74, s64, 0xc000
	s_addc_u32 s75, s65, 0
	global_load_dwordx4 v[140:143], v193, s[74:75]
	s_add_u32 s74, s64, 0x10000
	s_addc_u32 s75, s65, 0
	global_load_dwordx4 v[144:147], v193, s[74:75]
	s_add_u32 s74, s64, 0x14000
	s_addc_u32 s75, s65, 0
	global_load_dwordx4 v[148:151], v193, s[74:75]
	s_add_u32 s74, s64, 0x18000
	s_addc_u32 s75, s65, 0
	global_load_dwordx4 v[152:155], v193, s[74:75]
	s_add_u32 s74, s64, 0x1c000
	s_addc_u32 s75, s65, 0
	global_load_dwordx4 v[156:159], v193, s[74:75]
	s_mov_b32 s74, s79
	s_mov_b32 s75, s72
	v_bfe_u32 v208, v196, 3, 3
	v_and_b32_e32 v209, 7, v196
	v_mul_u32_u24_e32 v210, 272, v208
	v_lshl_add_u32 v210, v209, 4, v210
	v_add_u32_e32 v192, s76, v210
	v_add_u32_e32 v210, s74, v208
	v_lshlrev_b32_e32 v210, 10, v210
	v_lshl_add_u32 v210, v209, 3, v210
	v_add_lshl_u32 v194, v210, s75, 1
	v_mov_b32_e32 v199, 0
	v_mov_b32_e32 v204, 0
	s_waitcnt lgkmcnt(0)
	s_barrier
; DI bfr f2bf(float a) { return (bfr)(pack2(a, 0.f) & 0xffffu); }
; DI int crow(int reg, int h) { return (reg & 3) + 8 * (reg >> 2) + 4 * h; }
; template <bool FIRST, bool HAS_H>
; DI void phase_gemm_resid(const Params& p, const bfr* A, const bfr* Wt, const float* gnext, float* ss, char* smem) {
;     ...
; #pragma unroll
;     for (int i = 0; i < 2; ++i) {
; #pragma unroll
;       for (int qh = 0; qh < 2; ++qh) {
;         float rs[8];
; #pragma unroll
;         for (int q = 0; q < 8; ++q) rs[q] = 0.f;
; #pragma unroll
;         for (int jh = 0; jh < 2; ++jh) {
;           float xo[2][8];
; #pragma unroll
;           for (int jj = 0; jj < 2; ++jj)
; #pragma unroll
;             for (int q = 0; q < 8; ++q)
;               xo[jj][q] = xsrc[(rbase + i * 32 + crow(qh * 8 + q, 0)) * 1024 + cbase + (jh * 2 + jj) * 32];
; #pragma unroll
;           for (int q = 0; q < 8; ++q) {
;             const int o = (rbase + i * 32 + crow(qh * 8 + q, 0)) * 1024 + cbase;
; #pragma unroll
;             for (int jj = 0; jj < 2; ++jj) {
;               const int j = jh * 2 + jj;
;               const float xn = xo[jj][q] + acc[i][j][qh * 8 + q];
;               X[o + j * 32] = xn;
;               if (HAS_H) Hn[o + j * 32] = f2bf(xn * gnext[cbase + j * 32]);
;               rs[q] += xn * xn;
	s_waitcnt vmcnt(7)
	ds_write_b128 v191, v[128:131]
	s_waitcnt vmcnt(6)
	ds_write_b128 v191, v[132:135] offset:1088
	s_waitcnt vmcnt(5)
	ds_write_b128 v191, v[136:139] offset:2176
	s_waitcnt vmcnt(4)
	ds_write_b128 v191, v[140:143] offset:3264
	s_waitcnt vmcnt(3)
	ds_write_b128 v191, v[144:147] offset:4352
	s_waitcnt vmcnt(2)
	ds_write_b128 v191, v[148:151] offset:5440
	s_waitcnt vmcnt(1)
	ds_write_b128 v191, v[152:155] offset:6528
	s_waitcnt vmcnt(0)
	ds_write_b128 v191, v[156:159] offset:7616
	s_add_u32 s74, s64, 0x100
	s_addc_u32 s75, s65, 0
	global_load_dwordx4 v[128:131], v193, s[74:75]
	s_add_u32 s74, s64, 0x4100
	s_addc_u32 s75, s65, 0
	global_load_dwordx4 v[132:135], v193, s[74:75]
	s_add_u32 s74, s64, 0x8100
	s_addc_u32 s75, s65, 0
	global_load_dwordx4 v[136:139], v193, s[74:75]
	s_add_u32 s74, s64, 0xc100
	s_addc_u32 s75, s65, 0
	global_load_dwordx4 v[140:143], v193, s[74:75]
	s_add_u32 s74, s64, 0x10100
	s_addc_u32 s75, s65, 0
	global_load_dwordx4 v[144:147], v193, s[74:75]
	s_add_u32 s74, s64, 0x14100
	s_addc_u32 s75, s65, 0
	global_load_dwordx4 v[148:151], v193, s[74:75]
	s_add_u32 s74, s64, 0x18100
	s_addc_u32 s75, s65, 0
	global_load_dwordx4 v[152:155], v193, s[74:75]
	s_add_u32 s74, s64, 0x1c100
	s_addc_u32 s75, s65, 0
	global_load_dwordx4 v[156:159], v193, s[74:75]
	ds_read_b128 v[160:163], v188
	ds_read_b128 v[164:167], v188 offset:32
	ds_read_b128 v[168:171], v188 offset:64
	ds_read_b128 v[172:175], v188 offset:96
	ds_read_b128 v[176:179], v188 offset:128
	ds_read_b128 v[180:183], v188 offset:160
	ds_read_b128 v[184:187], v188 offset:192
	ds_read_b128 v[200:203], v188 offset:224
	s_waitcnt lgkmcnt(7)
	v_add_f32_e32 v112, v160, v112
	v_add_f32_e32 v113, v161, v113
	v_add_f32_e32 v114, v162, v114
	v_add_f32_e32 v115, v163, v115
	v_fmac_f32_e32 v199, v112, v112
	v_fmac_f32_e32 v199, v113, v113
	v_fmac_f32_e32 v199, v114, v114
	v_fmac_f32_e32 v199, v115, v115
	ds_write_b128 v188, v[112:115]
	s_waitcnt lgkmcnt(7)
	v_add_f32_e32 v116, v164, v116
	v_add_f32_e32 v117, v165, v117
	v_add_f32_e32 v118, v166, v118
	v_add_f32_e32 v119, v167, v119
	v_fmac_f32_e32 v199, v116, v116
	v_fmac_f32_e32 v199, v117, v117
	v_fmac_f32_e32 v199, v118, v118
	v_fmac_f32_e32 v199, v119, v119
	ds_write_b128 v188, v[116:119] offset:32
	s_waitcnt lgkmcnt(7)
	v_add_f32_e32 v120, v168, v120
	v_add_f32_e32 v121, v169, v121
	v_add_f32_e32 v122, v170, v122
	v_add_f32_e32 v123, v171, v123
	v_fmac_f32_e32 v199, v120, v120
	v_fmac_f32_e32 v199, v121, v121
	v_fmac_f32_e32 v199, v122, v122
	v_fmac_f32_e32 v199, v123, v123
	ds_write_b128 v188, v[120:123] offset:64
	s_waitcnt lgkmcnt(7)
	v_add_f32_e32 v124, v172, v124
	v_add_f32_e32 v125, v173, v125
	v_add_f32_e32 v126, v174, v126
	v_add_f32_e32 v127, v175, v127
	v_fmac_f32_e32 v199, v124, v124
	v_fmac_f32_e32 v199, v125, v125
	v_fmac_f32_e32 v199, v126, v126
	v_fmac_f32_e32 v199, v127, v127
	ds_write_b128 v188, v[124:127] offset:96
	s_waitcnt lgkmcnt(7)
	v_add_f32_e32 v96, v176, v96
	v_add_f32_e32 v97, v177, v97
	v_add_f32_e32 v98, v178, v98
	v_add_f32_e32 v99, v179, v99
	v_fmac_f32_e32 v199, v96, v96
	v_fmac_f32_e32 v199, v97, v97
	v_fmac_f32_e32 v199, v98, v98
	v_fmac_f32_e32 v199, v99, v99
	ds_write_b128 v188, v[96:99] offset:128
	s_waitcnt lgkmcnt(7)
	v_add_f32_e32 v100, v180, v100
	v_add_f32_e32 v101, v181, v101
	v_add_f32_e32 v102, v182, v102
	v_add_f32_e32 v103, v183, v103
	v_fmac_f32_e32 v199, v100, v100
	v_fmac_f32_e32 v199, v101, v101
	v_fmac_f32_e32 v199, v102, v102
	v_fmac_f32_e32 v199, v103, v103
	ds_write_b128 v188, v[100:103] offset:160
	s_waitcnt lgkmcnt(7)
	v_add_f32_e32 v104, v184, v104
	v_add_f32_e32 v105, v185, v105
	v_add_f32_e32 v106, v186, v106
	v_add_f32_e32 v107, v187, v107
	v_fmac_f32_e32 v199, v104, v104
	v_fmac_f32_e32 v199, v105, v105
	v_fmac_f32_e32 v199, v106, v106
	v_fmac_f32_e32 v199, v107, v107
	ds_write_b128 v188, v[104:107] offset:192
	s_waitcnt lgkmcnt(7)
	v_add_f32_e32 v108, v200, v108
	v_add_f32_e32 v109, v201, v109
	v_add_f32_e32 v110, v202, v110
	v_add_f32_e32 v111, v203, v111
	v_fmac_f32_e32 v199, v108, v108
	v_fmac_f32_e32 v199, v109, v109
	v_fmac_f32_e32 v199, v110, v110
	v_fmac_f32_e32 v199, v111, v111
	ds_write_b128 v188, v[108:111] offset:224
	ds_read_b128 v[160:163], v191
	ds_read_b128 v[164:167], v191 offset:1088
	ds_read_b128 v[168:171], v191 offset:2176
	ds_read_b128 v[172:175], v191 offset:3264
	ds_read_b128 v[176:179], v191 offset:4352
	ds_read_b128 v[180:183], v191 offset:5440
	ds_read_b128 v[184:187], v191 offset:6528
	ds_read_b128 v[200:203], v191 offset:7616
	s_add_u32 s74, s66, 0x0
	s_addc_u32 s75, s67, 0
	s_waitcnt lgkmcnt(7)
	global_store_dwordx4 v193, v[160:163], s[74:75]
	s_add_u32 s74, s66, 0x4000
	s_addc_u32 s75, s67, 0
	s_waitcnt lgkmcnt(6)
	global_store_dwordx4 v193, v[164:167], s[74:75]
	s_add_u32 s74, s66, 0x8000
	s_addc_u32 s75, s67, 0
	s_waitcnt lgkmcnt(5)
	global_store_dwordx4 v193, v[168:171], s[74:75]
	s_add_u32 s74, s66, 0xc000
	s_addc_u32 s75, s67, 0
	s_waitcnt lgkmcnt(4)
	global_store_dwordx4 v193, v[172:175], s[74:75]
	s_add_u32 s74, s66, 0x10000
	s_addc_u32 s75, s67, 0
	s_waitcnt lgkmcnt(3)
	global_store_dwordx4 v193, v[176:179], s[74:75]
	s_add_u32 s74, s66, 0x14000
	s_addc_u32 s75, s67, 0
	s_waitcnt lgkmcnt(2)
	global_store_dwordx4 v193, v[180:183], s[74:75]
	s_add_u32 s74, s66, 0x18000
	s_addc_u32 s75, s67, 0
	s_waitcnt lgkmcnt(1)
	global_store_dwordx4 v193, v[184:187], s[74:75]
	s_add_u32 s74, s66, 0x1c000
	s_addc_u32 s75, s67, 0
	s_waitcnt lgkmcnt(0)
; DI bfr f2bf(float a) { return (bfr)(pack2(a, 0.f) & 0xffffu); }
; DI int crow(int reg, int h) { return (reg & 3) + 8 * (reg >> 2) + 4 * h; }
; template <bool FIRST, bool HAS_H>
; DI void phase_gemm_resid(const Params& p, const bfr* A, const bfr* Wt, const float* gnext, float* ss, char* smem) {
;     ...
;         for (int jh = 0; jh < 2; ++jh) {
;           float xo[2][8];
; #pragma unroll
;           for (int jj = 0; jj < 2; ++jj)
; #pragma unroll
;             for (int q = 0; q < 8; ++q)
;               xo[jj][q] = xsrc[(rbase + i * 32 + crow(qh * 8 + q, 0)) * 1024 + cbase + (jh * 2 + jj) * 32];
; #pragma unroll
;           for (int q = 0; q < 8; ++q) {
;             const int o = (rbase + i * 32 + crow(qh * 8 + q, 0)) * 1024 + cbase;
; #pragma unroll
;             for (int jj = 0; jj < 2; ++jj) {
;               const int j = jh * 2 + jj;
;               const float xn = xo[jj][q] + acc[i][j][qh * 8 + q];
;               X[o + j * 32] = xn;
;               if (HAS_H) Hn[o + j * 32] = f2bf(xn * gnext[cbase + j * 32]);
;               rs[q] += xn * xn;
	global_store_dwordx4 v193, v[200:203], s[74:75]
	global_load_dwordx4 v[160:163], v198, s[70:71]
	global_load_dwordx4 v[164:167], v198, s[70:71] offset:32
	global_load_dwordx4 v[168:171], v198, s[70:71] offset:64
	global_load_dwordx4 v[172:175], v198, s[70:71] offset:96
	global_load_dwordx4 v[176:179], v198, s[70:71] offset:128
	global_load_dwordx4 v[180:183], v198, s[70:71] offset:160
	global_load_dwordx4 v[184:187], v198, s[70:71] offset:192
	global_load_dwordx4 v[200:203], v198, s[70:71] offset:224
	s_waitcnt vmcnt(7)
	v_mul_f32_e32 v112, v160, v112
	v_mul_f32_e32 v113, v161, v113
	v_mul_f32_e32 v114, v162, v114
	v_mul_f32_e32 v115, v163, v115
	v_cvt_pk_bf16_f32 v112, v112, v113
	v_cvt_pk_bf16_f32 v113, v114, v115
	ds_write_b64 v190, v[112:113]
	s_waitcnt vmcnt(6)
	v_mul_f32_e32 v116, v164, v116
	v_mul_f32_e32 v117, v165, v117
	v_mul_f32_e32 v118, v166, v118
	v_mul_f32_e32 v119, v167, v119
	v_cvt_pk_bf16_f32 v116, v116, v117
	v_cvt_pk_bf16_f32 v117, v118, v119
	ds_write_b64 v190, v[116:117] offset:16
	s_waitcnt vmcnt(5)
	v_mul_f32_e32 v120, v168, v120
	v_mul_f32_e32 v121, v169, v121
	v_mul_f32_e32 v122, v170, v122
	v_mul_f32_e32 v123, v171, v123
	v_cvt_pk_bf16_f32 v120, v120, v121
	v_cvt_pk_bf16_f32 v121, v122, v123
	ds_write_b64 v190, v[120:121] offset:32
	s_waitcnt vmcnt(4)
	v_mul_f32_e32 v124, v172, v124
	v_mul_f32_e32 v125, v173, v125
	v_mul_f32_e32 v126, v174, v126
	v_mul_f32_e32 v127, v175, v127
	v_cvt_pk_bf16_f32 v124, v124, v125
	v_cvt_pk_bf16_f32 v125, v126, v127
	ds_write_b64 v190, v[124:125] offset:48
	s_waitcnt vmcnt(3)
	v_mul_f32_e32 v96, v176, v96
	v_mul_f32_e32 v97, v177, v97
	v_mul_f32_e32 v98, v178, v98
	v_mul_f32_e32 v99, v179, v99
	v_cvt_pk_bf16_f32 v96, v96, v97
	v_cvt_pk_bf16_f32 v97, v98, v99
	ds_write_b64 v190, v[96:97] offset:64
	s_waitcnt vmcnt(2)
	v_mul_f32_e32 v100, v180, v100
	v_mul_f32_e32 v101, v181, v101
	v_mul_f32_e32 v102, v182, v102
	v_mul_f32_e32 v103, v183, v103
	v_cvt_pk_bf16_f32 v100, v100, v101
	v_cvt_pk_bf16_f32 v101, v102, v103
	ds_write_b64 v190, v[100:101] offset:80
	s_waitcnt vmcnt(1)
	v_mul_f32_e32 v104, v184, v104
	v_mul_f32_e32 v105, v185, v105
	v_mul_f32_e32 v106, v186, v106
	v_mul_f32_e32 v107, v187, v107
	v_cvt_pk_bf16_f32 v104, v104, v105
	v_cvt_pk_bf16_f32 v105, v106, v107
	ds_write_b64 v190, v[104:105] offset:96
	s_waitcnt vmcnt(0)
	v_mul_f32_e32 v108, v200, v108
	v_mul_f32_e32 v109, v201, v109
	v_mul_f32_e32 v110, v202, v110
	v_mul_f32_e32 v111, v203, v111
	v_cvt_pk_bf16_f32 v108, v108, v109
	v_cvt_pk_bf16_f32 v109, v110, v111
	ds_write_b64 v190, v[108:109] offset:112
	ds_read_b128 v[160:163], v192
	ds_read_b128 v[164:167], v192 offset:2176
	ds_read_b128 v[168:171], v192 offset:4352
	ds_read_b128 v[172:175], v192 offset:6528
	s_add_u32 s74, s68, 0x0
	s_addc_u32 s75, s69, 0
	s_waitcnt lgkmcnt(3)
	global_store_dwordx4 v194, v[160:163], s[74:75]
	s_add_u32 s74, s68, 0x4000
	s_addc_u32 s75, s69, 0
	s_waitcnt lgkmcnt(2)
	global_store_dwordx4 v194, v[164:167], s[74:75]
	s_add_u32 s74, s68, 0x8000
	s_addc_u32 s75, s69, 0
	s_waitcnt lgkmcnt(1)
	global_store_dwordx4 v194, v[168:171], s[74:75]
	s_add_u32 s74, s68, 0xc000
	s_addc_u32 s75, s69, 0
	s_waitcnt lgkmcnt(0)
	global_store_dwordx4 v194, v[172:175], s[74:75]
	s_waitcnt vmcnt(4)
	ds_write_b128 v191, v[128:131]
	s_waitcnt vmcnt(4)
	ds_write_b128 v191, v[132:135] offset:1088
	s_waitcnt vmcnt(4)
	ds_write_b128 v191, v[136:139] offset:2176
	s_waitcnt vmcnt(4)
	ds_write_b128 v191, v[140:143] offset:3264
	s_waitcnt vmcnt(4)
	ds_write_b128 v191, v[144:147] offset:4352
	s_waitcnt vmcnt(4)
	ds_write_b128 v191, v[148:151] offset:5440
	s_waitcnt vmcnt(4)
	ds_write_b128 v191, v[152:155] offset:6528
	s_waitcnt vmcnt(4)
	ds_write_b128 v191, v[156:159] offset:7616
	s_add_u32 s74, s64, 0x20000
	s_addc_u32 s75, s65, 0
	global_load_dwordx4 v[128:131], v193, s[74:75]
	s_add_u32 s74, s64, 0x24000
	s_addc_u32 s75, s65, 0
	global_load_dwordx4 v[132:135], v193, s[74:75]
	s_add_u32 s74, s64, 0x28000
	s_addc_u32 s75, s65, 0
	global_load_dwordx4 v[136:139], v193, s[74:75]
	s_add_u32 s74, s64, 0x2c000
	s_addc_u32 s75, s65, 0
	global_load_dwordx4 v[140:143], v193, s[74:75]
	s_add_u32 s74, s64, 0x30000
	s_addc_u32 s75, s65, 0
	global_load_dwordx4 v[144:147], v193, s[74:75]
	s_add_u32 s74, s64, 0x34000
	s_addc_u32 s75, s65, 0
	global_load_dwordx4 v[148:151], v193, s[74:75]
	s_add_u32 s74, s64, 0x38000
	s_addc_u32 s75, s65, 0
	global_load_dwordx4 v[152:155], v193, s[74:75]
	s_add_u32 s74, s64, 0x3c000
	s_addc_u32 s75, s65, 0
	global_load_dwordx4 v[156:159], v193, s[74:75]
	ds_read_b128 v[160:163], v188
	ds_read_b128 v[164:167], v188 offset:32
	ds_read_b128 v[168:171], v188 offset:64
	ds_read_b128 v[172:175], v188 offset:96
	ds_read_b128 v[176:179], v188 offset:128
	ds_read_b128 v[180:183], v188 offset:160
	ds_read_b128 v[184:187], v188 offset:192
	ds_read_b128 v[200:203], v188 offset:224
	s_waitcnt lgkmcnt(7)
	v_add_f32_e32 v80, v160, v80
	v_add_f32_e32 v81, v161, v81
	v_add_f32_e32 v82, v162, v82
	v_add_f32_e32 v83, v163, v83
	v_fmac_f32_e32 v199, v80, v80
	v_fmac_f32_e32 v199, v81, v81
	v_fmac_f32_e32 v199, v82, v82
	v_fmac_f32_e32 v199, v83, v83
	ds_write_b128 v188, v[80:83]
	s_waitcnt lgkmcnt(7)
	v_add_f32_e32 v84, v164, v84
	v_add_f32_e32 v85, v165, v85
	v_add_f32_e32 v86, v166, v86
	v_add_f32_e32 v87, v167, v87
	v_fmac_f32_e32 v199, v84, v84
	v_fmac_f32_e32 v199, v85, v85
	v_fmac_f32_e32 v199, v86, v86
	v_fmac_f32_e32 v199, v87, v87
	ds_write_b128 v188, v[84:87] offset:32
	s_waitcnt lgkmcnt(7)
	v_add_f32_e32 v88, v168, v88
	v_add_f32_e32 v89, v169, v89
	v_add_f32_e32 v90, v170, v90
	v_add_f32_e32 v91, v171, v91
	v_fmac_f32_e32 v199, v88, v88
	v_fmac_f32_e32 v199, v89, v89
	v_fmac_f32_e32 v199, v90, v90
	v_fmac_f32_e32 v199, v91, v91
	ds_write_b128 v188, v[88:91] offset:64
	s_waitcnt lgkmcnt(7)
; DI bfr f2bf(float a) { return (bfr)(pack2(a, 0.f) & 0xffffu); }
; DI int crow(int reg, int h) { return (reg & 3) + 8 * (reg >> 2) + 4 * h; }
; template <bool FIRST, bool HAS_H>
; DI void phase_gemm_resid(const Params& p, const bfr* A, const bfr* Wt, const float* gnext, float* ss, char* smem) {
;     ...
;         for (int jh = 0; jh < 2; ++jh) {
;           float xo[2][8];
; #pragma unroll
;           for (int jj = 0; jj < 2; ++jj)
; #pragma unroll
;             for (int q = 0; q < 8; ++q)
;               xo[jj][q] = xsrc[(rbase + i * 32 + crow(qh * 8 + q, 0)) * 1024 + cbase + (jh * 2 + jj) * 32];
; #pragma unroll
;           for (int q = 0; q < 8; ++q) {
;             const int o = (rbase + i * 32 + crow(qh * 8 + q, 0)) * 1024 + cbase;
; #pragma unroll
;             for (int jj = 0; jj < 2; ++jj) {
;               const int j = jh * 2 + jj;
;               const float xn = xo[jj][q] + acc[i][j][qh * 8 + q];
;               X[o + j * 32] = xn;
;               if (HAS_H) Hn[o + j * 32] = f2bf(xn * gnext[cbase + j * 32]);
;               rs[q] += xn * xn;
	v_add_f32_e32 v92, v172, v92
	v_add_f32_e32 v93, v173, v93
	v_add_f32_e32 v94, v174, v94
	v_add_f32_e32 v95, v175, v95
	v_fmac_f32_e32 v199, v92, v92
	v_fmac_f32_e32 v199, v93, v93
	v_fmac_f32_e32 v199, v94, v94
	v_fmac_f32_e32 v199, v95, v95
	ds_write_b128 v188, v[92:95] offset:96
	s_waitcnt lgkmcnt(7)
	v_add_f32_e32 v64, v176, v64
	v_add_f32_e32 v65, v177, v65
	v_add_f32_e32 v66, v178, v66
	v_add_f32_e32 v67, v179, v67
	v_fmac_f32_e32 v199, v64, v64
	v_fmac_f32_e32 v199, v65, v65
	v_fmac_f32_e32 v199, v66, v66
	v_fmac_f32_e32 v199, v67, v67
	ds_write_b128 v188, v[64:67] offset:128
	s_waitcnt lgkmcnt(7)
	v_add_f32_e32 v68, v180, v68
	v_add_f32_e32 v69, v181, v69
	v_add_f32_e32 v70, v182, v70
	v_add_f32_e32 v71, v183, v71
	v_fmac_f32_e32 v199, v68, v68
	v_fmac_f32_e32 v199, v69, v69
	v_fmac_f32_e32 v199, v70, v70
	v_fmac_f32_e32 v199, v71, v71
	ds_write_b128 v188, v[68:71] offset:160
	s_waitcnt lgkmcnt(7)
	v_add_f32_e32 v72, v184, v72
	v_add_f32_e32 v73, v185, v73
	v_add_f32_e32 v74, v186, v74
	v_add_f32_e32 v75, v187, v75
	v_fmac_f32_e32 v199, v72, v72
	v_fmac_f32_e32 v199, v73, v73
	v_fmac_f32_e32 v199, v74, v74
	v_fmac_f32_e32 v199, v75, v75
	ds_write_b128 v188, v[72:75] offset:192
	s_waitcnt lgkmcnt(7)
	v_add_f32_e32 v76, v200, v76
	v_add_f32_e32 v77, v201, v77
	v_add_f32_e32 v78, v202, v78
	v_add_f32_e32 v79, v203, v79
	v_fmac_f32_e32 v199, v76, v76
	v_fmac_f32_e32 v199, v77, v77
	v_fmac_f32_e32 v199, v78, v78
	v_fmac_f32_e32 v199, v79, v79
	ds_write_b128 v188, v[76:79] offset:224
	ds_read_b128 v[160:163], v191
	ds_read_b128 v[164:167], v191 offset:1088
	ds_read_b128 v[168:171], v191 offset:2176
	ds_read_b128 v[172:175], v191 offset:3264
	ds_read_b128 v[176:179], v191 offset:4352
	ds_read_b128 v[180:183], v191 offset:5440
	ds_read_b128 v[184:187], v191 offset:6528
	ds_read_b128 v[200:203], v191 offset:7616
	s_add_u32 s74, s66, 0x100
	s_addc_u32 s75, s67, 0
	s_waitcnt lgkmcnt(7)
	global_store_dwordx4 v193, v[160:163], s[74:75]
	s_add_u32 s74, s66, 0x4100
	s_addc_u32 s75, s67, 0
	s_waitcnt lgkmcnt(6)
	global_store_dwordx4 v193, v[164:167], s[74:75]
	s_add_u32 s74, s66, 0x8100
	s_addc_u32 s75, s67, 0
	s_waitcnt lgkmcnt(5)
	global_store_dwordx4 v193, v[168:171], s[74:75]
	s_add_u32 s74, s66, 0xc100
	s_addc_u32 s75, s67, 0
	s_waitcnt lgkmcnt(4)
	global_store_dwordx4 v193, v[172:175], s[74:75]
	s_add_u32 s74, s66, 0x10100
	s_addc_u32 s75, s67, 0
	s_waitcnt lgkmcnt(3)
	global_store_dwordx4 v193, v[176:179], s[74:75]
	s_add_u32 s74, s66, 0x14100
	s_addc_u32 s75, s67, 0
	s_waitcnt lgkmcnt(2)
	global_store_dwordx4 v193, v[180:183], s[74:75]
	s_add_u32 s74, s66, 0x18100
	s_addc_u32 s75, s67, 0
	s_waitcnt lgkmcnt(1)
	global_store_dwordx4 v193, v[184:187], s[74:75]
	s_add_u32 s74, s66, 0x1c100
	s_addc_u32 s75, s67, 0
	s_waitcnt lgkmcnt(0)
	global_store_dwordx4 v193, v[200:203], s[74:75]
	global_load_dwordx4 v[160:163], v198, s[70:71] offset:256
	global_load_dwordx4 v[164:167], v198, s[70:71] offset:288
	global_load_dwordx4 v[168:171], v198, s[70:71] offset:320
	global_load_dwordx4 v[172:175], v198, s[70:71] offset:352
	global_load_dwordx4 v[176:179], v198, s[70:71] offset:384
	global_load_dwordx4 v[180:183], v198, s[70:71] offset:416
	global_load_dwordx4 v[184:187], v198, s[70:71] offset:448
	global_load_dwordx4 v[200:203], v198, s[70:71] offset:480
	s_waitcnt vmcnt(7)
	v_mul_f32_e32 v80, v160, v80
	v_mul_f32_e32 v81, v161, v81
	v_mul_f32_e32 v82, v162, v82
	v_mul_f32_e32 v83, v163, v83
	v_cvt_pk_bf16_f32 v80, v80, v81
	v_cvt_pk_bf16_f32 v81, v82, v83
	ds_write_b64 v190, v[80:81]
	s_waitcnt vmcnt(6)
	v_mul_f32_e32 v84, v164, v84
	v_mul_f32_e32 v85, v165, v85
	v_mul_f32_e32 v86, v166, v86
	v_mul_f32_e32 v87, v167, v87
	v_cvt_pk_bf16_f32 v84, v84, v85
	v_cvt_pk_bf16_f32 v85, v86, v87
	ds_write_b64 v190, v[84:85] offset:16
	s_waitcnt vmcnt(5)
	v_mul_f32_e32 v88, v168, v88
	v_mul_f32_e32 v89, v169, v89
	v_mul_f32_e32 v90, v170, v90
	v_mul_f32_e32 v91, v171, v91
	v_cvt_pk_bf16_f32 v88, v88, v89
	v_cvt_pk_bf16_f32 v89, v90, v91
	ds_write_b64 v190, v[88:89] offset:32
	s_waitcnt vmcnt(4)
	v_mul_f32_e32 v92, v172, v92
	v_mul_f32_e32 v93, v173, v93
	v_mul_f32_e32 v94, v174, v94
	v_mul_f32_e32 v95, v175, v95
	v_cvt_pk_bf16_f32 v92, v92, v93
	v_cvt_pk_bf16_f32 v93, v94, v95
	ds_write_b64 v190, v[92:93] offset:48
	s_waitcnt vmcnt(3)
	v_mul_f32_e32 v64, v176, v64
	v_mul_f32_e32 v65, v177, v65
	v_mul_f32_e32 v66, v178, v66
	v_mul_f32_e32 v67, v179, v67
	v_cvt_pk_bf16_f32 v64, v64, v65
	v_cvt_pk_bf16_f32 v65, v66, v67
	ds_write_b64 v190, v[64:65] offset:64
	s_waitcnt vmcnt(2)
	v_mul_f32_e32 v68, v180, v68
	v_mul_f32_e32 v69, v181, v69
	v_mul_f32_e32 v70, v182, v70
	v_mul_f32_e32 v71, v183, v71
	v_cvt_pk_bf16_f32 v68, v68, v69
	v_cvt_pk_bf16_f32 v69, v70, v71
	ds_write_b64 v190, v[68:69] offset:80
	s_waitcnt vmcnt(1)
	v_mul_f32_e32 v72, v184, v72
	v_mul_f32_e32 v73, v185, v73
	v_mul_f32_e32 v74, v186, v74
	v_mul_f32_e32 v75, v187, v75
	v_cvt_pk_bf16_f32 v72, v72, v73
	v_cvt_pk_bf16_f32 v73, v74, v75
	ds_write_b64 v190, v[72:73] offset:96
	s_waitcnt vmcnt(0)
	v_mul_f32_e32 v76, v200, v76
	v_mul_f32_e32 v77, v201, v77
	v_mul_f32_e32 v78, v202, v78
	v_mul_f32_e32 v79, v203, v79
	v_cvt_pk_bf16_f32 v76, v76, v77
	v_cvt_pk_bf16_f32 v77, v78, v79
	ds_write_b64 v190, v[76:77] offset:112
	ds_read_b128 v[160:163], v192
	ds_read_b128 v[164:167], v192 offset:2176
	ds_read_b128 v[168:171], v192 offset:4352
	ds_read_b128 v[172:175], v192 offset:6528
	s_add_u32 s74, s68, 0x80
	s_addc_u32 s75, s69, 0
	s_waitcnt lgkmcnt(3)
	global_store_dwordx4 v194, v[160:163], s[74:75]
	s_add_u32 s74, s68, 0x4080
	s_addc_u32 s75, s69, 0
	s_waitcnt lgkmcnt(2)
; DI bfr f2bf(float a) { return (bfr)(pack2(a, 0.f) & 0xffffu); }
; DI int crow(int reg, int h) { return (reg & 3) + 8 * (reg >> 2) + 4 * h; }
; template <bool FIRST, bool HAS_H>
; DI void phase_gemm_resid(const Params& p, const bfr* A, const bfr* Wt, const float* gnext, float* ss, char* smem) {
;     ...
; #pragma unroll
;     for (int i = 0; i < 2; ++i) {
; #pragma unroll
;       for (int qh = 0; qh < 2; ++qh) {
;         float rs[8];
; #pragma unroll
;         for (int q = 0; q < 8; ++q) rs[q] = 0.f;
; #pragma unroll
;         for (int jh = 0; jh < 2; ++jh) {
;           float xo[2][8];
; #pragma unroll
;           for (int jj = 0; jj < 2; ++jj)
; #pragma unroll
;             for (int q = 0; q < 8; ++q)
;               xo[jj][q] = xsrc[(rbase + i * 32 + crow(qh * 8 + q, 0)) * 1024 + cbase + (jh * 2 + jj) * 32];
; #pragma unroll
;           for (int q = 0; q < 8; ++q) {
;             const int o = (rbase + i * 32 + crow(qh * 8 + q, 0)) * 1024 + cbase;
; #pragma unroll
;             for (int jj = 0; jj < 2; ++jj) {
;               const int j = jh * 2 + jj;
;               const float xn = xo[jj][q] + acc[i][j][qh * 8 + q];
;               X[o + j * 32] = xn;
;               if (HAS_H) Hn[o + j * 32] = f2bf(xn * gnext[cbase + j * 32]);
;               rs[q] += xn * xn;
;             }
;           }
	global_store_dwordx4 v194, v[164:167], s[74:75]
	s_add_u32 s74, s68, 0x8080
	s_addc_u32 s75, s69, 0
	s_waitcnt lgkmcnt(1)
	global_store_dwordx4 v194, v[168:171], s[74:75]
	s_add_u32 s74, s68, 0xc080
	s_addc_u32 s75, s69, 0
	s_waitcnt lgkmcnt(0)
	global_store_dwordx4 v194, v[172:175], s[74:75]
	s_waitcnt vmcnt(4)
	ds_write_b128 v191, v[128:131]
	s_waitcnt vmcnt(4)
	ds_write_b128 v191, v[132:135] offset:1088
	s_waitcnt vmcnt(4)
	ds_write_b128 v191, v[136:139] offset:2176
	s_waitcnt vmcnt(4)
	ds_write_b128 v191, v[140:143] offset:3264
	s_waitcnt vmcnt(4)
	ds_write_b128 v191, v[144:147] offset:4352
	s_waitcnt vmcnt(4)
	ds_write_b128 v191, v[148:151] offset:5440
	s_waitcnt vmcnt(4)
	ds_write_b128 v191, v[152:155] offset:6528
	s_waitcnt vmcnt(4)
	ds_write_b128 v191, v[156:159] offset:7616
	s_add_u32 s74, s64, 0x20100
	s_addc_u32 s75, s65, 0
	global_load_dwordx4 v[128:131], v193, s[74:75]
	s_add_u32 s74, s64, 0x24100
	s_addc_u32 s75, s65, 0
	global_load_dwordx4 v[132:135], v193, s[74:75]
	s_add_u32 s74, s64, 0x28100
	s_addc_u32 s75, s65, 0
	global_load_dwordx4 v[136:139], v193, s[74:75]
	s_add_u32 s74, s64, 0x2c100
	s_addc_u32 s75, s65, 0
	global_load_dwordx4 v[140:143], v193, s[74:75]
	s_add_u32 s74, s64, 0x30100
	s_addc_u32 s75, s65, 0
	global_load_dwordx4 v[144:147], v193, s[74:75]
	s_add_u32 s74, s64, 0x34100
	s_addc_u32 s75, s65, 0
	global_load_dwordx4 v[148:151], v193, s[74:75]
	s_add_u32 s74, s64, 0x38100
	s_addc_u32 s75, s65, 0
	global_load_dwordx4 v[152:155], v193, s[74:75]
	s_add_u32 s74, s64, 0x3c100
	s_addc_u32 s75, s65, 0
	global_load_dwordx4 v[156:159], v193, s[74:75]
	ds_read_b128 v[160:163], v188
	ds_read_b128 v[164:167], v188 offset:32
	ds_read_b128 v[168:171], v188 offset:64
	ds_read_b128 v[172:175], v188 offset:96
	ds_read_b128 v[176:179], v188 offset:128
	ds_read_b128 v[180:183], v188 offset:160
	ds_read_b128 v[184:187], v188 offset:192
	ds_read_b128 v[200:203], v188 offset:224
	s_waitcnt lgkmcnt(7)
	v_add_f32_e32 v48, v160, v48
	v_add_f32_e32 v49, v161, v49
	v_add_f32_e32 v50, v162, v50
	v_add_f32_e32 v51, v163, v51
	v_fmac_f32_e32 v204, v48, v48
	v_fmac_f32_e32 v204, v49, v49
	v_fmac_f32_e32 v204, v50, v50
	v_fmac_f32_e32 v204, v51, v51
	ds_write_b128 v188, v[48:51]
	s_waitcnt lgkmcnt(7)
	v_add_f32_e32 v52, v164, v52
	v_add_f32_e32 v53, v165, v53
	v_add_f32_e32 v54, v166, v54
	v_add_f32_e32 v55, v167, v55
	v_fmac_f32_e32 v204, v52, v52
	v_fmac_f32_e32 v204, v53, v53
	v_fmac_f32_e32 v204, v54, v54
	v_fmac_f32_e32 v204, v55, v55
	ds_write_b128 v188, v[52:55] offset:32
	s_waitcnt lgkmcnt(7)
	v_add_f32_e32 v56, v168, v56
	v_add_f32_e32 v57, v169, v57
	v_add_f32_e32 v58, v170, v58
	v_add_f32_e32 v59, v171, v59
	v_fmac_f32_e32 v204, v56, v56
	v_fmac_f32_e32 v204, v57, v57
	v_fmac_f32_e32 v204, v58, v58
	v_fmac_f32_e32 v204, v59, v59
	ds_write_b128 v188, v[56:59] offset:64
	s_waitcnt lgkmcnt(7)
	v_add_f32_e32 v60, v172, v60
	v_add_f32_e32 v61, v173, v61
	v_add_f32_e32 v62, v174, v62
	v_add_f32_e32 v63, v175, v63
	v_fmac_f32_e32 v204, v60, v60
	v_fmac_f32_e32 v204, v61, v61
	v_fmac_f32_e32 v204, v62, v62
	v_fmac_f32_e32 v204, v63, v63
	ds_write_b128 v188, v[60:63] offset:96
	s_waitcnt lgkmcnt(7)
	v_add_f32_e32 v32, v176, v32
	v_add_f32_e32 v33, v177, v33
	v_add_f32_e32 v34, v178, v34
	v_add_f32_e32 v35, v179, v35
	v_fmac_f32_e32 v204, v32, v32
	v_fmac_f32_e32 v204, v33, v33
	v_fmac_f32_e32 v204, v34, v34
	v_fmac_f32_e32 v204, v35, v35
	ds_write_b128 v188, v[32:35] offset:128
	s_waitcnt lgkmcnt(7)
	v_add_f32_e32 v36, v180, v36
	v_add_f32_e32 v37, v181, v37
	v_add_f32_e32 v38, v182, v38
	v_add_f32_e32 v39, v183, v39
	v_fmac_f32_e32 v204, v36, v36
	v_fmac_f32_e32 v204, v37, v37
	v_fmac_f32_e32 v204, v38, v38
	v_fmac_f32_e32 v204, v39, v39
	ds_write_b128 v188, v[36:39] offset:160
	s_waitcnt lgkmcnt(7)
	v_add_f32_e32 v40, v184, v40
	v_add_f32_e32 v41, v185, v41
	v_add_f32_e32 v42, v186, v42
	v_add_f32_e32 v43, v187, v43
	v_fmac_f32_e32 v204, v40, v40
	v_fmac_f32_e32 v204, v41, v41
	v_fmac_f32_e32 v204, v42, v42
	v_fmac_f32_e32 v204, v43, v43
	ds_write_b128 v188, v[40:43] offset:192
	s_waitcnt lgkmcnt(7)
	v_add_f32_e32 v44, v200, v44
	v_add_f32_e32 v45, v201, v45
	v_add_f32_e32 v46, v202, v46
	v_add_f32_e32 v47, v203, v47
	v_fmac_f32_e32 v204, v44, v44
	v_fmac_f32_e32 v204, v45, v45
	v_fmac_f32_e32 v204, v46, v46
	v_fmac_f32_e32 v204, v47, v47
	ds_write_b128 v188, v[44:47] offset:224
	ds_read_b128 v[160:163], v191
	ds_read_b128 v[164:167], v191 offset:1088
	ds_read_b128 v[168:171], v191 offset:2176
	ds_read_b128 v[172:175], v191 offset:3264
	ds_read_b128 v[176:179], v191 offset:4352
	ds_read_b128 v[180:183], v191 offset:5440
	ds_read_b128 v[184:187], v191 offset:6528
	ds_read_b128 v[200:203], v191 offset:7616
	s_add_u32 s74, s66, 0x20000
	s_addc_u32 s75, s67, 0
	s_waitcnt lgkmcnt(7)
	global_store_dwordx4 v193, v[160:163], s[74:75]
	s_add_u32 s74, s66, 0x24000
	s_addc_u32 s75, s67, 0
	s_waitcnt lgkmcnt(6)
	global_store_dwordx4 v193, v[164:167], s[74:75]
	s_add_u32 s74, s66, 0x28000
	s_addc_u32 s75, s67, 0
	s_waitcnt lgkmcnt(5)
	global_store_dwordx4 v193, v[168:171], s[74:75]
	s_add_u32 s74, s66, 0x2c000
	s_addc_u32 s75, s67, 0
	s_waitcnt lgkmcnt(4)
	global_store_dwordx4 v193, v[172:175], s[74:75]
	s_add_u32 s74, s66, 0x30000
	s_addc_u32 s75, s67, 0
	s_waitcnt lgkmcnt(3)
	global_store_dwordx4 v193, v[176:179], s[74:75]
	s_add_u32 s74, s66, 0x34000
	s_addc_u32 s75, s67, 0
	s_waitcnt lgkmcnt(2)
	global_store_dwordx4 v193, v[180:183], s[74:75]
	s_add_u32 s74, s66, 0x38000
	s_addc_u32 s75, s67, 0
	s_waitcnt lgkmcnt(1)
	global_store_dwordx4 v193, v[184:187], s[74:75]
	s_add_u32 s74, s66, 0x3c000
	s_addc_u32 s75, s67, 0
	s_waitcnt lgkmcnt(0)
; DI bfr f2bf(float a) { return (bfr)(pack2(a, 0.f) & 0xffffu); }
; DI int crow(int reg, int h) { return (reg & 3) + 8 * (reg >> 2) + 4 * h; }
; template <bool FIRST, bool HAS_H>
; DI void phase_gemm_resid(const Params& p, const bfr* A, const bfr* Wt, const float* gnext, float* ss, char* smem) {
;     ...
;         for (int jh = 0; jh < 2; ++jh) {
;           float xo[2][8];
; #pragma unroll
;           for (int jj = 0; jj < 2; ++jj)
; #pragma unroll
;             for (int q = 0; q < 8; ++q)
;               xo[jj][q] = xsrc[(rbase + i * 32 + crow(qh * 8 + q, 0)) * 1024 + cbase + (jh * 2 + jj) * 32];
; #pragma unroll
;           for (int q = 0; q < 8; ++q) {
;             const int o = (rbase + i * 32 + crow(qh * 8 + q, 0)) * 1024 + cbase;
; #pragma unroll
;             for (int jj = 0; jj < 2; ++jj) {
;               const int j = jh * 2 + jj;
;               const float xn = xo[jj][q] + acc[i][j][qh * 8 + q];
;               X[o + j * 32] = xn;
;               if (HAS_H) Hn[o + j * 32] = f2bf(xn * gnext[cbase + j * 32]);
;               rs[q] += xn * xn;
;             }
;           }
	global_store_dwordx4 v193, v[200:203], s[74:75]
	global_load_dwordx4 v[160:163], v198, s[70:71]
	global_load_dwordx4 v[164:167], v198, s[70:71] offset:32
	global_load_dwordx4 v[168:171], v198, s[70:71] offset:64
	global_load_dwordx4 v[172:175], v198, s[70:71] offset:96
	global_load_dwordx4 v[176:179], v198, s[70:71] offset:128
	global_load_dwordx4 v[180:183], v198, s[70:71] offset:160
	global_load_dwordx4 v[184:187], v198, s[70:71] offset:192
	global_load_dwordx4 v[200:203], v198, s[70:71] offset:224
	s_waitcnt vmcnt(7)
	v_mul_f32_e32 v48, v160, v48
	v_mul_f32_e32 v49, v161, v49
	v_mul_f32_e32 v50, v162, v50
	v_mul_f32_e32 v51, v163, v51
	v_cvt_pk_bf16_f32 v48, v48, v49
	v_cvt_pk_bf16_f32 v49, v50, v51
	ds_write_b64 v190, v[48:49]
	s_waitcnt vmcnt(6)
	v_mul_f32_e32 v52, v164, v52
	v_mul_f32_e32 v53, v165, v53
	v_mul_f32_e32 v54, v166, v54
	v_mul_f32_e32 v55, v167, v55
	v_cvt_pk_bf16_f32 v52, v52, v53
	v_cvt_pk_bf16_f32 v53, v54, v55
	ds_write_b64 v190, v[52:53] offset:16
	s_waitcnt vmcnt(5)
	v_mul_f32_e32 v56, v168, v56
	v_mul_f32_e32 v57, v169, v57
	v_mul_f32_e32 v58, v170, v58
	v_mul_f32_e32 v59, v171, v59
	v_cvt_pk_bf16_f32 v56, v56, v57
	v_cvt_pk_bf16_f32 v57, v58, v59
	ds_write_b64 v190, v[56:57] offset:32
	s_waitcnt vmcnt(4)
	v_mul_f32_e32 v60, v172, v60
	v_mul_f32_e32 v61, v173, v61
	v_mul_f32_e32 v62, v174, v62
	v_mul_f32_e32 v63, v175, v63
	v_cvt_pk_bf16_f32 v60, v60, v61
	v_cvt_pk_bf16_f32 v61, v62, v63
	ds_write_b64 v190, v[60:61] offset:48
	s_waitcnt vmcnt(3)
	v_mul_f32_e32 v32, v176, v32
	v_mul_f32_e32 v33, v177, v33
	v_mul_f32_e32 v34, v178, v34
	v_mul_f32_e32 v35, v179, v35
	v_cvt_pk_bf16_f32 v32, v32, v33
	v_cvt_pk_bf16_f32 v33, v34, v35
	ds_write_b64 v190, v[32:33] offset:64
	s_waitcnt vmcnt(2)
	v_mul_f32_e32 v36, v180, v36
	v_mul_f32_e32 v37, v181, v37
	v_mul_f32_e32 v38, v182, v38
	v_mul_f32_e32 v39, v183, v39
	v_cvt_pk_bf16_f32 v36, v36, v37
	v_cvt_pk_bf16_f32 v37, v38, v39
	ds_write_b64 v190, v[36:37] offset:80
	s_waitcnt vmcnt(1)
	v_mul_f32_e32 v40, v184, v40
	v_mul_f32_e32 v41, v185, v41
	v_mul_f32_e32 v42, v186, v42
	v_mul_f32_e32 v43, v187, v43
	v_cvt_pk_bf16_f32 v40, v40, v41
	v_cvt_pk_bf16_f32 v41, v42, v43
	ds_write_b64 v190, v[40:41] offset:96
	s_waitcnt vmcnt(0)
	v_mul_f32_e32 v44, v200, v44
	v_mul_f32_e32 v45, v201, v45
	v_mul_f32_e32 v46, v202, v46
	v_mul_f32_e32 v47, v203, v47
	v_cvt_pk_bf16_f32 v44, v44, v45
	v_cvt_pk_bf16_f32 v45, v46, v47
	ds_write_b64 v190, v[44:45] offset:112
	ds_read_b128 v[160:163], v192
	ds_read_b128 v[164:167], v192 offset:2176
	ds_read_b128 v[168:171], v192 offset:4352
	ds_read_b128 v[172:175], v192 offset:6528
	s_add_u32 s74, s68, 0x10000
	s_addc_u32 s75, s69, 0
	s_waitcnt lgkmcnt(3)
	global_store_dwordx4 v194, v[160:163], s[74:75]
	s_add_u32 s74, s68, 0x14000
	s_addc_u32 s75, s69, 0
	s_waitcnt lgkmcnt(2)
	global_store_dwordx4 v194, v[164:167], s[74:75]
	s_add_u32 s74, s68, 0x18000
	s_addc_u32 s75, s69, 0
	s_waitcnt lgkmcnt(1)
	global_store_dwordx4 v194, v[168:171], s[74:75]
	s_add_u32 s74, s68, 0x1c000
	s_addc_u32 s75, s69, 0
	s_waitcnt lgkmcnt(0)
	global_store_dwordx4 v194, v[172:175], s[74:75]
	s_waitcnt vmcnt(4)
	ds_write_b128 v191, v[128:131]
	s_waitcnt vmcnt(4)
	ds_write_b128 v191, v[132:135] offset:1088
	s_waitcnt vmcnt(4)
	ds_write_b128 v191, v[136:139] offset:2176
	s_waitcnt vmcnt(4)
	ds_write_b128 v191, v[140:143] offset:3264
	s_waitcnt vmcnt(4)
	ds_write_b128 v191, v[144:147] offset:4352
	s_waitcnt vmcnt(4)
	ds_write_b128 v191, v[148:151] offset:5440
	s_waitcnt vmcnt(4)
	ds_write_b128 v191, v[152:155] offset:6528
	s_waitcnt vmcnt(4)
	ds_write_b128 v191, v[156:159] offset:7616
	ds_read_b128 v[160:163], v188
	ds_read_b128 v[164:167], v188 offset:32
	ds_read_b128 v[168:171], v188 offset:64
	ds_read_b128 v[172:175], v188 offset:96
	ds_read_b128 v[176:179], v188 offset:128
	ds_read_b128 v[180:183], v188 offset:160
	ds_read_b128 v[184:187], v188 offset:192
	ds_read_b128 v[200:203], v188 offset:224
	s_waitcnt lgkmcnt(7)
	v_add_f32_e32 v16, v160, v16
	v_add_f32_e32 v17, v161, v17
	v_add_f32_e32 v18, v162, v18
	v_add_f32_e32 v19, v163, v19
	v_fmac_f32_e32 v204, v16, v16
	v_fmac_f32_e32 v204, v17, v17
	v_fmac_f32_e32 v204, v18, v18
	v_fmac_f32_e32 v204, v19, v19
	ds_write_b128 v188, v[16:19]
	s_waitcnt lgkmcnt(7)
	v_add_f32_e32 v20, v164, v20
	v_add_f32_e32 v21, v165, v21
	v_add_f32_e32 v22, v166, v22
	v_add_f32_e32 v23, v167, v23
	v_fmac_f32_e32 v204, v20, v20
	v_fmac_f32_e32 v204, v21, v21
	v_fmac_f32_e32 v204, v22, v22
	v_fmac_f32_e32 v204, v23, v23
	ds_write_b128 v188, v[20:23] offset:32
	s_waitcnt lgkmcnt(7)
	v_add_f32_e32 v24, v168, v24
	v_add_f32_e32 v25, v169, v25
	v_add_f32_e32 v26, v170, v26
	v_add_f32_e32 v27, v171, v27
	v_fmac_f32_e32 v204, v24, v24
	v_fmac_f32_e32 v204, v25, v25
	v_fmac_f32_e32 v204, v26, v26
	v_fmac_f32_e32 v204, v27, v27
	ds_write_b128 v188, v[24:27] offset:64
	s_waitcnt lgkmcnt(7)
	v_add_f32_e32 v28, v172, v28
	v_add_f32_e32 v29, v173, v29
	v_add_f32_e32 v30, v174, v30
	v_add_f32_e32 v31, v175, v31
	v_fmac_f32_e32 v204, v28, v28
	v_fmac_f32_e32 v204, v29, v29
	v_fmac_f32_e32 v204, v30, v30
	v_fmac_f32_e32 v204, v31, v31
	ds_write_b128 v188, v[28:31] offset:96
	s_waitcnt lgkmcnt(7)
	v_add_f32_e32 v0, v176, v0
	v_add_f32_e32 v1, v177, v1
	v_add_f32_e32 v2, v178, v2
	v_add_f32_e32 v3, v179, v3
	v_fmac_f32_e32 v204, v0, v0
	v_fmac_f32_e32 v204, v1, v1
	v_fmac_f32_e32 v204, v2, v2
	v_fmac_f32_e32 v204, v3, v3
	ds_write_b128 v188, v[0:3] offset:128
	s_waitcnt lgkmcnt(7)
	v_add_f32_e32 v4, v180, v4
	v_add_f32_e32 v5, v181, v5
	v_add_f32_e32 v6, v182, v6
	v_add_f32_e32 v7, v183, v7
	v_fmac_f32_e32 v204, v4, v4
	v_fmac_f32_e32 v204, v5, v5
	v_fmac_f32_e32 v204, v6, v6
	v_fmac_f32_e32 v204, v7, v7
	ds_write_b128 v188, v[4:7] offset:160
	s_waitcnt lgkmcnt(7)
; DI bfr f2bf(float a) { return (bfr)(pack2(a, 0.f) & 0xffffu); }
; DI int crow(int reg, int h) { return (reg & 3) + 8 * (reg >> 2) + 4 * h; }
; template <bool FIRST, bool HAS_H>
; DI void phase_gemm_resid(const Params& p, const bfr* A, const bfr* Wt, const float* gnext, float* ss, char* smem) {
;     ...
;           for (int q = 0; q < 8; ++q) {
;             const int o = (rbase + i * 32 + crow(qh * 8 + q, 0)) * 1024 + cbase;
; #pragma unroll
;             for (int jj = 0; jj < 2; ++jj) {
;               const int j = jh * 2 + jj;
;               const float xn = xo[jj][q] + acc[i][j][qh * 8 + q];
;               X[o + j * 32] = xn;
;               if (HAS_H) Hn[o + j * 32] = f2bf(xn * gnext[cbase + j * 32]);
;               rs[q] += xn * xn;
;             }
;           }
;         }
; #pragma unroll
;         for (int q = 0; q < 8; ++q) rs[q] = half32_sum_hi(rs[q]);
;         if (r == 31) {
; #pragma unroll
;           for (int q = 0; q < 8; ++q) unsafeAtomicAdd(ss + rbase + i * 32 + crow(qh * 8 + q, 0), rs[q]);
;         }
	v_add_f32_e32 v8, v184, v8
	v_add_f32_e32 v9, v185, v9
	v_add_f32_e32 v10, v186, v10
	v_add_f32_e32 v11, v187, v11
	v_fmac_f32_e32 v204, v8, v8
	v_fmac_f32_e32 v204, v9, v9
	v_fmac_f32_e32 v204, v10, v10
	v_fmac_f32_e32 v204, v11, v11
	ds_write_b128 v188, v[8:11] offset:192
	s_waitcnt lgkmcnt(7)
	v_add_f32_e32 v12, v200, v12
	v_add_f32_e32 v13, v201, v13
	v_add_f32_e32 v14, v202, v14
	v_add_f32_e32 v15, v203, v15
	v_fmac_f32_e32 v204, v12, v12
	v_fmac_f32_e32 v204, v13, v13
	v_fmac_f32_e32 v204, v14, v14
	v_fmac_f32_e32 v204, v15, v15
	ds_write_b128 v188, v[12:15] offset:224
	ds_read_b128 v[160:163], v191
	ds_read_b128 v[164:167], v191 offset:1088
	ds_read_b128 v[168:171], v191 offset:2176
	ds_read_b128 v[172:175], v191 offset:3264
	ds_read_b128 v[176:179], v191 offset:4352
	ds_read_b128 v[180:183], v191 offset:5440
	ds_read_b128 v[184:187], v191 offset:6528
	ds_read_b128 v[200:203], v191 offset:7616
	s_add_u32 s74, s66, 0x20100
	s_addc_u32 s75, s67, 0
	s_waitcnt lgkmcnt(7)
	global_store_dwordx4 v193, v[160:163], s[74:75]
	s_add_u32 s74, s66, 0x24100
	s_addc_u32 s75, s67, 0
	s_waitcnt lgkmcnt(6)
	global_store_dwordx4 v193, v[164:167], s[74:75]
	s_add_u32 s74, s66, 0x28100
	s_addc_u32 s75, s67, 0
	s_waitcnt lgkmcnt(5)
	global_store_dwordx4 v193, v[168:171], s[74:75]
	s_add_u32 s74, s66, 0x2c100
	s_addc_u32 s75, s67, 0
	s_waitcnt lgkmcnt(4)
	global_store_dwordx4 v193, v[172:175], s[74:75]
	s_add_u32 s74, s66, 0x30100
	s_addc_u32 s75, s67, 0
	s_waitcnt lgkmcnt(3)
	global_store_dwordx4 v193, v[176:179], s[74:75]
	s_add_u32 s74, s66, 0x34100
	s_addc_u32 s75, s67, 0
	s_waitcnt lgkmcnt(2)
	global_store_dwordx4 v193, v[180:183], s[74:75]
	s_add_u32 s74, s66, 0x38100
	s_addc_u32 s75, s67, 0
	s_waitcnt lgkmcnt(1)
	global_store_dwordx4 v193, v[184:187], s[74:75]
	s_add_u32 s74, s66, 0x3c100
	s_addc_u32 s75, s67, 0
	s_waitcnt lgkmcnt(0)
	global_store_dwordx4 v193, v[200:203], s[74:75]
	global_load_dwordx4 v[160:163], v198, s[70:71] offset:256
	global_load_dwordx4 v[164:167], v198, s[70:71] offset:288
	global_load_dwordx4 v[168:171], v198, s[70:71] offset:320
	global_load_dwordx4 v[172:175], v198, s[70:71] offset:352
	global_load_dwordx4 v[176:179], v198, s[70:71] offset:384
	global_load_dwordx4 v[180:183], v198, s[70:71] offset:416
	global_load_dwordx4 v[184:187], v198, s[70:71] offset:448
	global_load_dwordx4 v[200:203], v198, s[70:71] offset:480
	s_waitcnt vmcnt(7)
	v_mul_f32_e32 v16, v160, v16
	v_mul_f32_e32 v17, v161, v17
	v_mul_f32_e32 v18, v162, v18
	v_mul_f32_e32 v19, v163, v19
	v_cvt_pk_bf16_f32 v16, v16, v17
	v_cvt_pk_bf16_f32 v17, v18, v19
	ds_write_b64 v190, v[16:17]
	s_waitcnt vmcnt(6)
	v_mul_f32_e32 v20, v164, v20
	v_mul_f32_e32 v21, v165, v21
	v_mul_f32_e32 v22, v166, v22
	v_mul_f32_e32 v23, v167, v23
	v_cvt_pk_bf16_f32 v20, v20, v21
	v_cvt_pk_bf16_f32 v21, v22, v23
	ds_write_b64 v190, v[20:21] offset:16
	s_waitcnt vmcnt(5)
	v_mul_f32_e32 v24, v168, v24
	v_mul_f32_e32 v25, v169, v25
	v_mul_f32_e32 v26, v170, v26
	v_mul_f32_e32 v27, v171, v27
	v_cvt_pk_bf16_f32 v24, v24, v25
	v_cvt_pk_bf16_f32 v25, v26, v27
	ds_write_b64 v190, v[24:25] offset:32
	s_waitcnt vmcnt(4)
	v_mul_f32_e32 v28, v172, v28
	v_mul_f32_e32 v29, v173, v29
	v_mul_f32_e32 v30, v174, v30
	v_mul_f32_e32 v31, v175, v31
	v_cvt_pk_bf16_f32 v28, v28, v29
	v_cvt_pk_bf16_f32 v29, v30, v31
	ds_write_b64 v190, v[28:29] offset:48
	s_waitcnt vmcnt(3)
	v_mul_f32_e32 v0, v176, v0
	v_mul_f32_e32 v1, v177, v1
	v_mul_f32_e32 v2, v178, v2
	v_mul_f32_e32 v3, v179, v3
	v_cvt_pk_bf16_f32 v0, v0, v1
	v_cvt_pk_bf16_f32 v1, v2, v3
	ds_write_b64 v190, v[0:1] offset:64
	s_waitcnt vmcnt(2)
	v_mul_f32_e32 v4, v180, v4
	v_mul_f32_e32 v5, v181, v5
	v_mul_f32_e32 v6, v182, v6
	v_mul_f32_e32 v7, v183, v7
	v_cvt_pk_bf16_f32 v4, v4, v5
	v_cvt_pk_bf16_f32 v5, v6, v7
	ds_write_b64 v190, v[4:5] offset:80
	s_waitcnt vmcnt(1)
	v_mul_f32_e32 v8, v184, v8
	v_mul_f32_e32 v9, v185, v9
	v_mul_f32_e32 v10, v186, v10
	v_mul_f32_e32 v11, v187, v11
	v_cvt_pk_bf16_f32 v8, v8, v9
	v_cvt_pk_bf16_f32 v9, v10, v11
	ds_write_b64 v190, v[8:9] offset:96
	s_waitcnt vmcnt(0)
	v_mul_f32_e32 v12, v200, v12
	v_mul_f32_e32 v13, v201, v13
	v_mul_f32_e32 v14, v202, v14
	v_mul_f32_e32 v15, v203, v15
	v_cvt_pk_bf16_f32 v12, v12, v13
	v_cvt_pk_bf16_f32 v13, v14, v15
	ds_write_b64 v190, v[12:13] offset:112
	ds_read_b128 v[160:163], v192
	ds_read_b128 v[164:167], v192 offset:2176
	ds_read_b128 v[168:171], v192 offset:4352
	ds_read_b128 v[172:175], v192 offset:6528
	s_add_u32 s74, s68, 0x10080
	s_addc_u32 s75, s69, 0
	s_waitcnt lgkmcnt(3)
	global_store_dwordx4 v194, v[160:163], s[74:75]
	s_add_u32 s74, s68, 0x14080
	s_addc_u32 s75, s69, 0
	s_waitcnt lgkmcnt(2)
	global_store_dwordx4 v194, v[164:167], s[74:75]
	s_add_u32 s74, s68, 0x18080
	s_addc_u32 s75, s69, 0
	s_waitcnt lgkmcnt(1)
	global_store_dwordx4 v194, v[168:171], s[74:75]
	s_add_u32 s74, s68, 0x1c080
	s_addc_u32 s75, s69, 0
	s_waitcnt lgkmcnt(0)
	global_store_dwordx4 v194, v[172:175], s[74:75]
	s_load_dwordx2 s[64:65], s[92:93], 0x140
	ds_bpermute_b32 v208, v206, v199
	ds_bpermute_b32 v209, v206, v204
	s_waitcnt lgkmcnt(0)
	v_add_f32_e32 v208, v208, v199
	v_add_f32_e32 v209, v209, v204
	s_mov_b32 exec_hi, 0
	s_nop 1
	global_atomic_add_f32 v205, v208, s[64:65]
	global_atomic_add_f32 v205, v209, s[64:65] offset:128
	s_mov_b64 exec, -1
	v_readlane_b32 s64, v207, 0
	v_readlane_b32 s65, v207, 1
	v_readlane_b32 s66, v207, 2
	v_readlane_b32 s67, v207, 3
	v_readlane_b32 s68, v207, 4
	v_readlane_b32 s69, v207, 5
	v_readlane_b32 s70, v207, 6
	v_readlane_b32 s71, v207, 7
	v_readlane_b32 s72, v207, 8
	v_readlane_b32 s73, v207, 9
	v_readlane_b32 s74, v207, 10
	v_readlane_b32 s75, v207, 11
	v_readlane_b32 s76, v207, 12
	v_readlane_b32 s77, v207, 13
	v_readlane_b32 s78, v207, 14
	v_readlane_b32 s79, v207, 15
	s_nop 7
	s_branch .LBB0_840

; #define GA_LOAD(pr_) do { _Pragma("unroll") for (int i = 0; i < 4; ++i) ra[i] = *(const u32x4*)(Ab + (i * 32) * lda + (pr_) * 64); } while (0)
; #define GB_LOAD(kt_) do { const bfr* bk_ = Bb + (kt_) * NB * 32; \
;     _Pragma("unroll") for (int i = 0; i < 4; ++i) rb[i] = *(const u32x4*)(bk_ + (i * 64) * 32); } while (0)
; #define G_STORE(kt_) do { bfr* as_ = S0 + ((kt_) & 1) * GSTAGE; bfr* bs_ = as_ + 128 * 40; \
;     if (apar == ((kt_) & 1)) { _Pragma("unroll") for (int i = 0; i < 4; ++i) *(u32x4*)(as_ + asoff + i * 32 * 40) = ra[i]; } \
;     _Pragma("unroll") for (int i = 0; i < 4; ++i) *(u32x4*)(bs_ + bsoff + i * 64 * 40) = rb[i]; } while (0)
; template <int lda>
; DI void gemm_mainloop(const bfr* __restrict__ A, const bfr* __restrict__ Bt, int NB, int K, int m0, int n0, char* smem, f32x16 (&acc)[2][4]) {
;     ...
;   const int arow = tid >> 3, ac8 = tid & 7, apar = ac8 >> 2;
;   const bfr* Ab = A + (m0 + arow) * lda + ac8 * 8;
;   const int asoff = arow * 40 + (ac8 & 3) * 8;
;   const int brow = tid >> 2, bc4 = tid & 3;
;   const bfr* Bb = Bt + (n0 + brow) * 32 + bc4 * 8;
;   const int bsoff = brow * 40 + bc4 * 8;
;     ...
;   GA_LOAD(0);
;   GB_LOAD(0);
;   G_STORE(0);
;   GB_LOAD(1);
;   __syncthreads();
; template <bool FIRST, bool HAS_H>
; DI void phase_gemm_resid(const Params& p, const bfr* A, const bfr* Wt, const float* gnext, float* ss, char* smem) {
;     ...
;   for (int t0 = blockIdx.x; t0 < 128 * 4; t0 += gridDim.x) {
;     const int t = ((gridDim.x & 7) == 0) ? xcd_tile(t0, 4) : t0;
;     const int mt = t >> 2, nt = t & 3, m0 = mt * 128, n0 = nt * 256;
;     f32x16 acc[2][4];
;     gemm_mainloop<1024>(A, Wt, 1024, 1024, m0, n0, smem, acc);
;     int tid2 = threadIdx.x;
;     asm volatile("" : "+v"(tid2));
;     const int lane = tid2 & 63, wid = tid2 >> 6, wr = wid >> 1, wc = wid & 1, r = lane & 31, hl = lane >> 5;
.LBB0_1099:
	s_lshl_b32 s5, s4, 5
	s_and_b32 s36, s5, 0xffffff80
	s_lshl_b32 s4, s4, 8
	s_and_b32 s33, s4, 0x300
	s_mov_b32 s37, 0
	s_mov_b64 s[20:21], 0
	s_lshl_b32 s98, s36, 11
	s_add_u32 s98, s2, s98
	s_addc_u32 s99, s3, 0
	s_lshl_b32 s100, s33, 6
	s_add_u32 s100, s8, s100
	s_addc_u32 s101, s9, 0
	v_writelane_b32 v207, s64, 0
	v_writelane_b32 v207, s65, 1
	v_writelane_b32 v207, s66, 2
	v_writelane_b32 v207, s67, 3
	v_writelane_b32 v207, s68, 4
	v_writelane_b32 v207, s69, 5
	v_writelane_b32 v207, s70, 6
	v_writelane_b32 v207, s71, 7
	v_writelane_b32 v207, s72, 8
	v_writelane_b32 v207, s73, 9
	v_writelane_b32 v207, s74, 10
	v_writelane_b32 v207, s75, 11
	v_writelane_b32 v207, s76, 12
	v_writelane_b32 v207, s77, 13
	v_writelane_b32 v207, s78, 14
	v_writelane_b32 v207, s79, 15
	s_mov_b32 s77, s36
	s_mov_b32 s78, s33
	v_lshrrev_b32_e32 v208, 6, v196
	v_and_b32_e32 v209, 63, v196
	v_readfirstlane_b32 s73, v208
	v_lshrrev_b32_e32 v210, 2, v209
	v_bfe_u32 v211, v209, 4, 2
	v_and_b32_e32 v208, 3, v209
	v_xor_b32_e32 v208, v208, v211
	v_lshlrev_b32_e32 v208, 4, v208
	v_lshl_add_u32 v192, v210, 11, v208
	v_add_u32_e32 v194, 0x8000, v192
	v_lshl_add_u32 v198, v210, 6, v208
	v_and_b32_e32 v210, 31, v209
	v_lshrrev_b32_e32 v211, 5, v209
	v_bfe_u32 v208, v209, 2, 2
	v_xor_b32_e32 v208, v208, v211
	v_lshlrev_b32_e32 v208, 4, v208
	v_lshl_add_u32 v199, v210, 6, v208
	s_lshr_b32 s74, s73, 1
	s_lshl_b32 s74, s74, 12
	s_and_b32 s75, s73, 1
	s_lshl_b32 s75, s75, 13
	v_add_u32_e32 v201, s75, v199
	v_add_u32_e32 v199, s74, v199
	v_xor_b32_e32 v202, 32, v201
	v_xor_b32_e32 v200, 32, v199
	s_lshl_b32 s74, s73, 16
	s_add_u32 s64, s98, s74
	s_addc_u32 s65, s99, 0
	s_lshl_b32 s74, s73, 12
	s_add_u32 s66, s100, s74
	s_addc_u32 s67, s101, 0
	s_lshl_b32 s68, s73, 11
	s_lshl_b32 s69, s73, 12
	s_mov_b32 s70, 0
	s_mov_b32 s71, 0
	s_mov_b32 s72, 0
	s_waitcnt lgkmcnt(0)
	s_barrier
	s_mul_i32 s74, s70, 0x6000
	s_add_u32 s75, s74, s68
	s_mov_b32 m0, s75
	s_add_u32 s76, s74, 0x2000
	s_cmp_eq_u32 s70, 2
	s_cselect_b32 s76, 0x10000, s76
	global_load_lds_dwordx4 v192, s[64:65]
	s_add_u32 m0, s75, 0x400
	s_add_u32 s76, s76, s69
	global_load_lds_dwordx4 v194, s[64:65]
	s_mov_b32 m0, s76
	s_add_u32 s64, s64, 64
	s_addc_u32 s65, s65, 0
	global_load_lds_dwordx4 v198, s[66:67]
	global_load_lds_dwordx4 v198, s[66:67] offset:1024
	global_load_lds_dwordx4 v198, s[66:67] offset:2048
	global_load_lds_dwordx4 v198, s[66:67] offset:3072
	s_add_u32 s66, s66, 0x10000
	s_addc_u32 s67, s67, 0
	s_add_u32 s70, s70, 1
	s_cmp_eq_u32 s70, 3
	s_cselect_b32 s70, 0, s70
	s_mul_i32 s74, s70, 0x6000
	s_add_u32 s75, s74, s68
	s_mov_b32 m0, s75
	s_add_u32 s76, s74, 0x2000
	s_cmp_eq_u32 s70, 2
	s_cselect_b32 s76, 0x10000, s76
	global_load_lds_dwordx4 v192, s[64:65]
	s_add_u32 m0, s75, 0x400
	s_add_u32 s76, s76, s69
	global_load_lds_dwordx4 v194, s[64:65]
	s_mov_b32 m0, s76
	s_add_u32 s64, s64, 64
	s_addc_u32 s65, s65, 0
	global_load_lds_dwordx4 v198, s[66:67]
	global_load_lds_dwordx4 v198, s[66:67] offset:1024
	global_load_lds_dwordx4 v198, s[66:67] offset:2048
	global_load_lds_dwordx4 v198, s[66:67] offset:3072
	s_add_u32 s66, s66, 0x10000
	s_addc_u32 s67, s67, 0
	s_add_u32 s70, s70, 1
	s_cmp_eq_u32 s70, 3
	s_cselect_b32 s70, 0, s70
	s_cmp_lt_u32 s46, 0x100
	s_cbranch_scc1 .Lp10_nostag
	s_sleep 8

; #define MFMA32(a, b, c) __builtin_amdgcn_mfma_f32_32x32x16_bf16((a), (b), (c), 0, 0, 0)
; #define GA_LOAD(pr_) do { _Pragma("unroll") for (int i = 0; i < 4; ++i) ra[i] = *(const u32x4*)(Ab + (i * 32) * lda + (pr_) * 64); } while (0)
; #define GB_LOAD(kt_) do { const bfr* bk_ = Bb + (kt_) * NB * 32; \
;     _Pragma("unroll") for (int i = 0; i < 4; ++i) rb[i] = *(const u32x4*)(bk_ + (i * 64) * 32); } while (0)
; #define G_STORE(kt_) do { bfr* as_ = S0 + ((kt_) & 1) * GSTAGE; bfr* bs_ = as_ + 128 * 40; \
;     if (apar == ((kt_) & 1)) { _Pragma("unroll") for (int i = 0; i < 4; ++i) *(u32x4*)(as_ + asoff + i * 32 * 40) = ra[i]; } \
;     _Pragma("unroll") for (int i = 0; i < 4; ++i) *(u32x4*)(bs_ + bsoff + i * 64 * 40) = rb[i]; } while (0)
; template <int lda>
; DI void gemm_mainloop(const bfr* __restrict__ A, const bfr* __restrict__ Bt, int NB, int K, int m0, int n0, char* smem, f32x16 (&acc)[2][4]) {
;     ...
;   for (int kt = 0; kt < nk; ++kt) {
;     if (kt + 1 < nk) G_STORE(kt + 1);
;     if (kt + 2 < nk) {
;       GB_LOAD(kt + 2);
;       if ((kt & 1) == 0) GA_LOAD((kt >> 1) + 1);
;     }
;     const bfr* As = S0 + (kt & 1) * GSTAGE;
;     const bfr* Bs = As + 128 * 40;
; #pragma unroll
;     for (int ks = 0; ks < 2; ++ks) {
;       bf16x8 af[2], bfg[4];
; #pragma unroll
;       for (int i = 0; i < 2; ++i) af[i] = *(const bf16x8*)(As + (wr * 64 + i * 32 + r) * 40 + ks * 16 + hl * 8);
; #pragma unroll
;       for (int j = 0; j < 4; ++j) bfg[j] = *(const bf16x8*)(Bs + (wc * 128 + j * 32 + r) * 40 + ks * 16 + hl * 8);
; #pragma unroll
;       for (int i = 0; i < 2; ++i)
; #pragma unroll
;         for (int j = 0; j < 4; ++j) acc[i][j] = MFMA32(af[i], bfg[j], acc[i][j]);
;     }
;     __syncthreads();
;   }
.Lp10_loop:
	s_waitcnt vmcnt(6)
	s_barrier
	s_mul_i32 s74, s71, 0x6000
	s_add_u32 s75, s74, 0x2000
	s_cmp_eq_u32 s71, 2
	s_cselect_b32 s75, 0x10000, s75
	v_add_u32_e32 v203, s74, v199
	v_add_u32_e32 v205, s75, v201
	v_add_u32_e32 v204, s74, v200
	v_add_u32_e32 v206, s75, v202
	ds_read_b128 v[128:131], v203
	ds_read_b128 v[144:147], v205
	ds_read_b128 v[148:151], v205 offset:2048
	ds_read_b128 v[152:155], v205 offset:4096
	ds_read_b128 v[156:159], v205 offset:6144
	ds_read_b128 v[132:135], v203 offset:2048
	ds_read_b128 v[136:139], v204
	ds_read_b128 v[160:163], v206
	ds_read_b128 v[164:167], v206 offset:2048
	ds_read_b128 v[168:171], v206 offset:4096
	ds_read_b128 v[172:175], v206 offset:6144
	ds_read_b128 v[140:143], v204 offset:2048
	s_add_u32 s71, s71, 1
	s_cmp_eq_u32 s71, 3
	s_cselect_b32 s71, 0, s71
	s_waitcnt lgkmcnt(10)
	v_mfma_f32_32x32x16_bf16 v[112:127], v[144:147], v[128:131], v[112:127]
	s_mul_i32 s74, s70, 0x6000
	s_add_u32 s75, s74, s68
	s_mov_b32 m0, s75
	s_add_u32 s76, s74, 0x2000
	s_cmp_eq_u32 s70, 2
	s_cselect_b32 s76, 0x10000, s76
	global_load_lds_dwordx4 v192, s[64:65]
	s_waitcnt lgkmcnt(9)
	v_mfma_f32_32x32x16_bf16 v[96:111], v[148:151], v[128:131], v[96:111]
	s_add_u32 m0, s75, 0x400
	s_add_u32 s76, s76, s69
	global_load_lds_dwordx4 v194, s[64:65]
	s_waitcnt lgkmcnt(8)
	v_mfma_f32_32x32x16_bf16 v[80:95], v[152:155], v[128:131], v[80:95]
	s_mov_b32 m0, s76
	s_add_u32 s64, s64, 64
	s_addc_u32 s65, s65, 0
	global_load_lds_dwordx4 v198, s[66:67]
	s_waitcnt lgkmcnt(7)
	v_mfma_f32_32x32x16_bf16 v[64:79], v[156:159], v[128:131], v[64:79]
	global_load_lds_dwordx4 v198, s[66:67] offset:1024
	s_waitcnt lgkmcnt(6)
	v_mfma_f32_32x32x16_bf16 v[48:63], v[144:147], v[132:135], v[48:63]
	global_load_lds_dwordx4 v198, s[66:67] offset:2048
	v_mfma_f32_32x32x16_bf16 v[32:47], v[148:151], v[132:135], v[32:47]
	global_load_lds_dwordx4 v198, s[66:67] offset:3072
	s_add_u32 s66, s66, 0x10000
	s_addc_u32 s67, s67, 0
	v_mfma_f32_32x32x16_bf16 v[16:31], v[152:155], v[132:135], v[16:31]
	s_add_u32 s70, s70, 1
	s_cmp_eq_u32 s70, 3
	s_cselect_b32 s70, 0, s70
	v_mfma_f32_32x32x16_bf16 v[0:15], v[156:159], v[132:135], v[0:15]
	s_waitcnt lgkmcnt(4)
	v_mfma_f32_32x32x16_bf16 v[112:127], v[160:163], v[136:139], v[112:127]
	s_waitcnt lgkmcnt(3)
	v_mfma_f32_32x32x16_bf16 v[96:111], v[164:167], v[136:139], v[96:111]
	s_waitcnt lgkmcnt(2)
	v_mfma_f32_32x32x16_bf16 v[80:95], v[168:171], v[136:139], v[80:95]
	s_waitcnt lgkmcnt(1)
	v_mfma_f32_32x32x16_bf16 v[64:79], v[172:175], v[136:139], v[64:79]
	s_waitcnt lgkmcnt(0)
	v_mfma_f32_32x32x16_bf16 v[48:63], v[160:163], v[140:143], v[48:63]
	v_mfma_f32_32x32x16_bf16 v[32:47], v[164:167], v[140:143], v[32:47]
	v_mfma_f32_32x32x16_bf16 v[16:31], v[168:171], v[140:143], v[16:31]
	v_mfma_f32_32x32x16_bf16 v[0:15], v[172:175], v[140:143], v[0:15]
	s_add_u32 s72, s72, 1
	s_cmp_lt_u32 s72, 30
	s_cbranch_scc1 .Lp10_loop
	s_waitcnt vmcnt(6)
	s_barrier
	s_mul_i32 s74, s71, 0x6000
	s_add_u32 s75, s74, 0x2000
	s_cmp_eq_u32 s71, 2
	s_cselect_b32 s75, 0x10000, s75
	v_add_u32_e32 v203, s74, v199
	v_add_u32_e32 v205, s75, v201
	v_add_u32_e32 v204, s74, v200
	v_add_u32_e32 v206, s75, v202
	ds_read_b128 v[128:131], v203
	ds_read_b128 v[144:147], v205
	ds_read_b128 v[148:151], v205 offset:2048
	ds_read_b128 v[152:155], v205 offset:4096
	ds_read_b128 v[156:159], v205 offset:6144
	ds_read_b128 v[132:135], v203 offset:2048
	ds_read_b128 v[136:139], v204
	ds_read_b128 v[160:163], v206
	ds_read_b128 v[164:167], v206 offset:2048
	ds_read_b128 v[168:171], v206 offset:4096
	ds_read_b128 v[172:175], v206 offset:6144
	ds_read_b128 v[140:143], v204 offset:2048
	s_add_u32 s71, s71, 1
	s_cmp_eq_u32 s71, 3
	s_cselect_b32 s71, 0, s71
	s_waitcnt lgkmcnt(10)
	v_mfma_f32_32x32x16_bf16 v[112:127], v[144:147], v[128:131], v[112:127]
	s_waitcnt lgkmcnt(9)
	v_mfma_f32_32x32x16_bf16 v[96:111], v[148:151], v[128:131], v[96:111]
	s_waitcnt lgkmcnt(8)
	v_mfma_f32_32x32x16_bf16 v[80:95], v[152:155], v[128:131], v[80:95]
	s_waitcnt lgkmcnt(7)
	v_mfma_f32_32x32x16_bf16 v[64:79], v[156:159], v[128:131], v[64:79]
	s_waitcnt lgkmcnt(6)
	v_mfma_f32_32x32x16_bf16 v[48:63], v[144:147], v[132:135], v[48:63]
	v_mfma_f32_32x32x16_bf16 v[32:47], v[148:151], v[132:135], v[32:47]
	v_mfma_f32_32x32x16_bf16 v[16:31], v[152:155], v[132:135], v[16:31]
	v_mfma_f32_32x32x16_bf16 v[0:15], v[156:159], v[132:135], v[0:15]
	s_waitcnt lgkmcnt(4)
	v_mfma_f32_32x32x16_bf16 v[112:127], v[160:163], v[136:139], v[112:127]
	s_waitcnt lgkmcnt(3)
	v_mfma_f32_32x32x16_bf16 v[96:111], v[164:167], v[136:139], v[96:111]
	s_waitcnt lgkmcnt(2)
	v_mfma_f32_32x32x16_bf16 v[80:95], v[168:171], v[136:139], v[80:95]
	s_waitcnt lgkmcnt(1)
	v_mfma_f32_32x32x16_bf16 v[64:79], v[172:175], v[136:139], v[64:79]
	s_waitcnt lgkmcnt(0)
	v_mfma_f32_32x32x16_bf16 v[48:63], v[160:163], v[140:143], v[48:63]
	v_mfma_f32_32x32x16_bf16 v[32:47], v[164:167], v[140:143], v[32:47]
	v_mfma_f32_32x32x16_bf16 v[16:31], v[168:171], v[140:143], v[16:31]
	v_mfma_f32_32x32x16_bf16 v[0:15], v[172:175], v[140:143], v[0:15]
	s_waitcnt vmcnt(0)
	s_barrier
; #define MFMA32(a, b, c) __builtin_amdgcn_mfma_f32_32x32x16_bf16((a), (b), (c), 0, 0, 0)
; DI int crow(int reg, int h) { return (reg & 3) + 8 * (reg >> 2) + 4 * h; }
; #define GA_LOAD(pr_) do { _Pragma("unroll") for (int i = 0; i < 4; ++i) ra[i] = *(const u32x4*)(Ab + (i * 32) * lda + (pr_) * 64); } while (0)
; template <int lda>
; DI void gemm_mainloop(const bfr* __restrict__ A, const bfr* __restrict__ Bt, int NB, int K, int m0, int n0, char* smem, f32x16 (&acc)[2][4]) {
;     ...
;   for (int kt = 0; kt < nk; ++kt) {
;     if (kt + 1 < nk) G_STORE(kt + 1);
;     if (kt + 2 < nk) {
;       GB_LOAD(kt + 2);
;       if ((kt & 1) == 0) GA_LOAD((kt >> 1) + 1);
;     }
;     const bfr* As = S0 + (kt & 1) * GSTAGE;
;     const bfr* Bs = As + 128 * 40;
; #pragma unroll
;     for (int ks = 0; ks < 2; ++ks) {
;       bf16x8 af[2], bfg[4];
; #pragma unroll
;       for (int i = 0; i < 2; ++i) af[i] = *(const bf16x8*)(As + (wr * 64 + i * 32 + r) * 40 + ks * 16 + hl * 8);
; #pragma unroll
;       for (int j = 0; j < 4; ++j) bfg[j] = *(const bf16x8*)(Bs + (wc * 128 + j * 32 + r) * 40 + ks * 16 + hl * 8);
; #pragma unroll
;       for (int i = 0; i < 2; ++i)
; #pragma unroll
;         for (int j = 0; j < 4; ++j) acc[i][j] = MFMA32(af[i], bfg[j], acc[i][j]);
;     }
;     __syncthreads();
;   }
; template <bool FIRST, bool HAS_H>
; DI void phase_gemm_resid(const Params& p, const bfr* A, const bfr* Wt, const float* gnext, float* ss, char* smem) {
;     ...
;     int tid2 = threadIdx.x;
;     asm volatile("" : "+v"(tid2));
;     const int lane = tid2 & 63, wid = tid2 >> 6, wr = wid >> 1, wc = wid & 1, r = lane & 31, hl = lane >> 5;
;     const float* xsrc = FIRST ? p.x_prompt : X;
;     const int rbase = m0 + wr * 64 + 4 * hl, cbase = n0 + wc * 128 + r;
; #pragma unroll
;     for (int i = 0; i < 2; ++i) {
; #pragma unroll
;       for (int qh = 0; qh < 2; ++qh) {
;         float rs[8];
; #pragma unroll
;         for (int q = 0; q < 8; ++q) rs[q] = 0.f;
; #pragma unroll
;         for (int jh = 0; jh < 2; ++jh) {
;           float xo[2][8];
; #pragma unroll
;           for (int jj = 0; jj < 2; ++jj)
; #pragma unroll
;             for (int q = 0; q < 8; ++q)
;               xo[jj][q] = xsrc[(rbase + i * 32 + crow(qh * 8 + q, 0)) * 1024 + cbase + (jh * 2 + jj) * 32];
	s_mul_i32 s74, s71, 0x6000
	s_add_u32 s75, s74, 0x2000
	s_cmp_eq_u32 s71, 2
	s_cselect_b32 s75, 0x10000, s75
	v_add_u32_e32 v203, s74, v199
	v_add_u32_e32 v205, s75, v201
	v_add_u32_e32 v204, s74, v200
	v_add_u32_e32 v206, s75, v202
	ds_read_b128 v[128:131], v203
	ds_read_b128 v[144:147], v205
	ds_read_b128 v[148:151], v205 offset:2048
	ds_read_b128 v[152:155], v205 offset:4096
	ds_read_b128 v[156:159], v205 offset:6144
	ds_read_b128 v[132:135], v203 offset:2048
	ds_read_b128 v[136:139], v204
	ds_read_b128 v[160:163], v206
	ds_read_b128 v[164:167], v206 offset:2048
	ds_read_b128 v[168:171], v206 offset:4096
	ds_read_b128 v[172:175], v206 offset:6144
	ds_read_b128 v[140:143], v204 offset:2048
	s_add_u32 s71, s71, 1
	s_cmp_eq_u32 s71, 3
	s_cselect_b32 s71, 0, s71
	s_waitcnt lgkmcnt(10)
	v_mfma_f32_32x32x16_bf16 v[112:127], v[144:147], v[128:131], v[112:127]
	s_waitcnt lgkmcnt(9)
	v_mfma_f32_32x32x16_bf16 v[96:111], v[148:151], v[128:131], v[96:111]
	s_waitcnt lgkmcnt(8)
	v_mfma_f32_32x32x16_bf16 v[80:95], v[152:155], v[128:131], v[80:95]
	s_waitcnt lgkmcnt(7)
	v_mfma_f32_32x32x16_bf16 v[64:79], v[156:159], v[128:131], v[64:79]
	s_waitcnt lgkmcnt(6)
	v_mfma_f32_32x32x16_bf16 v[48:63], v[144:147], v[132:135], v[48:63]
	v_mfma_f32_32x32x16_bf16 v[32:47], v[148:151], v[132:135], v[32:47]
	v_mfma_f32_32x32x16_bf16 v[16:31], v[152:155], v[132:135], v[16:31]
	v_mfma_f32_32x32x16_bf16 v[0:15], v[156:159], v[132:135], v[0:15]
	s_waitcnt lgkmcnt(4)
	v_mfma_f32_32x32x16_bf16 v[112:127], v[160:163], v[136:139], v[112:127]
	s_waitcnt lgkmcnt(3)
	v_mfma_f32_32x32x16_bf16 v[96:111], v[164:167], v[136:139], v[96:111]
	s_waitcnt lgkmcnt(2)
	v_mfma_f32_32x32x16_bf16 v[80:95], v[168:171], v[136:139], v[80:95]
	s_waitcnt lgkmcnt(1)
	v_mfma_f32_32x32x16_bf16 v[64:79], v[172:175], v[136:139], v[64:79]
	s_waitcnt lgkmcnt(0)
	v_mfma_f32_32x32x16_bf16 v[48:63], v[160:163], v[140:143], v[48:63]
	v_mfma_f32_32x32x16_bf16 v[32:47], v[164:167], v[140:143], v[32:47]
	v_mfma_f32_32x32x16_bf16 v[16:31], v[168:171], v[140:143], v[16:31]
	v_mfma_f32_32x32x16_bf16 v[0:15], v[172:175], v[140:143], v[0:15]
	s_nop 7
	s_nop 3
	s_load_dwordx2 s[64:65], s[92:93], 0x100
	s_load_dwordx2 s[66:67], s[92:93], 0x100
	s_load_dwordx2 s[68:69], s[92:93], 0x148
	s_load_dwordx2 s[70:71], s[92:93], 0x48
	s_mul_i32 s76, s73, 8704
	s_lshr_b32 s74, s73, 1
	s_lshl_b32 s74, s74, 6
	s_add_u32 s74, s74, s77
	s_and_b32 s75, s73, 1
	s_lshl_b32 s75, s75, 7
	s_add_u32 s75, s75, s78
	v_and_b32_e32 v208, 31, v196
	v_bfe_u32 v209, v196, 5, 1
	v_mul_u32_u24_e32 v210, 272, v208
	v_add_u32_e32 v210, s76, v210
	v_lshl_add_u32 v192, v209, 4, v210
	v_lshl_add_u32 v194, v209, 3, v210
	v_lshlrev_b32_e32 v210, 2, v209
	v_add_lshl_u32 v202, v210, s75, 2
	v_add_lshl_u32 v205, v208, s74, 2
	v_and_b32_e32 v210, 63, v196
	v_xor_b32_e32 v210, 32, v210
	v_lshlrev_b32_e32 v206, 2, v210
	v_bfe_u32 v208, v196, 4, 2
	v_and_b32_e32 v209, 15, v196
	v_mul_u32_u24_e32 v210, 272, v208
	v_lshl_add_u32 v210, v209, 4, v210
	v_add_u32_e32 v198, s76, v210
	v_add_u32_e32 v210, s74, v208
	v_lshlrev_b32_e32 v210, 10, v210
	v_lshl_add_u32 v210, v209, 2, v210
	v_add_lshl_u32 v200, v210, s75, 2
	s_mov_b32 s79, s74
	s_mov_b32 s72, s75
	s_waitcnt lgkmcnt(0)
	s_add_u32 s74, s64, 0x0
	s_addc_u32 s75, s65, 0
	global_load_dwordx4 v[128:131], v200, s[74:75]
	s_add_u32 s74, s64, 0x4000
	s_addc_u32 s75, s65, 0
	global_load_dwordx4 v[132:135], v200, s[74:75]
	s_add_u32 s74, s64, 0x8000
	s_addc_u32 s75, s65, 0
	global_load_dwordx4 v[136:139], v200, s[74:75]
	s_add_u32 s74, s64, 0xc000
	s_addc_u32 s75, s65, 0
	global_load_dwordx4 v[140:143], v200, s[74:75]
	s_add_u32 s74, s64, 0x10000
	s_addc_u32 s75, s65, 0
	global_load_dwordx4 v[144:147], v200, s[74:75]
	s_add_u32 s74, s64, 0x14000
	s_addc_u32 s75, s65, 0
	global_load_dwordx4 v[148:151], v200, s[74:75]
	s_add_u32 s74, s64, 0x18000
	s_addc_u32 s75, s65, 0
	global_load_dwordx4 v[152:155], v200, s[74:75]
	s_add_u32 s74, s64, 0x1c000
	s_addc_u32 s75, s65, 0
	global_load_dwordx4 v[156:159], v200, s[74:75]
	s_mov_b32 s74, s79
	s_mov_b32 s75, s72
	v_bfe_u32 v208, v196, 3, 3
	v_and_b32_e32 v209, 7, v196
	v_mul_u32_u24_e32 v210, 272, v208
	v_lshl_add_u32 v210, v209, 4, v210
	v_add_u32_e32 v199, s76, v210
	v_add_u32_e32 v210, s74, v208
	v_lshlrev_b32_e32 v210, 10, v210
	v_lshl_add_u32 v210, v209, 3, v210
	v_add_lshl_u32 v201, v210, s75, 1
	v_mov_b32_e32 v203, 0
	v_mov_b32_e32 v204, 0
	s_waitcnt lgkmcnt(0)
	s_barrier
; DI bfr f2bf(float a) { return (bfr)(pack2(a, 0.f) & 0xffffu); }
; DI int crow(int reg, int h) { return (reg & 3) + 8 * (reg >> 2) + 4 * h; }
; template <bool FIRST, bool HAS_H>
; DI void phase_gemm_resid(const Params& p, const bfr* A, const bfr* Wt, const float* gnext, float* ss, char* smem) {
;     ...
;         for (int jh = 0; jh < 2; ++jh) {
;           float xo[2][8];
; #pragma unroll
;           for (int jj = 0; jj < 2; ++jj)
; #pragma unroll
;             for (int q = 0; q < 8; ++q)
;               xo[jj][q] = xsrc[(rbase + i * 32 + crow(qh * 8 + q, 0)) * 1024 + cbase + (jh * 2 + jj) * 32];
; #pragma unroll
;           for (int q = 0; q < 8; ++q) {
;             const int o = (rbase + i * 32 + crow(qh * 8 + q, 0)) * 1024 + cbase;
; #pragma unroll
;             for (int jj = 0; jj < 2; ++jj) {
;               const int j = jh * 2 + jj;
;               const float xn = xo[jj][q] + acc[i][j][qh * 8 + q];
;               X[o + j * 32] = xn;
;               if (HAS_H) Hn[o + j * 32] = f2bf(xn * gnext[cbase + j * 32]);
;               rs[q] += xn * xn;
;             }
;           }
	s_add_u32 s70, s70, 0x1000
	s_addc_u32 s71, s71, 0
	s_waitcnt vmcnt(7)
	ds_write_b128 v198, v[128:131]
	s_waitcnt vmcnt(6)
	ds_write_b128 v198, v[132:135] offset:1088
	s_waitcnt vmcnt(5)
	ds_write_b128 v198, v[136:139] offset:2176
	s_waitcnt vmcnt(4)
	ds_write_b128 v198, v[140:143] offset:3264
	s_waitcnt vmcnt(3)
	ds_write_b128 v198, v[144:147] offset:4352
	s_waitcnt vmcnt(2)
	ds_write_b128 v198, v[148:151] offset:5440
	s_waitcnt vmcnt(1)
	ds_write_b128 v198, v[152:155] offset:6528
	s_waitcnt vmcnt(0)
	ds_write_b128 v198, v[156:159] offset:7616
	s_add_u32 s74, s64, 0x100
	s_addc_u32 s75, s65, 0
	global_load_dwordx4 v[128:131], v200, s[74:75]
	s_add_u32 s74, s64, 0x4100
	s_addc_u32 s75, s65, 0
	global_load_dwordx4 v[132:135], v200, s[74:75]
	s_add_u32 s74, s64, 0x8100
	s_addc_u32 s75, s65, 0
	global_load_dwordx4 v[136:139], v200, s[74:75]
	s_add_u32 s74, s64, 0xc100
	s_addc_u32 s75, s65, 0
	global_load_dwordx4 v[140:143], v200, s[74:75]
	s_add_u32 s74, s64, 0x10100
	s_addc_u32 s75, s65, 0
	global_load_dwordx4 v[144:147], v200, s[74:75]
	s_add_u32 s74, s64, 0x14100
	s_addc_u32 s75, s65, 0
	global_load_dwordx4 v[148:151], v200, s[74:75]
	s_add_u32 s74, s64, 0x18100
	s_addc_u32 s75, s65, 0
	global_load_dwordx4 v[152:155], v200, s[74:75]
	s_add_u32 s74, s64, 0x1c100
	s_addc_u32 s75, s65, 0
	global_load_dwordx4 v[156:159], v200, s[74:75]
	ds_read_b128 v[160:163], v192
	ds_read_b128 v[164:167], v192 offset:32
	ds_read_b128 v[168:171], v192 offset:64
	ds_read_b128 v[172:175], v192 offset:96
	ds_read_b128 v[176:179], v192 offset:128
	ds_read_b128 v[180:183], v192 offset:160
	ds_read_b128 v[184:187], v192 offset:192
	ds_read_b128 v[188:191], v192 offset:224
	s_waitcnt lgkmcnt(7)
	v_add_f32_e32 v112, v160, v112
	v_add_f32_e32 v113, v161, v113
	v_add_f32_e32 v114, v162, v114
	v_add_f32_e32 v115, v163, v115
	v_fmac_f32_e32 v203, v112, v112
	v_fmac_f32_e32 v203, v113, v113
	v_fmac_f32_e32 v203, v114, v114
	v_fmac_f32_e32 v203, v115, v115
	ds_write_b128 v192, v[112:115]
	s_waitcnt lgkmcnt(7)
	v_add_f32_e32 v116, v164, v116
	v_add_f32_e32 v117, v165, v117
	v_add_f32_e32 v118, v166, v118
	v_add_f32_e32 v119, v167, v119
	v_fmac_f32_e32 v203, v116, v116
	v_fmac_f32_e32 v203, v117, v117
	v_fmac_f32_e32 v203, v118, v118
	v_fmac_f32_e32 v203, v119, v119
	ds_write_b128 v192, v[116:119] offset:32
	s_waitcnt lgkmcnt(7)
	v_add_f32_e32 v120, v168, v120
	v_add_f32_e32 v121, v169, v121
	v_add_f32_e32 v122, v170, v122
	v_add_f32_e32 v123, v171, v123
	v_fmac_f32_e32 v203, v120, v120
	v_fmac_f32_e32 v203, v121, v121
	v_fmac_f32_e32 v203, v122, v122
	v_fmac_f32_e32 v203, v123, v123
	ds_write_b128 v192, v[120:123] offset:64
	s_waitcnt lgkmcnt(7)
	v_add_f32_e32 v124, v172, v124
	v_add_f32_e32 v125, v173, v125
	v_add_f32_e32 v126, v174, v126
	v_add_f32_e32 v127, v175, v127
	v_fmac_f32_e32 v203, v124, v124
	v_fmac_f32_e32 v203, v125, v125
	v_fmac_f32_e32 v203, v126, v126
	v_fmac_f32_e32 v203, v127, v127
	ds_write_b128 v192, v[124:127] offset:96
	s_waitcnt lgkmcnt(7)
	v_add_f32_e32 v96, v176, v96
	v_add_f32_e32 v97, v177, v97
	v_add_f32_e32 v98, v178, v98
	v_add_f32_e32 v99, v179, v99
	v_fmac_f32_e32 v203, v96, v96
	v_fmac_f32_e32 v203, v97, v97
	v_fmac_f32_e32 v203, v98, v98
	v_fmac_f32_e32 v203, v99, v99
	ds_write_b128 v192, v[96:99] offset:128
	s_waitcnt lgkmcnt(7)
	v_add_f32_e32 v100, v180, v100
	v_add_f32_e32 v101, v181, v101
	v_add_f32_e32 v102, v182, v102
	v_add_f32_e32 v103, v183, v103
	v_fmac_f32_e32 v203, v100, v100
	v_fmac_f32_e32 v203, v101, v101
	v_fmac_f32_e32 v203, v102, v102
	v_fmac_f32_e32 v203, v103, v103
	ds_write_b128 v192, v[100:103] offset:160
	s_waitcnt lgkmcnt(7)
	v_add_f32_e32 v104, v184, v104
	v_add_f32_e32 v105, v185, v105
	v_add_f32_e32 v106, v186, v106
	v_add_f32_e32 v107, v187, v107
	v_fmac_f32_e32 v203, v104, v104
	v_fmac_f32_e32 v203, v105, v105
	v_fmac_f32_e32 v203, v106, v106
	v_fmac_f32_e32 v203, v107, v107
	ds_write_b128 v192, v[104:107] offset:192
	s_waitcnt lgkmcnt(7)
	v_add_f32_e32 v108, v188, v108
	v_add_f32_e32 v109, v189, v109
	v_add_f32_e32 v110, v190, v110
	v_add_f32_e32 v111, v191, v111
	v_fmac_f32_e32 v203, v108, v108
	v_fmac_f32_e32 v203, v109, v109
	v_fmac_f32_e32 v203, v110, v110
	v_fmac_f32_e32 v203, v111, v111
	ds_write_b128 v192, v[108:111] offset:224
	ds_read_b128 v[160:163], v198
	ds_read_b128 v[164:167], v198 offset:1088
	ds_read_b128 v[168:171], v198 offset:2176
	ds_read_b128 v[172:175], v198 offset:3264
	ds_read_b128 v[176:179], v198 offset:4352
	ds_read_b128 v[180:183], v198 offset:5440
	ds_read_b128 v[184:187], v198 offset:6528
	ds_read_b128 v[188:191], v198 offset:7616
	s_add_u32 s74, s66, 0x0
	s_addc_u32 s75, s67, 0
	s_waitcnt lgkmcnt(7)
	global_store_dwordx4 v200, v[160:163], s[74:75]
	s_add_u32 s74, s66, 0x4000
	s_addc_u32 s75, s67, 0
	s_waitcnt lgkmcnt(6)
	global_store_dwordx4 v200, v[164:167], s[74:75]
	s_add_u32 s74, s66, 0x8000
	s_addc_u32 s75, s67, 0
	s_waitcnt lgkmcnt(5)
	global_store_dwordx4 v200, v[168:171], s[74:75]
	s_add_u32 s74, s66, 0xc000
	s_addc_u32 s75, s67, 0
	s_waitcnt lgkmcnt(4)
	global_store_dwordx4 v200, v[172:175], s[74:75]
	s_add_u32 s74, s66, 0x10000
	s_addc_u32 s75, s67, 0
	s_waitcnt lgkmcnt(3)
	global_store_dwordx4 v200, v[176:179], s[74:75]
	s_add_u32 s74, s66, 0x14000
	s_addc_u32 s75, s67, 0
	s_waitcnt lgkmcnt(2)
	global_store_dwordx4 v200, v[180:183], s[74:75]
	s_add_u32 s74, s66, 0x18000
	s_addc_u32 s75, s67, 0
	s_waitcnt lgkmcnt(1)
	global_store_dwordx4 v200, v[184:187], s[74:75]
	s_add_u32 s74, s66, 0x1c000
	s_addc_u32 s75, s67, 0
	s_waitcnt lgkmcnt(0)
; DI bfr f2bf(float a) { return (bfr)(pack2(a, 0.f) & 0xffffu); }
; DI int crow(int reg, int h) { return (reg & 3) + 8 * (reg >> 2) + 4 * h; }
; template <bool FIRST, bool HAS_H>
; DI void phase_gemm_resid(const Params& p, const bfr* A, const bfr* Wt, const float* gnext, float* ss, char* smem) {
;     ...
;         for (int jh = 0; jh < 2; ++jh) {
;           float xo[2][8];
; #pragma unroll
;           for (int jj = 0; jj < 2; ++jj)
; #pragma unroll
;             for (int q = 0; q < 8; ++q)
;               xo[jj][q] = xsrc[(rbase + i * 32 + crow(qh * 8 + q, 0)) * 1024 + cbase + (jh * 2 + jj) * 32];
; #pragma unroll
;           for (int q = 0; q < 8; ++q) {
;             const int o = (rbase + i * 32 + crow(qh * 8 + q, 0)) * 1024 + cbase;
; #pragma unroll
;             for (int jj = 0; jj < 2; ++jj) {
;               const int j = jh * 2 + jj;
;               const float xn = xo[jj][q] + acc[i][j][qh * 8 + q];
;               X[o + j * 32] = xn;
;               if (HAS_H) Hn[o + j * 32] = f2bf(xn * gnext[cbase + j * 32]);
;               rs[q] += xn * xn;
;             }
;           }
	global_store_dwordx4 v200, v[188:191], s[74:75]
	global_load_dwordx4 v[160:163], v202, s[70:71]
	global_load_dwordx4 v[164:167], v202, s[70:71] offset:32
	global_load_dwordx4 v[168:171], v202, s[70:71] offset:64
	global_load_dwordx4 v[172:175], v202, s[70:71] offset:96
	global_load_dwordx4 v[176:179], v202, s[70:71] offset:128
	global_load_dwordx4 v[180:183], v202, s[70:71] offset:160
	global_load_dwordx4 v[184:187], v202, s[70:71] offset:192
	global_load_dwordx4 v[188:191], v202, s[70:71] offset:224
	s_waitcnt vmcnt(7)
	v_mul_f32_e32 v112, v160, v112
	v_mul_f32_e32 v113, v161, v113
	v_mul_f32_e32 v114, v162, v114
	v_mul_f32_e32 v115, v163, v115
	v_cvt_pk_bf16_f32 v112, v112, v113
	v_cvt_pk_bf16_f32 v113, v114, v115
	ds_write_b64 v194, v[112:113]
	s_waitcnt vmcnt(6)
	v_mul_f32_e32 v116, v164, v116
	v_mul_f32_e32 v117, v165, v117
	v_mul_f32_e32 v118, v166, v118
	v_mul_f32_e32 v119, v167, v119
	v_cvt_pk_bf16_f32 v116, v116, v117
	v_cvt_pk_bf16_f32 v117, v118, v119
	ds_write_b64 v194, v[116:117] offset:16
	s_waitcnt vmcnt(5)
	v_mul_f32_e32 v120, v168, v120
	v_mul_f32_e32 v121, v169, v121
	v_mul_f32_e32 v122, v170, v122
	v_mul_f32_e32 v123, v171, v123
	v_cvt_pk_bf16_f32 v120, v120, v121
	v_cvt_pk_bf16_f32 v121, v122, v123
	ds_write_b64 v194, v[120:121] offset:32
	s_waitcnt vmcnt(4)
	v_mul_f32_e32 v124, v172, v124
	v_mul_f32_e32 v125, v173, v125
	v_mul_f32_e32 v126, v174, v126
	v_mul_f32_e32 v127, v175, v127
	v_cvt_pk_bf16_f32 v124, v124, v125
	v_cvt_pk_bf16_f32 v125, v126, v127
	ds_write_b64 v194, v[124:125] offset:48
	s_waitcnt vmcnt(3)
	v_mul_f32_e32 v96, v176, v96
	v_mul_f32_e32 v97, v177, v97
	v_mul_f32_e32 v98, v178, v98
	v_mul_f32_e32 v99, v179, v99
	v_cvt_pk_bf16_f32 v96, v96, v97
	v_cvt_pk_bf16_f32 v97, v98, v99
	ds_write_b64 v194, v[96:97] offset:64
	s_waitcnt vmcnt(2)
	v_mul_f32_e32 v100, v180, v100
	v_mul_f32_e32 v101, v181, v101
	v_mul_f32_e32 v102, v182, v102
	v_mul_f32_e32 v103, v183, v103
	v_cvt_pk_bf16_f32 v100, v100, v101
	v_cvt_pk_bf16_f32 v101, v102, v103
	ds_write_b64 v194, v[100:101] offset:80
	s_waitcnt vmcnt(1)
	v_mul_f32_e32 v104, v184, v104
	v_mul_f32_e32 v105, v185, v105
	v_mul_f32_e32 v106, v186, v106
	v_mul_f32_e32 v107, v187, v107
	v_cvt_pk_bf16_f32 v104, v104, v105
	v_cvt_pk_bf16_f32 v105, v106, v107
	ds_write_b64 v194, v[104:105] offset:96
	s_waitcnt vmcnt(0)
	v_mul_f32_e32 v108, v188, v108
	v_mul_f32_e32 v109, v189, v109
	v_mul_f32_e32 v110, v190, v110
	v_mul_f32_e32 v111, v191, v111
	v_cvt_pk_bf16_f32 v108, v108, v109
	v_cvt_pk_bf16_f32 v109, v110, v111
	ds_write_b64 v194, v[108:109] offset:112
	ds_read_b128 v[160:163], v199
	ds_read_b128 v[164:167], v199 offset:2176
	ds_read_b128 v[168:171], v199 offset:4352
	ds_read_b128 v[172:175], v199 offset:6528
	s_add_u32 s74, s68, 0x0
	s_addc_u32 s75, s69, 0
	s_waitcnt lgkmcnt(3)
	global_store_dwordx4 v201, v[160:163], s[74:75]
	s_add_u32 s74, s68, 0x4000
	s_addc_u32 s75, s69, 0
	s_waitcnt lgkmcnt(2)
	global_store_dwordx4 v201, v[164:167], s[74:75]
	s_add_u32 s74, s68, 0x8000
	s_addc_u32 s75, s69, 0
	s_waitcnt lgkmcnt(1)
	global_store_dwordx4 v201, v[168:171], s[74:75]
	s_add_u32 s74, s68, 0xc000
	s_addc_u32 s75, s69, 0
	s_waitcnt lgkmcnt(0)
	global_store_dwordx4 v201, v[172:175], s[74:75]
	s_waitcnt vmcnt(4)
	ds_write_b128 v198, v[128:131]
	s_waitcnt vmcnt(4)
	ds_write_b128 v198, v[132:135] offset:1088
	s_waitcnt vmcnt(4)
	ds_write_b128 v198, v[136:139] offset:2176
	s_waitcnt vmcnt(4)
	ds_write_b128 v198, v[140:143] offset:3264
	s_waitcnt vmcnt(4)
	ds_write_b128 v198, v[144:147] offset:4352
	s_waitcnt vmcnt(4)
	ds_write_b128 v198, v[148:151] offset:5440
	s_waitcnt vmcnt(4)
	ds_write_b128 v198, v[152:155] offset:6528
	s_waitcnt vmcnt(4)
	ds_write_b128 v198, v[156:159] offset:7616
	s_add_u32 s74, s64, 0x20000
	s_addc_u32 s75, s65, 0
	global_load_dwordx4 v[128:131], v200, s[74:75]
	s_add_u32 s74, s64, 0x24000
	s_addc_u32 s75, s65, 0
	global_load_dwordx4 v[132:135], v200, s[74:75]
	s_add_u32 s74, s64, 0x28000
	s_addc_u32 s75, s65, 0
	global_load_dwordx4 v[136:139], v200, s[74:75]
	s_add_u32 s74, s64, 0x2c000
	s_addc_u32 s75, s65, 0
	global_load_dwordx4 v[140:143], v200, s[74:75]
	s_add_u32 s74, s64, 0x30000
	s_addc_u32 s75, s65, 0
	global_load_dwordx4 v[144:147], v200, s[74:75]
	s_add_u32 s74, s64, 0x34000
	s_addc_u32 s75, s65, 0
	global_load_dwordx4 v[148:151], v200, s[74:75]
	s_add_u32 s74, s64, 0x38000
	s_addc_u32 s75, s65, 0
	global_load_dwordx4 v[152:155], v200, s[74:75]
	s_add_u32 s74, s64, 0x3c000
	s_addc_u32 s75, s65, 0
	global_load_dwordx4 v[156:159], v200, s[74:75]
	ds_read_b128 v[160:163], v192
	ds_read_b128 v[164:167], v192 offset:32
	ds_read_b128 v[168:171], v192 offset:64
	ds_read_b128 v[172:175], v192 offset:96
	ds_read_b128 v[176:179], v192 offset:128
	ds_read_b128 v[180:183], v192 offset:160
	ds_read_b128 v[184:187], v192 offset:192
	ds_read_b128 v[188:191], v192 offset:224
	s_waitcnt lgkmcnt(7)
	v_add_f32_e32 v80, v160, v80
	v_add_f32_e32 v81, v161, v81
	v_add_f32_e32 v82, v162, v82
	v_add_f32_e32 v83, v163, v83
	v_fmac_f32_e32 v203, v80, v80
	v_fmac_f32_e32 v203, v81, v81
	v_fmac_f32_e32 v203, v82, v82
	v_fmac_f32_e32 v203, v83, v83
	ds_write_b128 v192, v[80:83]
	s_waitcnt lgkmcnt(7)
	v_add_f32_e32 v84, v164, v84
	v_add_f32_e32 v85, v165, v85
	v_add_f32_e32 v86, v166, v86
	v_add_f32_e32 v87, v167, v87
	v_fmac_f32_e32 v203, v84, v84
	v_fmac_f32_e32 v203, v85, v85
	v_fmac_f32_e32 v203, v86, v86
	v_fmac_f32_e32 v203, v87, v87
	ds_write_b128 v192, v[84:87] offset:32
	s_waitcnt lgkmcnt(7)
	v_add_f32_e32 v88, v168, v88
	v_add_f32_e32 v89, v169, v89
	v_add_f32_e32 v90, v170, v90
	v_add_f32_e32 v91, v171, v91
	v_fmac_f32_e32 v203, v88, v88
	v_fmac_f32_e32 v203, v89, v89
	v_fmac_f32_e32 v203, v90, v90
	v_fmac_f32_e32 v203, v91, v91
	ds_write_b128 v192, v[88:91] offset:64
	s_waitcnt lgkmcnt(7)
; DI bfr f2bf(float a) { return (bfr)(pack2(a, 0.f) & 0xffffu); }
; DI int crow(int reg, int h) { return (reg & 3) + 8 * (reg >> 2) + 4 * h; }
; template <bool FIRST, bool HAS_H>
; DI void phase_gemm_resid(const Params& p, const bfr* A, const bfr* Wt, const float* gnext, float* ss, char* smem) {
;     ...
;         for (int jh = 0; jh < 2; ++jh) {
;           float xo[2][8];
; #pragma unroll
;           for (int jj = 0; jj < 2; ++jj)
; #pragma unroll
;             for (int q = 0; q < 8; ++q)
;               xo[jj][q] = xsrc[(rbase + i * 32 + crow(qh * 8 + q, 0)) * 1024 + cbase + (jh * 2 + jj) * 32];
; #pragma unroll
;           for (int q = 0; q < 8; ++q) {
;             const int o = (rbase + i * 32 + crow(qh * 8 + q, 0)) * 1024 + cbase;
; #pragma unroll
;             for (int jj = 0; jj < 2; ++jj) {
;               const int j = jh * 2 + jj;
;               const float xn = xo[jj][q] + acc[i][j][qh * 8 + q];
;               X[o + j * 32] = xn;
;               if (HAS_H) Hn[o + j * 32] = f2bf(xn * gnext[cbase + j * 32]);
;               rs[q] += xn * xn;
;             }
;           }
	v_add_f32_e32 v92, v172, v92
	v_add_f32_e32 v93, v173, v93
	v_add_f32_e32 v94, v174, v94
	v_add_f32_e32 v95, v175, v95
	v_fmac_f32_e32 v203, v92, v92
	v_fmac_f32_e32 v203, v93, v93
	v_fmac_f32_e32 v203, v94, v94
	v_fmac_f32_e32 v203, v95, v95
	ds_write_b128 v192, v[92:95] offset:96
	s_waitcnt lgkmcnt(7)
	v_add_f32_e32 v64, v176, v64
	v_add_f32_e32 v65, v177, v65
	v_add_f32_e32 v66, v178, v66
	v_add_f32_e32 v67, v179, v67
	v_fmac_f32_e32 v203, v64, v64
	v_fmac_f32_e32 v203, v65, v65
	v_fmac_f32_e32 v203, v66, v66
	v_fmac_f32_e32 v203, v67, v67
	ds_write_b128 v192, v[64:67] offset:128
	s_waitcnt lgkmcnt(7)
	v_add_f32_e32 v68, v180, v68
	v_add_f32_e32 v69, v181, v69
	v_add_f32_e32 v70, v182, v70
	v_add_f32_e32 v71, v183, v71
	v_fmac_f32_e32 v203, v68, v68
	v_fmac_f32_e32 v203, v69, v69
	v_fmac_f32_e32 v203, v70, v70
	v_fmac_f32_e32 v203, v71, v71
	ds_write_b128 v192, v[68:71] offset:160
	s_waitcnt lgkmcnt(7)
	v_add_f32_e32 v72, v184, v72
	v_add_f32_e32 v73, v185, v73
	v_add_f32_e32 v74, v186, v74
	v_add_f32_e32 v75, v187, v75
	v_fmac_f32_e32 v203, v72, v72
	v_fmac_f32_e32 v203, v73, v73
	v_fmac_f32_e32 v203, v74, v74
	v_fmac_f32_e32 v203, v75, v75
	ds_write_b128 v192, v[72:75] offset:192
	s_waitcnt lgkmcnt(7)
	v_add_f32_e32 v76, v188, v76
	v_add_f32_e32 v77, v189, v77
	v_add_f32_e32 v78, v190, v78
	v_add_f32_e32 v79, v191, v79
	v_fmac_f32_e32 v203, v76, v76
	v_fmac_f32_e32 v203, v77, v77
	v_fmac_f32_e32 v203, v78, v78
	v_fmac_f32_e32 v203, v79, v79
	ds_write_b128 v192, v[76:79] offset:224
	ds_read_b128 v[160:163], v198
	ds_read_b128 v[164:167], v198 offset:1088
	ds_read_b128 v[168:171], v198 offset:2176
	ds_read_b128 v[172:175], v198 offset:3264
	ds_read_b128 v[176:179], v198 offset:4352
	ds_read_b128 v[180:183], v198 offset:5440
	ds_read_b128 v[184:187], v198 offset:6528
	ds_read_b128 v[188:191], v198 offset:7616
	s_add_u32 s74, s66, 0x100
	s_addc_u32 s75, s67, 0
	s_waitcnt lgkmcnt(7)
	global_store_dwordx4 v200, v[160:163], s[74:75]
	s_add_u32 s74, s66, 0x4100
	s_addc_u32 s75, s67, 0
	s_waitcnt lgkmcnt(6)
	global_store_dwordx4 v200, v[164:167], s[74:75]
	s_add_u32 s74, s66, 0x8100
	s_addc_u32 s75, s67, 0
	s_waitcnt lgkmcnt(5)
	global_store_dwordx4 v200, v[168:171], s[74:75]
	s_add_u32 s74, s66, 0xc100
	s_addc_u32 s75, s67, 0
	s_waitcnt lgkmcnt(4)
	global_store_dwordx4 v200, v[172:175], s[74:75]
	s_add_u32 s74, s66, 0x10100
	s_addc_u32 s75, s67, 0
	s_waitcnt lgkmcnt(3)
	global_store_dwordx4 v200, v[176:179], s[74:75]
	s_add_u32 s74, s66, 0x14100
	s_addc_u32 s75, s67, 0
	s_waitcnt lgkmcnt(2)
	global_store_dwordx4 v200, v[180:183], s[74:75]
	s_add_u32 s74, s66, 0x18100
	s_addc_u32 s75, s67, 0
	s_waitcnt lgkmcnt(1)
	global_store_dwordx4 v200, v[184:187], s[74:75]
	s_add_u32 s74, s66, 0x1c100
	s_addc_u32 s75, s67, 0
	s_waitcnt lgkmcnt(0)
	global_store_dwordx4 v200, v[188:191], s[74:75]
	global_load_dwordx4 v[160:163], v202, s[70:71] offset:256
	global_load_dwordx4 v[164:167], v202, s[70:71] offset:288
	global_load_dwordx4 v[168:171], v202, s[70:71] offset:320
	global_load_dwordx4 v[172:175], v202, s[70:71] offset:352
	global_load_dwordx4 v[176:179], v202, s[70:71] offset:384
	global_load_dwordx4 v[180:183], v202, s[70:71] offset:416
	global_load_dwordx4 v[184:187], v202, s[70:71] offset:448
	global_load_dwordx4 v[188:191], v202, s[70:71] offset:480
	s_waitcnt vmcnt(7)
	v_mul_f32_e32 v80, v160, v80
	v_mul_f32_e32 v81, v161, v81
	v_mul_f32_e32 v82, v162, v82
	v_mul_f32_e32 v83, v163, v83
	v_cvt_pk_bf16_f32 v80, v80, v81
	v_cvt_pk_bf16_f32 v81, v82, v83
	ds_write_b64 v194, v[80:81]
	s_waitcnt vmcnt(6)
	v_mul_f32_e32 v84, v164, v84
	v_mul_f32_e32 v85, v165, v85
	v_mul_f32_e32 v86, v166, v86
	v_mul_f32_e32 v87, v167, v87
	v_cvt_pk_bf16_f32 v84, v84, v85
	v_cvt_pk_bf16_f32 v85, v86, v87
	ds_write_b64 v194, v[84:85] offset:16
	s_waitcnt vmcnt(5)
	v_mul_f32_e32 v88, v168, v88
	v_mul_f32_e32 v89, v169, v89
	v_mul_f32_e32 v90, v170, v90
	v_mul_f32_e32 v91, v171, v91
	v_cvt_pk_bf16_f32 v88, v88, v89
	v_cvt_pk_bf16_f32 v89, v90, v91
	ds_write_b64 v194, v[88:89] offset:32
	s_waitcnt vmcnt(4)
	v_mul_f32_e32 v92, v172, v92
	v_mul_f32_e32 v93, v173, v93
	v_mul_f32_e32 v94, v174, v94
	v_mul_f32_e32 v95, v175, v95
	v_cvt_pk_bf16_f32 v92, v92, v93
	v_cvt_pk_bf16_f32 v93, v94, v95
	ds_write_b64 v194, v[92:93] offset:48
	s_waitcnt vmcnt(3)
	v_mul_f32_e32 v64, v176, v64
	v_mul_f32_e32 v65, v177, v65
	v_mul_f32_e32 v66, v178, v66
	v_mul_f32_e32 v67, v179, v67
	v_cvt_pk_bf16_f32 v64, v64, v65
	v_cvt_pk_bf16_f32 v65, v66, v67
	ds_write_b64 v194, v[64:65] offset:64
	s_waitcnt vmcnt(2)
	v_mul_f32_e32 v68, v180, v68
	v_mul_f32_e32 v69, v181, v69
	v_mul_f32_e32 v70, v182, v70
	v_mul_f32_e32 v71, v183, v71
	v_cvt_pk_bf16_f32 v68, v68, v69
	v_cvt_pk_bf16_f32 v69, v70, v71
	ds_write_b64 v194, v[68:69] offset:80
	s_waitcnt vmcnt(1)
	v_mul_f32_e32 v72, v184, v72
	v_mul_f32_e32 v73, v185, v73
	v_mul_f32_e32 v74, v186, v74
	v_mul_f32_e32 v75, v187, v75
	v_cvt_pk_bf16_f32 v72, v72, v73
	v_cvt_pk_bf16_f32 v73, v74, v75
	ds_write_b64 v194, v[72:73] offset:96
	s_waitcnt vmcnt(0)
	v_mul_f32_e32 v76, v188, v76
	v_mul_f32_e32 v77, v189, v77
	v_mul_f32_e32 v78, v190, v78
	v_mul_f32_e32 v79, v191, v79
	v_cvt_pk_bf16_f32 v76, v76, v77
	v_cvt_pk_bf16_f32 v77, v78, v79
	ds_write_b64 v194, v[76:77] offset:112
	ds_read_b128 v[160:163], v199
	ds_read_b128 v[164:167], v199 offset:2176
	ds_read_b128 v[168:171], v199 offset:4352
	ds_read_b128 v[172:175], v199 offset:6528
	s_add_u32 s74, s68, 0x80
	s_addc_u32 s75, s69, 0
	s_waitcnt lgkmcnt(3)
	global_store_dwordx4 v201, v[160:163], s[74:75]
	s_add_u32 s74, s68, 0x4080
	s_addc_u32 s75, s69, 0
	s_waitcnt lgkmcnt(2)
; DI bfr f2bf(float a) { return (bfr)(pack2(a, 0.f) & 0xffffu); }
; DI int crow(int reg, int h) { return (reg & 3) + 8 * (reg >> 2) + 4 * h; }
; template <bool FIRST, bool HAS_H>
; DI void phase_gemm_resid(const Params& p, const bfr* A, const bfr* Wt, const float* gnext, float* ss, char* smem) {
;     ...
;         for (int jh = 0; jh < 2; ++jh) {
;           float xo[2][8];
; #pragma unroll
;           for (int jj = 0; jj < 2; ++jj)
; #pragma unroll
;             for (int q = 0; q < 8; ++q)
;               xo[jj][q] = xsrc[(rbase + i * 32 + crow(qh * 8 + q, 0)) * 1024 + cbase + (jh * 2 + jj) * 32];
; #pragma unroll
;           for (int q = 0; q < 8; ++q) {
;             const int o = (rbase + i * 32 + crow(qh * 8 + q, 0)) * 1024 + cbase;
; #pragma unroll
;             for (int jj = 0; jj < 2; ++jj) {
;               const int j = jh * 2 + jj;
;               const float xn = xo[jj][q] + acc[i][j][qh * 8 + q];
;               X[o + j * 32] = xn;
;               if (HAS_H) Hn[o + j * 32] = f2bf(xn * gnext[cbase + j * 32]);
;               rs[q] += xn * xn;
;             }
;           }
	global_store_dwordx4 v201, v[164:167], s[74:75]
	s_add_u32 s74, s68, 0x8080
	s_addc_u32 s75, s69, 0
	s_waitcnt lgkmcnt(1)
	global_store_dwordx4 v201, v[168:171], s[74:75]
	s_add_u32 s74, s68, 0xc080
	s_addc_u32 s75, s69, 0
	s_waitcnt lgkmcnt(0)
	global_store_dwordx4 v201, v[172:175], s[74:75]
	s_waitcnt vmcnt(4)
	ds_write_b128 v198, v[128:131]
	s_waitcnt vmcnt(4)
	ds_write_b128 v198, v[132:135] offset:1088
	s_waitcnt vmcnt(4)
	ds_write_b128 v198, v[136:139] offset:2176
	s_waitcnt vmcnt(4)
	ds_write_b128 v198, v[140:143] offset:3264
	s_waitcnt vmcnt(4)
	ds_write_b128 v198, v[144:147] offset:4352
	s_waitcnt vmcnt(4)
	ds_write_b128 v198, v[148:151] offset:5440
	s_waitcnt vmcnt(4)
	ds_write_b128 v198, v[152:155] offset:6528
	s_waitcnt vmcnt(4)
	ds_write_b128 v198, v[156:159] offset:7616
	s_add_u32 s74, s64, 0x20100
	s_addc_u32 s75, s65, 0
	global_load_dwordx4 v[128:131], v200, s[74:75]
	s_add_u32 s74, s64, 0x24100
	s_addc_u32 s75, s65, 0
	global_load_dwordx4 v[132:135], v200, s[74:75]
	s_add_u32 s74, s64, 0x28100
	s_addc_u32 s75, s65, 0
	global_load_dwordx4 v[136:139], v200, s[74:75]
	s_add_u32 s74, s64, 0x2c100
	s_addc_u32 s75, s65, 0
	global_load_dwordx4 v[140:143], v200, s[74:75]
	s_add_u32 s74, s64, 0x30100
	s_addc_u32 s75, s65, 0
	global_load_dwordx4 v[144:147], v200, s[74:75]
	s_add_u32 s74, s64, 0x34100
	s_addc_u32 s75, s65, 0
	global_load_dwordx4 v[148:151], v200, s[74:75]
	s_add_u32 s74, s64, 0x38100
	s_addc_u32 s75, s65, 0
	global_load_dwordx4 v[152:155], v200, s[74:75]
	s_add_u32 s74, s64, 0x3c100
	s_addc_u32 s75, s65, 0
	global_load_dwordx4 v[156:159], v200, s[74:75]
	ds_read_b128 v[160:163], v192
	ds_read_b128 v[164:167], v192 offset:32
	ds_read_b128 v[168:171], v192 offset:64
	ds_read_b128 v[172:175], v192 offset:96
	ds_read_b128 v[176:179], v192 offset:128
	ds_read_b128 v[180:183], v192 offset:160
	ds_read_b128 v[184:187], v192 offset:192
	ds_read_b128 v[188:191], v192 offset:224
	s_waitcnt lgkmcnt(7)
	v_add_f32_e32 v48, v160, v48
	v_add_f32_e32 v49, v161, v49
	v_add_f32_e32 v50, v162, v50
	v_add_f32_e32 v51, v163, v51
	v_fmac_f32_e32 v204, v48, v48
	v_fmac_f32_e32 v204, v49, v49
	v_fmac_f32_e32 v204, v50, v50
	v_fmac_f32_e32 v204, v51, v51
	ds_write_b128 v192, v[48:51]
	s_waitcnt lgkmcnt(7)
	v_add_f32_e32 v52, v164, v52
	v_add_f32_e32 v53, v165, v53
	v_add_f32_e32 v54, v166, v54
	v_add_f32_e32 v55, v167, v55
	v_fmac_f32_e32 v204, v52, v52
	v_fmac_f32_e32 v204, v53, v53
	v_fmac_f32_e32 v204, v54, v54
	v_fmac_f32_e32 v204, v55, v55
	ds_write_b128 v192, v[52:55] offset:32
	s_waitcnt lgkmcnt(7)
	v_add_f32_e32 v56, v168, v56
	v_add_f32_e32 v57, v169, v57
	v_add_f32_e32 v58, v170, v58
	v_add_f32_e32 v59, v171, v59
	v_fmac_f32_e32 v204, v56, v56
	v_fmac_f32_e32 v204, v57, v57
	v_fmac_f32_e32 v204, v58, v58
	v_fmac_f32_e32 v204, v59, v59
	ds_write_b128 v192, v[56:59] offset:64
	s_waitcnt lgkmcnt(7)
	v_add_f32_e32 v60, v172, v60
	v_add_f32_e32 v61, v173, v61
	v_add_f32_e32 v62, v174, v62
	v_add_f32_e32 v63, v175, v63
	v_fmac_f32_e32 v204, v60, v60
	v_fmac_f32_e32 v204, v61, v61
	v_fmac_f32_e32 v204, v62, v62
	v_fmac_f32_e32 v204, v63, v63
	ds_write_b128 v192, v[60:63] offset:96
	s_waitcnt lgkmcnt(7)
	v_add_f32_e32 v32, v176, v32
	v_add_f32_e32 v33, v177, v33
	v_add_f32_e32 v34, v178, v34
	v_add_f32_e32 v35, v179, v35
	v_fmac_f32_e32 v204, v32, v32
	v_fmac_f32_e32 v204, v33, v33
	v_fmac_f32_e32 v204, v34, v34
	v_fmac_f32_e32 v204, v35, v35
	ds_write_b128 v192, v[32:35] offset:128
	s_waitcnt lgkmcnt(7)
	v_add_f32_e32 v36, v180, v36
	v_add_f32_e32 v37, v181, v37
	v_add_f32_e32 v38, v182, v38
	v_add_f32_e32 v39, v183, v39
	v_fmac_f32_e32 v204, v36, v36
	v_fmac_f32_e32 v204, v37, v37
	v_fmac_f32_e32 v204, v38, v38
	v_fmac_f32_e32 v204, v39, v39
	ds_write_b128 v192, v[36:39] offset:160
	s_waitcnt lgkmcnt(7)
	v_add_f32_e32 v40, v184, v40
	v_add_f32_e32 v41, v185, v41
	v_add_f32_e32 v42, v186, v42
	v_add_f32_e32 v43, v187, v43
	v_fmac_f32_e32 v204, v40, v40
	v_fmac_f32_e32 v204, v41, v41
	v_fmac_f32_e32 v204, v42, v42
	v_fmac_f32_e32 v204, v43, v43
	ds_write_b128 v192, v[40:43] offset:192
	s_waitcnt lgkmcnt(7)
	v_add_f32_e32 v44, v188, v44
	v_add_f32_e32 v45, v189, v45
	v_add_f32_e32 v46, v190, v46
	v_add_f32_e32 v47, v191, v47
	v_fmac_f32_e32 v204, v44, v44
	v_fmac_f32_e32 v204, v45, v45
	v_fmac_f32_e32 v204, v46, v46
	v_fmac_f32_e32 v204, v47, v47
	ds_write_b128 v192, v[44:47] offset:224
	ds_read_b128 v[160:163], v198
	ds_read_b128 v[164:167], v198 offset:1088
	ds_read_b128 v[168:171], v198 offset:2176
	ds_read_b128 v[172:175], v198 offset:3264
	ds_read_b128 v[176:179], v198 offset:4352
	ds_read_b128 v[180:183], v198 offset:5440
	ds_read_b128 v[184:187], v198 offset:6528
	ds_read_b128 v[188:191], v198 offset:7616
	s_add_u32 s74, s66, 0x20000
	s_addc_u32 s75, s67, 0
	s_waitcnt lgkmcnt(7)
	global_store_dwordx4 v200, v[160:163], s[74:75]
	s_add_u32 s74, s66, 0x24000
	s_addc_u32 s75, s67, 0
	s_waitcnt lgkmcnt(6)
	global_store_dwordx4 v200, v[164:167], s[74:75]
	s_add_u32 s74, s66, 0x28000
	s_addc_u32 s75, s67, 0
	s_waitcnt lgkmcnt(5)
	global_store_dwordx4 v200, v[168:171], s[74:75]
	s_add_u32 s74, s66, 0x2c000
	s_addc_u32 s75, s67, 0
	s_waitcnt lgkmcnt(4)
	global_store_dwordx4 v200, v[172:175], s[74:75]
	s_add_u32 s74, s66, 0x30000
	s_addc_u32 s75, s67, 0
	s_waitcnt lgkmcnt(3)
	global_store_dwordx4 v200, v[176:179], s[74:75]
	s_add_u32 s74, s66, 0x34000
	s_addc_u32 s75, s67, 0
	s_waitcnt lgkmcnt(2)
	global_store_dwordx4 v200, v[180:183], s[74:75]
	s_add_u32 s74, s66, 0x38000
	s_addc_u32 s75, s67, 0
	s_waitcnt lgkmcnt(1)
	global_store_dwordx4 v200, v[184:187], s[74:75]
	s_add_u32 s74, s66, 0x3c000
	s_addc_u32 s75, s67, 0
	s_waitcnt lgkmcnt(0)
; DI bfr f2bf(float a) { return (bfr)(pack2(a, 0.f) & 0xffffu); }
; DI int crow(int reg, int h) { return (reg & 3) + 8 * (reg >> 2) + 4 * h; }
; template <bool FIRST, bool HAS_H>
; DI void phase_gemm_resid(const Params& p, const bfr* A, const bfr* Wt, const float* gnext, float* ss, char* smem) {
;     ...
;         for (int jh = 0; jh < 2; ++jh) {
;           float xo[2][8];
; #pragma unroll
;           for (int jj = 0; jj < 2; ++jj)
; #pragma unroll
;             for (int q = 0; q < 8; ++q)
;               xo[jj][q] = xsrc[(rbase + i * 32 + crow(qh * 8 + q, 0)) * 1024 + cbase + (jh * 2 + jj) * 32];
; #pragma unroll
;           for (int q = 0; q < 8; ++q) {
;             const int o = (rbase + i * 32 + crow(qh * 8 + q, 0)) * 1024 + cbase;
; #pragma unroll
;             for (int jj = 0; jj < 2; ++jj) {
;               const int j = jh * 2 + jj;
;               const float xn = xo[jj][q] + acc[i][j][qh * 8 + q];
;               X[o + j * 32] = xn;
;               if (HAS_H) Hn[o + j * 32] = f2bf(xn * gnext[cbase + j * 32]);
;               rs[q] += xn * xn;
;             }
;           }
	global_store_dwordx4 v200, v[188:191], s[74:75]
	global_load_dwordx4 v[160:163], v202, s[70:71]
	global_load_dwordx4 v[164:167], v202, s[70:71] offset:32
	global_load_dwordx4 v[168:171], v202, s[70:71] offset:64
	global_load_dwordx4 v[172:175], v202, s[70:71] offset:96
	global_load_dwordx4 v[176:179], v202, s[70:71] offset:128
	global_load_dwordx4 v[180:183], v202, s[70:71] offset:160
	global_load_dwordx4 v[184:187], v202, s[70:71] offset:192
	global_load_dwordx4 v[188:191], v202, s[70:71] offset:224
	s_waitcnt vmcnt(7)
	v_mul_f32_e32 v48, v160, v48
	v_mul_f32_e32 v49, v161, v49
	v_mul_f32_e32 v50, v162, v50
	v_mul_f32_e32 v51, v163, v51
	v_cvt_pk_bf16_f32 v48, v48, v49
	v_cvt_pk_bf16_f32 v49, v50, v51
	ds_write_b64 v194, v[48:49]
	s_waitcnt vmcnt(6)
	v_mul_f32_e32 v52, v164, v52
	v_mul_f32_e32 v53, v165, v53
	v_mul_f32_e32 v54, v166, v54
	v_mul_f32_e32 v55, v167, v55
	v_cvt_pk_bf16_f32 v52, v52, v53
	v_cvt_pk_bf16_f32 v53, v54, v55
	ds_write_b64 v194, v[52:53] offset:16
	s_waitcnt vmcnt(5)
	v_mul_f32_e32 v56, v168, v56
	v_mul_f32_e32 v57, v169, v57
	v_mul_f32_e32 v58, v170, v58
	v_mul_f32_e32 v59, v171, v59
	v_cvt_pk_bf16_f32 v56, v56, v57
	v_cvt_pk_bf16_f32 v57, v58, v59
	ds_write_b64 v194, v[56:57] offset:32
	s_waitcnt vmcnt(4)
	v_mul_f32_e32 v60, v172, v60
	v_mul_f32_e32 v61, v173, v61
	v_mul_f32_e32 v62, v174, v62
	v_mul_f32_e32 v63, v175, v63
	v_cvt_pk_bf16_f32 v60, v60, v61
	v_cvt_pk_bf16_f32 v61, v62, v63
	ds_write_b64 v194, v[60:61] offset:48
	s_waitcnt vmcnt(3)
	v_mul_f32_e32 v32, v176, v32
	v_mul_f32_e32 v33, v177, v33
	v_mul_f32_e32 v34, v178, v34
	v_mul_f32_e32 v35, v179, v35
	v_cvt_pk_bf16_f32 v32, v32, v33
	v_cvt_pk_bf16_f32 v33, v34, v35
	ds_write_b64 v194, v[32:33] offset:64
	s_waitcnt vmcnt(2)
	v_mul_f32_e32 v36, v180, v36
	v_mul_f32_e32 v37, v181, v37
	v_mul_f32_e32 v38, v182, v38
	v_mul_f32_e32 v39, v183, v39
	v_cvt_pk_bf16_f32 v36, v36, v37
	v_cvt_pk_bf16_f32 v37, v38, v39
	ds_write_b64 v194, v[36:37] offset:80
	s_waitcnt vmcnt(1)
	v_mul_f32_e32 v40, v184, v40
	v_mul_f32_e32 v41, v185, v41
	v_mul_f32_e32 v42, v186, v42
	v_mul_f32_e32 v43, v187, v43
	v_cvt_pk_bf16_f32 v40, v40, v41
	v_cvt_pk_bf16_f32 v41, v42, v43
	ds_write_b64 v194, v[40:41] offset:96
	s_waitcnt vmcnt(0)
	v_mul_f32_e32 v44, v188, v44
	v_mul_f32_e32 v45, v189, v45
	v_mul_f32_e32 v46, v190, v46
	v_mul_f32_e32 v47, v191, v47
	v_cvt_pk_bf16_f32 v44, v44, v45
	v_cvt_pk_bf16_f32 v45, v46, v47
	ds_write_b64 v194, v[44:45] offset:112
	ds_read_b128 v[160:163], v199
	ds_read_b128 v[164:167], v199 offset:2176
	ds_read_b128 v[168:171], v199 offset:4352
	ds_read_b128 v[172:175], v199 offset:6528
	s_add_u32 s74, s68, 0x10000
	s_addc_u32 s75, s69, 0
	s_waitcnt lgkmcnt(3)
	global_store_dwordx4 v201, v[160:163], s[74:75]
	s_add_u32 s74, s68, 0x14000
	s_addc_u32 s75, s69, 0
	s_waitcnt lgkmcnt(2)
	global_store_dwordx4 v201, v[164:167], s[74:75]
	s_add_u32 s74, s68, 0x18000
	s_addc_u32 s75, s69, 0
	s_waitcnt lgkmcnt(1)
	global_store_dwordx4 v201, v[168:171], s[74:75]
	s_add_u32 s74, s68, 0x1c000
	s_addc_u32 s75, s69, 0
	s_waitcnt lgkmcnt(0)
	global_store_dwordx4 v201, v[172:175], s[74:75]
	s_waitcnt vmcnt(4)
	ds_write_b128 v198, v[128:131]
	s_waitcnt vmcnt(4)
	ds_write_b128 v198, v[132:135] offset:1088
	s_waitcnt vmcnt(4)
	ds_write_b128 v198, v[136:139] offset:2176
	s_waitcnt vmcnt(4)
	ds_write_b128 v198, v[140:143] offset:3264
	s_waitcnt vmcnt(4)
	ds_write_b128 v198, v[144:147] offset:4352
	s_waitcnt vmcnt(4)
	ds_write_b128 v198, v[148:151] offset:5440
	s_waitcnt vmcnt(4)
	ds_write_b128 v198, v[152:155] offset:6528
	s_waitcnt vmcnt(4)
	ds_write_b128 v198, v[156:159] offset:7616
	ds_read_b128 v[160:163], v192
	ds_read_b128 v[164:167], v192 offset:32
	ds_read_b128 v[168:171], v192 offset:64
	ds_read_b128 v[172:175], v192 offset:96
	ds_read_b128 v[176:179], v192 offset:128
	ds_read_b128 v[180:183], v192 offset:160
	ds_read_b128 v[184:187], v192 offset:192
	ds_read_b128 v[188:191], v192 offset:224
	s_waitcnt lgkmcnt(7)
	v_add_f32_e32 v16, v160, v16
	v_add_f32_e32 v17, v161, v17
	v_add_f32_e32 v18, v162, v18
	v_add_f32_e32 v19, v163, v19
	v_fmac_f32_e32 v204, v16, v16
	v_fmac_f32_e32 v204, v17, v17
	v_fmac_f32_e32 v204, v18, v18
	v_fmac_f32_e32 v204, v19, v19
	ds_write_b128 v192, v[16:19]
	s_waitcnt lgkmcnt(7)
	v_add_f32_e32 v20, v164, v20
	v_add_f32_e32 v21, v165, v21
	v_add_f32_e32 v22, v166, v22
	v_add_f32_e32 v23, v167, v23
	v_fmac_f32_e32 v204, v20, v20
	v_fmac_f32_e32 v204, v21, v21
	v_fmac_f32_e32 v204, v22, v22
	v_fmac_f32_e32 v204, v23, v23
	ds_write_b128 v192, v[20:23] offset:32
	s_waitcnt lgkmcnt(7)
	v_add_f32_e32 v24, v168, v24
	v_add_f32_e32 v25, v169, v25
	v_add_f32_e32 v26, v170, v26
	v_add_f32_e32 v27, v171, v27
	v_fmac_f32_e32 v204, v24, v24
	v_fmac_f32_e32 v204, v25, v25
	v_fmac_f32_e32 v204, v26, v26
	v_fmac_f32_e32 v204, v27, v27
	ds_write_b128 v192, v[24:27] offset:64
	s_waitcnt lgkmcnt(7)
	v_add_f32_e32 v28, v172, v28
	v_add_f32_e32 v29, v173, v29
	v_add_f32_e32 v30, v174, v30
	v_add_f32_e32 v31, v175, v31
	v_fmac_f32_e32 v204, v28, v28
	v_fmac_f32_e32 v204, v29, v29
	v_fmac_f32_e32 v204, v30, v30
	v_fmac_f32_e32 v204, v31, v31
	ds_write_b128 v192, v[28:31] offset:96
	s_waitcnt lgkmcnt(7)
	v_add_f32_e32 v0, v176, v0
	v_add_f32_e32 v1, v177, v1
	v_add_f32_e32 v2, v178, v2
	v_add_f32_e32 v3, v179, v3
	v_fmac_f32_e32 v204, v0, v0
	v_fmac_f32_e32 v204, v1, v1
	v_fmac_f32_e32 v204, v2, v2
	v_fmac_f32_e32 v204, v3, v3
	ds_write_b128 v192, v[0:3] offset:128
	s_waitcnt lgkmcnt(7)
	v_add_f32_e32 v4, v180, v4
	v_add_f32_e32 v5, v181, v5
	v_add_f32_e32 v6, v182, v6
	v_add_f32_e32 v7, v183, v7
	v_fmac_f32_e32 v204, v4, v4
	v_fmac_f32_e32 v204, v5, v5
	v_fmac_f32_e32 v204, v6, v6
	v_fmac_f32_e32 v204, v7, v7
	ds_write_b128 v192, v[4:7] offset:160
	s_waitcnt lgkmcnt(7)
; DI bfr f2bf(float a) { return (bfr)(pack2(a, 0.f) & 0xffffu); }
; DI int crow(int reg, int h) { return (reg & 3) + 8 * (reg >> 2) + 4 * h; }
; template <bool FIRST, bool HAS_H>
; DI void phase_gemm_resid(const Params& p, const bfr* A, const bfr* Wt, const float* gnext, float* ss, char* smem) {
;     ...
;           for (int q = 0; q < 8; ++q) {
;             const int o = (rbase + i * 32 + crow(qh * 8 + q, 0)) * 1024 + cbase;
; #pragma unroll
;             for (int jj = 0; jj < 2; ++jj) {
;               const int j = jh * 2 + jj;
;               const float xn = xo[jj][q] + acc[i][j][qh * 8 + q];
;               X[o + j * 32] = xn;
;               if (HAS_H) Hn[o + j * 32] = f2bf(xn * gnext[cbase + j * 32]);
;               rs[q] += xn * xn;
;             }
;           }
;         }
; #pragma unroll
;         for (int q = 0; q < 8; ++q) rs[q] = half32_sum_hi(rs[q]);
;         if (r == 31) {
; #pragma unroll
;           for (int q = 0; q < 8; ++q) unsafeAtomicAdd(ss + rbase + i * 32 + crow(qh * 8 + q, 0), rs[q]);
;         }
	v_add_f32_e32 v8, v184, v8
	v_add_f32_e32 v9, v185, v9
	v_add_f32_e32 v10, v186, v10
	v_add_f32_e32 v11, v187, v11
	v_fmac_f32_e32 v204, v8, v8
	v_fmac_f32_e32 v204, v9, v9
	v_fmac_f32_e32 v204, v10, v10
	v_fmac_f32_e32 v204, v11, v11
	ds_write_b128 v192, v[8:11] offset:192
	s_waitcnt lgkmcnt(7)
	v_add_f32_e32 v12, v188, v12
	v_add_f32_e32 v13, v189, v13
	v_add_f32_e32 v14, v190, v14
	v_add_f32_e32 v15, v191, v15
	v_fmac_f32_e32 v204, v12, v12
	v_fmac_f32_e32 v204, v13, v13
	v_fmac_f32_e32 v204, v14, v14
	v_fmac_f32_e32 v204, v15, v15
	ds_write_b128 v192, v[12:15] offset:224
	ds_read_b128 v[160:163], v198
	ds_read_b128 v[164:167], v198 offset:1088
	ds_read_b128 v[168:171], v198 offset:2176
	ds_read_b128 v[172:175], v198 offset:3264
	ds_read_b128 v[176:179], v198 offset:4352
	ds_read_b128 v[180:183], v198 offset:5440
	ds_read_b128 v[184:187], v198 offset:6528
	ds_read_b128 v[188:191], v198 offset:7616
	s_add_u32 s74, s66, 0x20100
	s_addc_u32 s75, s67, 0
	s_waitcnt lgkmcnt(7)
	global_store_dwordx4 v200, v[160:163], s[74:75]
	s_add_u32 s74, s66, 0x24100
	s_addc_u32 s75, s67, 0
	s_waitcnt lgkmcnt(6)
	global_store_dwordx4 v200, v[164:167], s[74:75]
	s_add_u32 s74, s66, 0x28100
	s_addc_u32 s75, s67, 0
	s_waitcnt lgkmcnt(5)
	global_store_dwordx4 v200, v[168:171], s[74:75]
	s_add_u32 s74, s66, 0x2c100
	s_addc_u32 s75, s67, 0
	s_waitcnt lgkmcnt(4)
	global_store_dwordx4 v200, v[172:175], s[74:75]
	s_add_u32 s74, s66, 0x30100
	s_addc_u32 s75, s67, 0
	s_waitcnt lgkmcnt(3)
	global_store_dwordx4 v200, v[176:179], s[74:75]
	s_add_u32 s74, s66, 0x34100
	s_addc_u32 s75, s67, 0
	s_waitcnt lgkmcnt(2)
	global_store_dwordx4 v200, v[180:183], s[74:75]
	s_add_u32 s74, s66, 0x38100
	s_addc_u32 s75, s67, 0
	s_waitcnt lgkmcnt(1)
	global_store_dwordx4 v200, v[184:187], s[74:75]
	s_add_u32 s74, s66, 0x3c100
	s_addc_u32 s75, s67, 0
	s_waitcnt lgkmcnt(0)
	global_store_dwordx4 v200, v[188:191], s[74:75]
	global_load_dwordx4 v[160:163], v202, s[70:71] offset:256
	global_load_dwordx4 v[164:167], v202, s[70:71] offset:288
	global_load_dwordx4 v[168:171], v202, s[70:71] offset:320
	global_load_dwordx4 v[172:175], v202, s[70:71] offset:352
	global_load_dwordx4 v[176:179], v202, s[70:71] offset:384
	global_load_dwordx4 v[180:183], v202, s[70:71] offset:416
	global_load_dwordx4 v[184:187], v202, s[70:71] offset:448
	global_load_dwordx4 v[188:191], v202, s[70:71] offset:480
	s_waitcnt vmcnt(7)
	v_mul_f32_e32 v16, v160, v16
	v_mul_f32_e32 v17, v161, v17
	v_mul_f32_e32 v18, v162, v18
	v_mul_f32_e32 v19, v163, v19
	v_cvt_pk_bf16_f32 v16, v16, v17
	v_cvt_pk_bf16_f32 v17, v18, v19
	ds_write_b64 v194, v[16:17]
	s_waitcnt vmcnt(6)
	v_mul_f32_e32 v20, v164, v20
	v_mul_f32_e32 v21, v165, v21
	v_mul_f32_e32 v22, v166, v22
	v_mul_f32_e32 v23, v167, v23
	v_cvt_pk_bf16_f32 v20, v20, v21
	v_cvt_pk_bf16_f32 v21, v22, v23
	ds_write_b64 v194, v[20:21] offset:16
	s_waitcnt vmcnt(5)
	v_mul_f32_e32 v24, v168, v24
	v_mul_f32_e32 v25, v169, v25
	v_mul_f32_e32 v26, v170, v26
	v_mul_f32_e32 v27, v171, v27
	v_cvt_pk_bf16_f32 v24, v24, v25
	v_cvt_pk_bf16_f32 v25, v26, v27
	ds_write_b64 v194, v[24:25] offset:32
	s_waitcnt vmcnt(4)
	v_mul_f32_e32 v28, v172, v28
	v_mul_f32_e32 v29, v173, v29
	v_mul_f32_e32 v30, v174, v30
	v_mul_f32_e32 v31, v175, v31
	v_cvt_pk_bf16_f32 v28, v28, v29
	v_cvt_pk_bf16_f32 v29, v30, v31
	ds_write_b64 v194, v[28:29] offset:48
	s_waitcnt vmcnt(3)
	v_mul_f32_e32 v0, v176, v0
	v_mul_f32_e32 v1, v177, v1
	v_mul_f32_e32 v2, v178, v2
	v_mul_f32_e32 v3, v179, v3
	v_cvt_pk_bf16_f32 v0, v0, v1
	v_cvt_pk_bf16_f32 v1, v2, v3
	ds_write_b64 v194, v[0:1] offset:64
	s_waitcnt vmcnt(2)
	v_mul_f32_e32 v4, v180, v4
	v_mul_f32_e32 v5, v181, v5
	v_mul_f32_e32 v6, v182, v6
	v_mul_f32_e32 v7, v183, v7
	v_cvt_pk_bf16_f32 v4, v4, v5
	v_cvt_pk_bf16_f32 v5, v6, v7
	ds_write_b64 v194, v[4:5] offset:80
	s_waitcnt vmcnt(1)
	v_mul_f32_e32 v8, v184, v8
	v_mul_f32_e32 v9, v185, v9
	v_mul_f32_e32 v10, v186, v10
	v_mul_f32_e32 v11, v187, v11
	v_cvt_pk_bf16_f32 v8, v8, v9
	v_cvt_pk_bf16_f32 v9, v10, v11
	ds_write_b64 v194, v[8:9] offset:96
	s_waitcnt vmcnt(0)
	v_mul_f32_e32 v12, v188, v12
	v_mul_f32_e32 v13, v189, v13
	v_mul_f32_e32 v14, v190, v14
	v_mul_f32_e32 v15, v191, v15
	v_cvt_pk_bf16_f32 v12, v12, v13
	v_cvt_pk_bf16_f32 v13, v14, v15
	ds_write_b64 v194, v[12:13] offset:112
	ds_read_b128 v[160:163], v199
	ds_read_b128 v[164:167], v199 offset:2176
	ds_read_b128 v[168:171], v199 offset:4352
	ds_read_b128 v[172:175], v199 offset:6528
	s_add_u32 s74, s68, 0x10080
	s_addc_u32 s75, s69, 0
	s_waitcnt lgkmcnt(3)
	global_store_dwordx4 v201, v[160:163], s[74:75]
	s_add_u32 s74, s68, 0x14080
	s_addc_u32 s75, s69, 0
	s_waitcnt lgkmcnt(2)
	global_store_dwordx4 v201, v[164:167], s[74:75]
	s_add_u32 s74, s68, 0x18080
	s_addc_u32 s75, s69, 0
	s_waitcnt lgkmcnt(1)
	global_store_dwordx4 v201, v[168:171], s[74:75]
	s_add_u32 s74, s68, 0x1c080
	s_addc_u32 s75, s69, 0
	s_waitcnt lgkmcnt(0)
	global_store_dwordx4 v201, v[172:175], s[74:75]
	s_load_dwordx2 s[64:65], s[92:93], 0x140
	ds_bpermute_b32 v208, v206, v203
	ds_bpermute_b32 v209, v206, v204
	s_waitcnt lgkmcnt(0)
	s_add_u32 s64, s64, 0x10200
	s_addc_u32 s65, s65, 0
	v_add_f32_e32 v208, v208, v203
	v_add_f32_e32 v209, v209, v204
	s_mov_b32 exec_hi, 0
	s_nop 1
	global_atomic_add_f32 v205, v208, s[64:65]
	global_atomic_add_f32 v205, v209, s[64:65] offset:128
	s_mov_b64 exec, -1
	v_readlane_b32 s64, v207, 0
	v_readlane_b32 s65, v207, 1
	v_readlane_b32 s66, v207, 2
	v_readlane_b32 s67, v207, 3
	v_readlane_b32 s68, v207, 4
	v_readlane_b32 s69, v207, 5
	v_readlane_b32 s70, v207, 6
	v_readlane_b32 s71, v207, 7
	v_readlane_b32 s72, v207, 8
	v_readlane_b32 s73, v207, 9
	v_readlane_b32 s74, v207, 10
	v_readlane_b32 s75, v207, 11
	v_readlane_b32 s76, v207, 12
	v_readlane_b32 s77, v207, 13
	v_readlane_b32 s78, v207, 14
	v_readlane_b32 s79, v207, 15
	s_nop 7
	s_branch .LBB0_1096

; #define GA_LOAD(pr_) do { _Pragma("unroll") for (int i = 0; i < 4; ++i) ra[i] = *(const u32x4*)(Ab + (i * 32) * lda + (pr_) * 64); } while (0)
; #define GB_LOAD(kt_) do { const bfr* bk_ = Bb + (kt_) * NB * 32; \
;     _Pragma("unroll") for (int i = 0; i < 4; ++i) rb[i] = *(const u32x4*)(bk_ + (i * 64) * 32); } while (0)
; #define G_STORE(kt_) do { bfr* as_ = S0 + ((kt_) & 1) * GSTAGE; bfr* bs_ = as_ + 128 * 40; \
;     if (apar == ((kt_) & 1)) { _Pragma("unroll") for (int i = 0; i < 4; ++i) *(u32x4*)(as_ + asoff + i * 32 * 40) = ra[i]; } \
;     _Pragma("unroll") for (int i = 0; i < 4; ++i) *(u32x4*)(bs_ + bsoff + i * 64 * 40) = rb[i]; } while (0)
; template <int lda>
; DI void gemm_mainloop(const bfr* __restrict__ A, const bfr* __restrict__ Bt, int NB, int K, int m0, int n0, char* smem, f32x16 (&acc)[2][4]) {
;     ...
;   const int arow = tid >> 3, ac8 = tid & 7, apar = ac8 >> 2;
;   const bfr* Ab = A + (m0 + arow) * lda + ac8 * 8;
;   const int asoff = arow * 40 + (ac8 & 3) * 8;
;   const int brow = tid >> 2, bc4 = tid & 3;
;   const bfr* Bb = Bt + (n0 + brow) * 32 + bc4 * 8;
;   const int bsoff = brow * 40 + bc4 * 8;
;     ...
;   GA_LOAD(0);
;   GB_LOAD(0);
;   G_STORE(0);
;   GB_LOAD(1);
;   __syncthreads();
; template <bool FIRST, bool HAS_H>
; DI void phase_gemm_resid(const Params& p, const bfr* A, const bfr* Wt, const float* gnext, float* ss, char* smem) {
;     ...
;   for (int t0 = blockIdx.x; t0 < 128 * 4; t0 += gridDim.x) {
;     const int t = ((gridDim.x & 7) == 0) ? xcd_tile(t0, 4) : t0;
;     const int mt = t >> 2, nt = t & 3, m0 = mt * 128, n0 = nt * 256;
;     f32x16 acc[2][4];
;     gemm_mainloop<1024>(A, Wt, 1024, 1024, m0, n0, smem, acc);
;     int tid2 = threadIdx.x;
;     asm volatile("" : "+v"(tid2));
;     const int lane = tid2 & 63, wid = tid2 >> 6, wr = wid >> 1, wc = wid & 1, r = lane & 31, hl = lane >> 5;
.LBB0_1466:
	s_lshl_b32 s5, s4, 5
	s_and_b32 s36, s5, 0xffffff80
	s_lshl_b32 s4, s4, 8
	s_and_b32 s33, s4, 0x300
	s_mov_b32 s37, 0
	s_mov_b64 s[20:21], 0
	s_lshl_b32 s98, s36, 11
	s_add_u32 s98, s2, s98
	s_addc_u32 s99, s3, 0
	s_lshl_b32 s100, s33, 6
	s_add_u32 s100, s8, s100
	s_addc_u32 s101, s9, 0
	v_writelane_b32 v209, s64, 0
	v_writelane_b32 v209, s65, 1
	v_writelane_b32 v209, s66, 2
	v_writelane_b32 v209, s67, 3
	v_writelane_b32 v209, s68, 4
	v_writelane_b32 v209, s69, 5
	v_writelane_b32 v209, s70, 6
	v_writelane_b32 v209, s71, 7
	v_writelane_b32 v209, s72, 8
	v_writelane_b32 v209, s73, 9
	v_writelane_b32 v209, s74, 10
	v_writelane_b32 v209, s75, 11
	v_writelane_b32 v209, s76, 12
	v_writelane_b32 v209, s77, 13
	v_writelane_b32 v209, s78, 14
	v_writelane_b32 v209, s79, 15
	s_mov_b32 s77, s36
	s_mov_b32 s78, s33
	v_lshrrev_b32_e32 v210, 6, v196
	v_and_b32_e32 v211, 63, v196
	v_readfirstlane_b32 s73, v210
	v_lshrrev_b32_e32 v216, 2, v211
	v_bfe_u32 v217, v211, 4, 2
	v_and_b32_e32 v210, 3, v211
	v_xor_b32_e32 v210, v210, v217
	v_lshlrev_b32_e32 v210, 4, v210
	v_lshl_add_u32 v192, v216, 11, v210
	v_add_u32_e32 v194, 0x8000, v192
	v_lshl_add_u32 v200, v216, 6, v210
	v_and_b32_e32 v216, 31, v211
	v_lshrrev_b32_e32 v217, 5, v211
	v_bfe_u32 v210, v211, 2, 2
	v_xor_b32_e32 v210, v210, v217
	v_lshlrev_b32_e32 v210, 4, v210
	v_lshl_add_u32 v201, v216, 6, v210
	s_lshr_b32 s74, s73, 1
	s_lshl_b32 s74, s74, 12
	s_and_b32 s75, s73, 1
	s_lshl_b32 s75, s75, 13
	v_add_u32_e32 v203, s75, v201
	v_add_u32_e32 v201, s74, v201
	v_xor_b32_e32 v204, 32, v203
	v_xor_b32_e32 v202, 32, v201
	s_lshl_b32 s74, s73, 16
	s_add_u32 s64, s98, s74
	s_addc_u32 s65, s99, 0
	s_lshl_b32 s74, s73, 12
	s_add_u32 s66, s100, s74
	s_addc_u32 s67, s101, 0
	s_lshl_b32 s68, s73, 11
	s_lshl_b32 s69, s73, 12
	s_mov_b32 s70, 0
	s_mov_b32 s71, 0
	s_mov_b32 s72, 0
	s_waitcnt lgkmcnt(0)
	s_barrier
	s_mul_i32 s74, s70, 0x6000
	s_add_u32 s75, s74, s68
	s_mov_b32 m0, s75
	s_add_u32 s76, s74, 0x2000
	s_cmp_eq_u32 s70, 2
	s_cselect_b32 s76, 0x10000, s76
	global_load_lds_dwordx4 v192, s[64:65]
	s_add_u32 m0, s75, 0x400
	s_add_u32 s76, s76, s69
	global_load_lds_dwordx4 v194, s[64:65]
	s_mov_b32 m0, s76
	s_add_u32 s64, s64, 64
	s_addc_u32 s65, s65, 0
	global_load_lds_dwordx4 v200, s[66:67]
	global_load_lds_dwordx4 v200, s[66:67] offset:1024
	global_load_lds_dwordx4 v200, s[66:67] offset:2048
	global_load_lds_dwordx4 v200, s[66:67] offset:3072
	s_add_u32 s66, s66, 0x10000
	s_addc_u32 s67, s67, 0
	s_add_u32 s70, s70, 1
	s_cmp_eq_u32 s70, 3
	s_cselect_b32 s70, 0, s70
	s_mul_i32 s74, s70, 0x6000
	s_add_u32 s75, s74, s68
	s_mov_b32 m0, s75
	s_add_u32 s76, s74, 0x2000
	s_cmp_eq_u32 s70, 2
	s_cselect_b32 s76, 0x10000, s76
	global_load_lds_dwordx4 v192, s[64:65]
	s_add_u32 m0, s75, 0x400
	s_add_u32 s76, s76, s69
	global_load_lds_dwordx4 v194, s[64:65]
	s_mov_b32 m0, s76
	s_add_u32 s64, s64, 64
	s_addc_u32 s65, s65, 0
	global_load_lds_dwordx4 v200, s[66:67]
	global_load_lds_dwordx4 v200, s[66:67] offset:1024
	global_load_lds_dwordx4 v200, s[66:67] offset:2048
	global_load_lds_dwordx4 v200, s[66:67] offset:3072
	s_add_u32 s66, s66, 0x10000
	s_addc_u32 s67, s67, 0
	s_add_u32 s70, s70, 1
	s_cmp_eq_u32 s70, 3
	s_cselect_b32 s70, 0, s70
	s_cmp_lt_u32 s46, 0x100
	s_cbranch_scc1 .Lp15_nostag
	s_sleep 8

; #define MFMA32(a, b, c) __builtin_amdgcn_mfma_f32_32x32x16_bf16((a), (b), (c), 0, 0, 0)
; #define GA_LOAD(pr_) do { _Pragma("unroll") for (int i = 0; i < 4; ++i) ra[i] = *(const u32x4*)(Ab + (i * 32) * lda + (pr_) * 64); } while (0)
; #define GB_LOAD(kt_) do { const bfr* bk_ = Bb + (kt_) * NB * 32; \
;     _Pragma("unroll") for (int i = 0; i < 4; ++i) rb[i] = *(const u32x4*)(bk_ + (i * 64) * 32); } while (0)
; #define G_STORE(kt_) do { bfr* as_ = S0 + ((kt_) & 1) * GSTAGE; bfr* bs_ = as_ + 128 * 40; \
;     if (apar == ((kt_) & 1)) { _Pragma("unroll") for (int i = 0; i < 4; ++i) *(u32x4*)(as_ + asoff + i * 32 * 40) = ra[i]; } \
;     _Pragma("unroll") for (int i = 0; i < 4; ++i) *(u32x4*)(bs_ + bsoff + i * 64 * 40) = rb[i]; } while (0)
; template <int lda>
; DI void gemm_mainloop(const bfr* __restrict__ A, const bfr* __restrict__ Bt, int NB, int K, int m0, int n0, char* smem, f32x16 (&acc)[2][4]) {
;     ...
;   for (int kt = 0; kt < nk; ++kt) {
;     if (kt + 1 < nk) G_STORE(kt + 1);
;     if (kt + 2 < nk) {
;       GB_LOAD(kt + 2);
;       if ((kt & 1) == 0) GA_LOAD((kt >> 1) + 1);
;     }
;     const bfr* As = S0 + (kt & 1) * GSTAGE;
;     const bfr* Bs = As + 128 * 40;
; #pragma unroll
;     for (int ks = 0; ks < 2; ++ks) {
;       bf16x8 af[2], bfg[4];
; #pragma unroll
;       for (int i = 0; i < 2; ++i) af[i] = *(const bf16x8*)(As + (wr * 64 + i * 32 + r) * 40 + ks * 16 + hl * 8);
; #pragma unroll
;       for (int j = 0; j < 4; ++j) bfg[j] = *(const bf16x8*)(Bs + (wc * 128 + j * 32 + r) * 40 + ks * 16 + hl * 8);
; #pragma unroll
;       for (int i = 0; i < 2; ++i)
; #pragma unroll
;         for (int j = 0; j < 4; ++j) acc[i][j] = MFMA32(af[i], bfg[j], acc[i][j]);
;     }
;     __syncthreads();
;   }
.Lp15_loop:
	s_waitcnt vmcnt(6)
	s_barrier
	s_mul_i32 s74, s71, 0x6000
	s_add_u32 s75, s74, 0x2000
	s_cmp_eq_u32 s71, 2
	s_cselect_b32 s75, 0x10000, s75
	v_add_u32_e32 v205, s74, v201
	v_add_u32_e32 v207, s75, v203
	v_add_u32_e32 v206, s74, v202
	v_add_u32_e32 v208, s75, v204
	ds_read_b128 v[128:131], v205
	ds_read_b128 v[144:147], v207
	ds_read_b128 v[148:151], v207 offset:2048
	ds_read_b128 v[152:155], v207 offset:4096
	ds_read_b128 v[156:159], v207 offset:6144
	ds_read_b128 v[132:135], v205 offset:2048
	ds_read_b128 v[136:139], v206
	ds_read_b128 v[160:163], v208
	ds_read_b128 v[164:167], v208 offset:2048
	ds_read_b128 v[168:171], v208 offset:4096
	ds_read_b128 v[172:175], v208 offset:6144
	ds_read_b128 v[140:143], v206 offset:2048
	s_add_u32 s71, s71, 1
	s_cmp_eq_u32 s71, 3
	s_cselect_b32 s71, 0, s71
	s_waitcnt lgkmcnt(10)
	v_mfma_f32_32x32x16_bf16 v[112:127], v[144:147], v[128:131], v[112:127]
	s_mul_i32 s74, s70, 0x6000
	s_add_u32 s75, s74, s68
	s_mov_b32 m0, s75
	s_add_u32 s76, s74, 0x2000
	s_cmp_eq_u32 s70, 2
	s_cselect_b32 s76, 0x10000, s76
	global_load_lds_dwordx4 v192, s[64:65]
	s_waitcnt lgkmcnt(9)
	v_mfma_f32_32x32x16_bf16 v[96:111], v[148:151], v[128:131], v[96:111]
	s_add_u32 m0, s75, 0x400
	s_add_u32 s76, s76, s69
	global_load_lds_dwordx4 v194, s[64:65]
	s_waitcnt lgkmcnt(8)
	v_mfma_f32_32x32x16_bf16 v[80:95], v[152:155], v[128:131], v[80:95]
	s_mov_b32 m0, s76
	s_add_u32 s64, s64, 64
	s_addc_u32 s65, s65, 0
	global_load_lds_dwordx4 v200, s[66:67]
	s_waitcnt lgkmcnt(7)
	v_mfma_f32_32x32x16_bf16 v[64:79], v[156:159], v[128:131], v[64:79]
	global_load_lds_dwordx4 v200, s[66:67] offset:1024
	s_waitcnt lgkmcnt(6)
	v_mfma_f32_32x32x16_bf16 v[48:63], v[144:147], v[132:135], v[48:63]
	global_load_lds_dwordx4 v200, s[66:67] offset:2048
	v_mfma_f32_32x32x16_bf16 v[32:47], v[148:151], v[132:135], v[32:47]
	global_load_lds_dwordx4 v200, s[66:67] offset:3072
	s_add_u32 s66, s66, 0x10000
	s_addc_u32 s67, s67, 0
	v_mfma_f32_32x32x16_bf16 v[16:31], v[152:155], v[132:135], v[16:31]
	s_add_u32 s70, s70, 1
	s_cmp_eq_u32 s70, 3
	s_cselect_b32 s70, 0, s70
	v_mfma_f32_32x32x16_bf16 v[0:15], v[156:159], v[132:135], v[0:15]
	s_waitcnt lgkmcnt(4)
	v_mfma_f32_32x32x16_bf16 v[112:127], v[160:163], v[136:139], v[112:127]
	s_waitcnt lgkmcnt(3)
	v_mfma_f32_32x32x16_bf16 v[96:111], v[164:167], v[136:139], v[96:111]
	s_waitcnt lgkmcnt(2)
	v_mfma_f32_32x32x16_bf16 v[80:95], v[168:171], v[136:139], v[80:95]
	s_waitcnt lgkmcnt(1)
	v_mfma_f32_32x32x16_bf16 v[64:79], v[172:175], v[136:139], v[64:79]
	s_waitcnt lgkmcnt(0)
	v_mfma_f32_32x32x16_bf16 v[48:63], v[160:163], v[140:143], v[48:63]
	v_mfma_f32_32x32x16_bf16 v[32:47], v[164:167], v[140:143], v[32:47]
	v_mfma_f32_32x32x16_bf16 v[16:31], v[168:171], v[140:143], v[16:31]
	v_mfma_f32_32x32x16_bf16 v[0:15], v[172:175], v[140:143], v[0:15]
	s_add_u32 s72, s72, 1
	s_cmp_lt_u32 s72, 30
	s_cbranch_scc1 .Lp15_loop
	s_waitcnt vmcnt(6)
	s_barrier
	s_mul_i32 s74, s71, 0x6000
	s_add_u32 s75, s74, 0x2000
	s_cmp_eq_u32 s71, 2
	s_cselect_b32 s75, 0x10000, s75
	v_add_u32_e32 v205, s74, v201
	v_add_u32_e32 v207, s75, v203
	v_add_u32_e32 v206, s74, v202
	v_add_u32_e32 v208, s75, v204
	ds_read_b128 v[128:131], v205
	ds_read_b128 v[144:147], v207
	ds_read_b128 v[148:151], v207 offset:2048
	ds_read_b128 v[152:155], v207 offset:4096
	ds_read_b128 v[156:159], v207 offset:6144
	ds_read_b128 v[132:135], v205 offset:2048
	ds_read_b128 v[136:139], v206
	ds_read_b128 v[160:163], v208
	ds_read_b128 v[164:167], v208 offset:2048
	ds_read_b128 v[168:171], v208 offset:4096
	ds_read_b128 v[172:175], v208 offset:6144
	ds_read_b128 v[140:143], v206 offset:2048
	s_add_u32 s71, s71, 1
	s_cmp_eq_u32 s71, 3
	s_cselect_b32 s71, 0, s71
	s_waitcnt lgkmcnt(10)
	v_mfma_f32_32x32x16_bf16 v[112:127], v[144:147], v[128:131], v[112:127]
	s_waitcnt lgkmcnt(9)
	v_mfma_f32_32x32x16_bf16 v[96:111], v[148:151], v[128:131], v[96:111]
	s_waitcnt lgkmcnt(8)
	v_mfma_f32_32x32x16_bf16 v[80:95], v[152:155], v[128:131], v[80:95]
	s_waitcnt lgkmcnt(7)
	v_mfma_f32_32x32x16_bf16 v[64:79], v[156:159], v[128:131], v[64:79]
	s_waitcnt lgkmcnt(6)
	v_mfma_f32_32x32x16_bf16 v[48:63], v[144:147], v[132:135], v[48:63]
	v_mfma_f32_32x32x16_bf16 v[32:47], v[148:151], v[132:135], v[32:47]
	v_mfma_f32_32x32x16_bf16 v[16:31], v[152:155], v[132:135], v[16:31]
	v_mfma_f32_32x32x16_bf16 v[0:15], v[156:159], v[132:135], v[0:15]
	s_waitcnt lgkmcnt(4)
	v_mfma_f32_32x32x16_bf16 v[112:127], v[160:163], v[136:139], v[112:127]
	s_waitcnt lgkmcnt(3)
	v_mfma_f32_32x32x16_bf16 v[96:111], v[164:167], v[136:139], v[96:111]
	s_waitcnt lgkmcnt(2)
	v_mfma_f32_32x32x16_bf16 v[80:95], v[168:171], v[136:139], v[80:95]
	s_waitcnt lgkmcnt(1)
	v_mfma_f32_32x32x16_bf16 v[64:79], v[172:175], v[136:139], v[64:79]
	s_waitcnt lgkmcnt(0)
	v_mfma_f32_32x32x16_bf16 v[48:63], v[160:163], v[140:143], v[48:63]
	v_mfma_f32_32x32x16_bf16 v[32:47], v[164:167], v[140:143], v[32:47]
	v_mfma_f32_32x32x16_bf16 v[16:31], v[168:171], v[140:143], v[16:31]
	v_mfma_f32_32x32x16_bf16 v[0:15], v[172:175], v[140:143], v[0:15]
	s_waitcnt vmcnt(0)
	s_barrier
; #define MFMA32(a, b, c) __builtin_amdgcn_mfma_f32_32x32x16_bf16((a), (b), (c), 0, 0, 0)
; DI int crow(int reg, int h) { return (reg & 3) + 8 * (reg >> 2) + 4 * h; }
; template <int lda>
; DI void gemm_mainloop(const bfr* __restrict__ A, const bfr* __restrict__ Bt, int NB, int K, int m0, int n0, char* smem, f32x16 (&acc)[2][4]) {
;     ...
;     const bfr* As = S0 + (kt & 1) * GSTAGE;
;     const bfr* Bs = As + 128 * 40;
; #pragma unroll
;     for (int ks = 0; ks < 2; ++ks) {
;       bf16x8 af[2], bfg[4];
; #pragma unroll
;       for (int i = 0; i < 2; ++i) af[i] = *(const bf16x8*)(As + (wr * 64 + i * 32 + r) * 40 + ks * 16 + hl * 8);
; #pragma unroll
;       for (int j = 0; j < 4; ++j) bfg[j] = *(const bf16x8*)(Bs + (wc * 128 + j * 32 + r) * 40 + ks * 16 + hl * 8);
; #pragma unroll
;       for (int i = 0; i < 2; ++i)
; #pragma unroll
;         for (int j = 0; j < 4; ++j) acc[i][j] = MFMA32(af[i], bfg[j], acc[i][j]);
; template <bool FIRST, bool HAS_H>
; DI void phase_gemm_resid(const Params& p, const bfr* A, const bfr* Wt, const float* gnext, float* ss, char* smem) {
;     ...
;     int tid2 = threadIdx.x;
;     asm volatile("" : "+v"(tid2));
;     const int lane = tid2 & 63, wid = tid2 >> 6, wr = wid >> 1, wc = wid & 1, r = lane & 31, hl = lane >> 5;
;     const float* xsrc = FIRST ? p.x_prompt : X;
;     const int rbase = m0 + wr * 64 + 4 * hl, cbase = n0 + wc * 128 + r;
; #pragma unroll
;     for (int i = 0; i < 2; ++i) {
; #pragma unroll
;       for (int qh = 0; qh < 2; ++qh) {
;         float rs[8];
; #pragma unroll
;         for (int q = 0; q < 8; ++q) rs[q] = 0.f;
; #pragma unroll
;         for (int jh = 0; jh < 2; ++jh) {
;           float xo[2][8];
; #pragma unroll
;           for (int jj = 0; jj < 2; ++jj)
; #pragma unroll
;             for (int q = 0; q < 8; ++q)
;               xo[jj][q] = xsrc[(rbase + i * 32 + crow(qh * 8 + q, 0)) * 1024 + cbase + (jh * 2 + jj) * 32];
	s_mul_i32 s74, s71, 0x6000
	s_add_u32 s75, s74, 0x2000
	s_cmp_eq_u32 s71, 2
	s_cselect_b32 s75, 0x10000, s75
	v_add_u32_e32 v205, s74, v201
	v_add_u32_e32 v207, s75, v203
	v_add_u32_e32 v206, s74, v202
	v_add_u32_e32 v208, s75, v204
	ds_read_b128 v[128:131], v205
	ds_read_b128 v[144:147], v207
	ds_read_b128 v[148:151], v207 offset:2048
	ds_read_b128 v[152:155], v207 offset:4096
	ds_read_b128 v[156:159], v207 offset:6144
	ds_read_b128 v[132:135], v205 offset:2048
	ds_read_b128 v[136:139], v206
	ds_read_b128 v[160:163], v208
	ds_read_b128 v[164:167], v208 offset:2048
	ds_read_b128 v[168:171], v208 offset:4096
	ds_read_b128 v[172:175], v208 offset:6144
	ds_read_b128 v[140:143], v206 offset:2048
	s_add_u32 s71, s71, 1
	s_cmp_eq_u32 s71, 3
	s_cselect_b32 s71, 0, s71
	s_waitcnt lgkmcnt(10)
	v_mfma_f32_32x32x16_bf16 v[112:127], v[144:147], v[128:131], v[112:127]
	s_waitcnt lgkmcnt(9)
	v_mfma_f32_32x32x16_bf16 v[96:111], v[148:151], v[128:131], v[96:111]
	s_waitcnt lgkmcnt(8)
	v_mfma_f32_32x32x16_bf16 v[80:95], v[152:155], v[128:131], v[80:95]
	s_waitcnt lgkmcnt(7)
	v_mfma_f32_32x32x16_bf16 v[64:79], v[156:159], v[128:131], v[64:79]
	s_waitcnt lgkmcnt(6)
	v_mfma_f32_32x32x16_bf16 v[48:63], v[144:147], v[132:135], v[48:63]
	v_mfma_f32_32x32x16_bf16 v[32:47], v[148:151], v[132:135], v[32:47]
	v_mfma_f32_32x32x16_bf16 v[16:31], v[152:155], v[132:135], v[16:31]
	v_mfma_f32_32x32x16_bf16 v[0:15], v[156:159], v[132:135], v[0:15]
	s_waitcnt lgkmcnt(4)
	v_mfma_f32_32x32x16_bf16 v[112:127], v[160:163], v[136:139], v[112:127]
	s_waitcnt lgkmcnt(3)
	v_mfma_f32_32x32x16_bf16 v[96:111], v[164:167], v[136:139], v[96:111]
	s_waitcnt lgkmcnt(2)
	v_mfma_f32_32x32x16_bf16 v[80:95], v[168:171], v[136:139], v[80:95]
	s_waitcnt lgkmcnt(1)
	v_mfma_f32_32x32x16_bf16 v[64:79], v[172:175], v[136:139], v[64:79]
	s_waitcnt lgkmcnt(0)
	v_mfma_f32_32x32x16_bf16 v[48:63], v[160:163], v[140:143], v[48:63]
	v_mfma_f32_32x32x16_bf16 v[32:47], v[164:167], v[140:143], v[32:47]
	v_mfma_f32_32x32x16_bf16 v[16:31], v[168:171], v[140:143], v[16:31]
	v_mfma_f32_32x32x16_bf16 v[0:15], v[172:175], v[140:143], v[0:15]
	s_nop 7
	s_nop 3
	s_load_dwordx2 s[64:65], s[92:93], 0x100
	s_load_dwordx2 s[66:67], s[92:93], 0x100
	s_load_dwordx2 s[68:69], s[92:93], 0x148
	s_load_dwordx2 s[70:71], s[92:93], 0x50
	s_mul_i32 s76, s73, 8704
	s_lshr_b32 s74, s73, 1
	s_lshl_b32 s74, s74, 6
	s_add_u32 s74, s74, s77
	s_and_b32 s75, s73, 1
	s_lshl_b32 s75, s75, 7
	s_add_u32 s75, s75, s78
	v_and_b32_e32 v210, 31, v196
	v_bfe_u32 v211, v196, 5, 1
	v_mul_u32_u24_e32 v216, 272, v210
	v_add_u32_e32 v216, s76, v216
	v_lshl_add_u32 v192, v211, 4, v216
	v_lshl_add_u32 v194, v211, 3, v216
	v_lshlrev_b32_e32 v216, 2, v211
	v_add_lshl_u32 v204, v216, s75, 2
	v_add_lshl_u32 v207, v210, s74, 2
	v_and_b32_e32 v216, 63, v196
	v_xor_b32_e32 v216, 32, v216
	v_lshlrev_b32_e32 v208, 2, v216
	v_bfe_u32 v210, v196, 4, 2
	v_and_b32_e32 v211, 15, v196
	v_mul_u32_u24_e32 v216, 272, v210
	v_lshl_add_u32 v216, v211, 4, v216
	v_add_u32_e32 v200, s76, v216
	v_add_u32_e32 v216, s74, v210
	v_lshlrev_b32_e32 v216, 10, v216
	v_lshl_add_u32 v216, v211, 2, v216
	v_add_lshl_u32 v202, v216, s75, 2
	s_mov_b32 s79, s74
	s_mov_b32 s72, s75
	s_waitcnt lgkmcnt(0)
	s_add_u32 s74, s64, 0x0
	s_addc_u32 s75, s65, 0
	global_load_dwordx4 v[128:131], v202, s[74:75]
	s_add_u32 s74, s64, 0x4000
	s_addc_u32 s75, s65, 0
	global_load_dwordx4 v[132:135], v202, s[74:75]
	s_add_u32 s74, s64, 0x8000
	s_addc_u32 s75, s65, 0
	global_load_dwordx4 v[136:139], v202, s[74:75]
	s_add_u32 s74, s64, 0xc000
	s_addc_u32 s75, s65, 0
	global_load_dwordx4 v[140:143], v202, s[74:75]
	s_add_u32 s74, s64, 0x10000
	s_addc_u32 s75, s65, 0
	global_load_dwordx4 v[144:147], v202, s[74:75]
	s_add_u32 s74, s64, 0x14000
	s_addc_u32 s75, s65, 0
	global_load_dwordx4 v[148:151], v202, s[74:75]
	s_add_u32 s74, s64, 0x18000
	s_addc_u32 s75, s65, 0
	global_load_dwordx4 v[152:155], v202, s[74:75]
	s_add_u32 s74, s64, 0x1c000
	s_addc_u32 s75, s65, 0
	global_load_dwordx4 v[156:159], v202, s[74:75]
	s_mov_b32 s74, s79
	s_mov_b32 s75, s72
	v_bfe_u32 v210, v196, 3, 3
	v_and_b32_e32 v211, 7, v196
	v_mul_u32_u24_e32 v216, 272, v210
	v_lshl_add_u32 v216, v211, 4, v216
	v_add_u32_e32 v201, s76, v216
	v_add_u32_e32 v216, s74, v210
	v_lshlrev_b32_e32 v216, 10, v216
	v_lshl_add_u32 v216, v211, 3, v216
	v_add_lshl_u32 v203, v216, s75, 1
	v_mov_b32_e32 v205, 0
	v_mov_b32_e32 v206, 0
	s_waitcnt lgkmcnt(0)
	s_barrier
; DI bfr f2bf(float a) { return (bfr)(pack2(a, 0.f) & 0xffffu); }
; DI int crow(int reg, int h) { return (reg & 3) + 8 * (reg >> 2) + 4 * h; }
; template <bool FIRST, bool HAS_H>
; DI void phase_gemm_resid(const Params& p, const bfr* A, const bfr* Wt, const float* gnext, float* ss, char* smem) {
;     ...
;         for (int jh = 0; jh < 2; ++jh) {
;           float xo[2][8];
; #pragma unroll
;           for (int jj = 0; jj < 2; ++jj)
; #pragma unroll
;             for (int q = 0; q < 8; ++q)
;               xo[jj][q] = xsrc[(rbase + i * 32 + crow(qh * 8 + q, 0)) * 1024 + cbase + (jh * 2 + jj) * 32];
; #pragma unroll
;           for (int q = 0; q < 8; ++q) {
;             const int o = (rbase + i * 32 + crow(qh * 8 + q, 0)) * 1024 + cbase;
; #pragma unroll
;             for (int jj = 0; jj < 2; ++jj) {
;               const int j = jh * 2 + jj;
;               const float xn = xo[jj][q] + acc[i][j][qh * 8 + q];
;               X[o + j * 32] = xn;
;               if (HAS_H) Hn[o + j * 32] = f2bf(xn * gnext[cbase + j * 32]);
;               rs[q] += xn * xn;
;             }
;           }
;         }
	s_add_u32 s70, s70, 0x1000
	s_addc_u32 s71, s71, 0
	s_waitcnt vmcnt(7)
	ds_write_b128 v200, v[128:131]
	s_waitcnt vmcnt(6)
	ds_write_b128 v200, v[132:135] offset:1088
	s_waitcnt vmcnt(5)
	ds_write_b128 v200, v[136:139] offset:2176
	s_waitcnt vmcnt(4)
	ds_write_b128 v200, v[140:143] offset:3264
	s_waitcnt vmcnt(3)
	ds_write_b128 v200, v[144:147] offset:4352
	s_waitcnt vmcnt(2)
	ds_write_b128 v200, v[148:151] offset:5440
	s_waitcnt vmcnt(1)
	ds_write_b128 v200, v[152:155] offset:6528
	s_waitcnt vmcnt(0)
	ds_write_b128 v200, v[156:159] offset:7616
	s_add_u32 s74, s64, 0x100
	s_addc_u32 s75, s65, 0
	global_load_dwordx4 v[128:131], v202, s[74:75]
	s_add_u32 s74, s64, 0x4100
	s_addc_u32 s75, s65, 0
	global_load_dwordx4 v[132:135], v202, s[74:75]
	s_add_u32 s74, s64, 0x8100
	s_addc_u32 s75, s65, 0
	global_load_dwordx4 v[136:139], v202, s[74:75]
	s_add_u32 s74, s64, 0xc100
	s_addc_u32 s75, s65, 0
	global_load_dwordx4 v[140:143], v202, s[74:75]
	s_add_u32 s74, s64, 0x10100
	s_addc_u32 s75, s65, 0
	global_load_dwordx4 v[144:147], v202, s[74:75]
	s_add_u32 s74, s64, 0x14100
	s_addc_u32 s75, s65, 0
	global_load_dwordx4 v[148:151], v202, s[74:75]
	s_add_u32 s74, s64, 0x18100
	s_addc_u32 s75, s65, 0
	global_load_dwordx4 v[152:155], v202, s[74:75]
	s_add_u32 s74, s64, 0x1c100
	s_addc_u32 s75, s65, 0
	global_load_dwordx4 v[156:159], v202, s[74:75]
	ds_read_b128 v[160:163], v192
	ds_read_b128 v[164:167], v192 offset:32
	ds_read_b128 v[168:171], v192 offset:64
	ds_read_b128 v[172:175], v192 offset:96
	ds_read_b128 v[176:179], v192 offset:128
	ds_read_b128 v[180:183], v192 offset:160
	ds_read_b128 v[184:187], v192 offset:192
	ds_read_b128 v[188:191], v192 offset:224
	s_waitcnt lgkmcnt(7)
	v_add_f32_e32 v112, v160, v112
	v_add_f32_e32 v113, v161, v113
	v_add_f32_e32 v114, v162, v114
	v_add_f32_e32 v115, v163, v115
	v_fmac_f32_e32 v205, v112, v112
	v_fmac_f32_e32 v205, v113, v113
	v_fmac_f32_e32 v205, v114, v114
	v_fmac_f32_e32 v205, v115, v115
	ds_write_b128 v192, v[112:115]
	s_waitcnt lgkmcnt(7)
	v_add_f32_e32 v116, v164, v116
	v_add_f32_e32 v117, v165, v117
	v_add_f32_e32 v118, v166, v118
	v_add_f32_e32 v119, v167, v119
	v_fmac_f32_e32 v205, v116, v116
	v_fmac_f32_e32 v205, v117, v117
	v_fmac_f32_e32 v205, v118, v118
	v_fmac_f32_e32 v205, v119, v119
	ds_write_b128 v192, v[116:119] offset:32
	s_waitcnt lgkmcnt(7)
	v_add_f32_e32 v120, v168, v120
	v_add_f32_e32 v121, v169, v121
	v_add_f32_e32 v122, v170, v122
	v_add_f32_e32 v123, v171, v123
	v_fmac_f32_e32 v205, v120, v120
	v_fmac_f32_e32 v205, v121, v121
	v_fmac_f32_e32 v205, v122, v122
	v_fmac_f32_e32 v205, v123, v123
	ds_write_b128 v192, v[120:123] offset:64
	s_waitcnt lgkmcnt(7)
	v_add_f32_e32 v124, v172, v124
	v_add_f32_e32 v125, v173, v125
	v_add_f32_e32 v126, v174, v126
	v_add_f32_e32 v127, v175, v127
	v_fmac_f32_e32 v205, v124, v124
	v_fmac_f32_e32 v205, v125, v125
	v_fmac_f32_e32 v205, v126, v126
	v_fmac_f32_e32 v205, v127, v127
	ds_write_b128 v192, v[124:127] offset:96
	s_waitcnt lgkmcnt(7)
	v_add_f32_e32 v96, v176, v96
	v_add_f32_e32 v97, v177, v97
	v_add_f32_e32 v98, v178, v98
	v_add_f32_e32 v99, v179, v99
	v_fmac_f32_e32 v205, v96, v96
	v_fmac_f32_e32 v205, v97, v97
	v_fmac_f32_e32 v205, v98, v98
	v_fmac_f32_e32 v205, v99, v99
	ds_write_b128 v192, v[96:99] offset:128
	s_waitcnt lgkmcnt(7)
	v_add_f32_e32 v100, v180, v100
	v_add_f32_e32 v101, v181, v101
	v_add_f32_e32 v102, v182, v102
	v_add_f32_e32 v103, v183, v103
	v_fmac_f32_e32 v205, v100, v100
	v_fmac_f32_e32 v205, v101, v101
	v_fmac_f32_e32 v205, v102, v102
	v_fmac_f32_e32 v205, v103, v103
	ds_write_b128 v192, v[100:103] offset:160
	s_waitcnt lgkmcnt(7)
	v_add_f32_e32 v104, v184, v104
	v_add_f32_e32 v105, v185, v105
	v_add_f32_e32 v106, v186, v106
	v_add_f32_e32 v107, v187, v107
	v_fmac_f32_e32 v205, v104, v104
	v_fmac_f32_e32 v205, v105, v105
	v_fmac_f32_e32 v205, v106, v106
	v_fmac_f32_e32 v205, v107, v107
	ds_write_b128 v192, v[104:107] offset:192
	s_waitcnt lgkmcnt(7)
	v_add_f32_e32 v108, v188, v108
	v_add_f32_e32 v109, v189, v109
	v_add_f32_e32 v110, v190, v110
	v_add_f32_e32 v111, v191, v111
	v_fmac_f32_e32 v205, v108, v108
	v_fmac_f32_e32 v205, v109, v109
	v_fmac_f32_e32 v205, v110, v110
	v_fmac_f32_e32 v205, v111, v111
	ds_write_b128 v192, v[108:111] offset:224
	ds_read_b128 v[160:163], v200
	ds_read_b128 v[164:167], v200 offset:1088
	ds_read_b128 v[168:171], v200 offset:2176
	ds_read_b128 v[172:175], v200 offset:3264
	ds_read_b128 v[176:179], v200 offset:4352
	ds_read_b128 v[180:183], v200 offset:5440
	ds_read_b128 v[184:187], v200 offset:6528
	ds_read_b128 v[188:191], v200 offset:7616
	s_add_u32 s74, s66, 0x0
	s_addc_u32 s75, s67, 0
	s_waitcnt lgkmcnt(7)
	global_store_dwordx4 v202, v[160:163], s[74:75]
	s_add_u32 s74, s66, 0x4000
	s_addc_u32 s75, s67, 0
	s_waitcnt lgkmcnt(6)
	global_store_dwordx4 v202, v[164:167], s[74:75]
	s_add_u32 s74, s66, 0x8000
	s_addc_u32 s75, s67, 0
	s_waitcnt lgkmcnt(5)
	global_store_dwordx4 v202, v[168:171], s[74:75]
	s_add_u32 s74, s66, 0xc000
	s_addc_u32 s75, s67, 0
	s_waitcnt lgkmcnt(4)
	global_store_dwordx4 v202, v[172:175], s[74:75]
	s_add_u32 s74, s66, 0x10000
	s_addc_u32 s75, s67, 0
	s_waitcnt lgkmcnt(3)
	global_store_dwordx4 v202, v[176:179], s[74:75]
	s_add_u32 s74, s66, 0x14000
	s_addc_u32 s75, s67, 0
	s_waitcnt lgkmcnt(2)
	global_store_dwordx4 v202, v[180:183], s[74:75]
	s_add_u32 s74, s66, 0x18000
	s_addc_u32 s75, s67, 0
	s_waitcnt lgkmcnt(1)
	global_store_dwordx4 v202, v[184:187], s[74:75]
	s_add_u32 s74, s66, 0x1c000
	s_addc_u32 s75, s67, 0
	s_waitcnt lgkmcnt(0)
; DI bfr f2bf(float a) { return (bfr)(pack2(a, 0.f) & 0xffffu); }
; DI int crow(int reg, int h) { return (reg & 3) + 8 * (reg >> 2) + 4 * h; }
; template <bool FIRST, bool HAS_H>
; DI void phase_gemm_resid(const Params& p, const bfr* A, const bfr* Wt, const float* gnext, float* ss, char* smem) {
;     ...
;         for (int jh = 0; jh < 2; ++jh) {
;           float xo[2][8];
; #pragma unroll
;           for (int jj = 0; jj < 2; ++jj)
; #pragma unroll
;             for (int q = 0; q < 8; ++q)
;               xo[jj][q] = xsrc[(rbase + i * 32 + crow(qh * 8 + q, 0)) * 1024 + cbase + (jh * 2 + jj) * 32];
; #pragma unroll
;           for (int q = 0; q < 8; ++q) {
;             const int o = (rbase + i * 32 + crow(qh * 8 + q, 0)) * 1024 + cbase;
; #pragma unroll
;             for (int jj = 0; jj < 2; ++jj) {
;               const int j = jh * 2 + jj;
;               const float xn = xo[jj][q] + acc[i][j][qh * 8 + q];
;               X[o + j * 32] = xn;
;               if (HAS_H) Hn[o + j * 32] = f2bf(xn * gnext[cbase + j * 32]);
;               rs[q] += xn * xn;
;             }
;           }
;         }
	global_store_dwordx4 v202, v[188:191], s[74:75]
	global_load_dwordx4 v[160:163], v204, s[70:71]
	global_load_dwordx4 v[164:167], v204, s[70:71] offset:32
	global_load_dwordx4 v[168:171], v204, s[70:71] offset:64
	global_load_dwordx4 v[172:175], v204, s[70:71] offset:96
	global_load_dwordx4 v[176:179], v204, s[70:71] offset:128
	global_load_dwordx4 v[180:183], v204, s[70:71] offset:160
	global_load_dwordx4 v[184:187], v204, s[70:71] offset:192
	global_load_dwordx4 v[188:191], v204, s[70:71] offset:224
	s_waitcnt vmcnt(7)
	v_mul_f32_e32 v112, v160, v112
	v_mul_f32_e32 v113, v161, v113
	v_mul_f32_e32 v114, v162, v114
	v_mul_f32_e32 v115, v163, v115
	v_cvt_pk_bf16_f32 v112, v112, v113
	v_cvt_pk_bf16_f32 v113, v114, v115
	ds_write_b64 v194, v[112:113]
	s_waitcnt vmcnt(6)
	v_mul_f32_e32 v116, v164, v116
	v_mul_f32_e32 v117, v165, v117
	v_mul_f32_e32 v118, v166, v118
	v_mul_f32_e32 v119, v167, v119
	v_cvt_pk_bf16_f32 v116, v116, v117
	v_cvt_pk_bf16_f32 v117, v118, v119
	ds_write_b64 v194, v[116:117] offset:16
	s_waitcnt vmcnt(5)
	v_mul_f32_e32 v120, v168, v120
	v_mul_f32_e32 v121, v169, v121
	v_mul_f32_e32 v122, v170, v122
	v_mul_f32_e32 v123, v171, v123
	v_cvt_pk_bf16_f32 v120, v120, v121
	v_cvt_pk_bf16_f32 v121, v122, v123
	ds_write_b64 v194, v[120:121] offset:32
	s_waitcnt vmcnt(4)
	v_mul_f32_e32 v124, v172, v124
	v_mul_f32_e32 v125, v173, v125
	v_mul_f32_e32 v126, v174, v126
	v_mul_f32_e32 v127, v175, v127
	v_cvt_pk_bf16_f32 v124, v124, v125
	v_cvt_pk_bf16_f32 v125, v126, v127
	ds_write_b64 v194, v[124:125] offset:48
	s_waitcnt vmcnt(3)
	v_mul_f32_e32 v96, v176, v96
	v_mul_f32_e32 v97, v177, v97
	v_mul_f32_e32 v98, v178, v98
	v_mul_f32_e32 v99, v179, v99
	v_cvt_pk_bf16_f32 v96, v96, v97
	v_cvt_pk_bf16_f32 v97, v98, v99
	ds_write_b64 v194, v[96:97] offset:64
	s_waitcnt vmcnt(2)
	v_mul_f32_e32 v100, v180, v100
	v_mul_f32_e32 v101, v181, v101
	v_mul_f32_e32 v102, v182, v102
	v_mul_f32_e32 v103, v183, v103
	v_cvt_pk_bf16_f32 v100, v100, v101
	v_cvt_pk_bf16_f32 v101, v102, v103
	ds_write_b64 v194, v[100:101] offset:80
	s_waitcnt vmcnt(1)
	v_mul_f32_e32 v104, v184, v104
	v_mul_f32_e32 v105, v185, v105
	v_mul_f32_e32 v106, v186, v106
	v_mul_f32_e32 v107, v187, v107
	v_cvt_pk_bf16_f32 v104, v104, v105
	v_cvt_pk_bf16_f32 v105, v106, v107
	ds_write_b64 v194, v[104:105] offset:96
	s_waitcnt vmcnt(0)
	v_mul_f32_e32 v108, v188, v108
	v_mul_f32_e32 v109, v189, v109
	v_mul_f32_e32 v110, v190, v110
	v_mul_f32_e32 v111, v191, v111
	v_cvt_pk_bf16_f32 v108, v108, v109
	v_cvt_pk_bf16_f32 v109, v110, v111
	ds_write_b64 v194, v[108:109] offset:112
	ds_read_b128 v[160:163], v201
	ds_read_b128 v[164:167], v201 offset:2176
	ds_read_b128 v[168:171], v201 offset:4352
	ds_read_b128 v[172:175], v201 offset:6528
	s_add_u32 s74, s68, 0x0
	s_addc_u32 s75, s69, 0
	s_waitcnt lgkmcnt(3)
	global_store_dwordx4 v203, v[160:163], s[74:75]
	s_add_u32 s74, s68, 0x4000
	s_addc_u32 s75, s69, 0
	s_waitcnt lgkmcnt(2)
	global_store_dwordx4 v203, v[164:167], s[74:75]
	s_add_u32 s74, s68, 0x8000
	s_addc_u32 s75, s69, 0
	s_waitcnt lgkmcnt(1)
	global_store_dwordx4 v203, v[168:171], s[74:75]
	s_add_u32 s74, s68, 0xc000
	s_addc_u32 s75, s69, 0
	s_waitcnt lgkmcnt(0)
	global_store_dwordx4 v203, v[172:175], s[74:75]
	s_waitcnt vmcnt(4)
	ds_write_b128 v200, v[128:131]
	s_waitcnt vmcnt(4)
	ds_write_b128 v200, v[132:135] offset:1088
	s_waitcnt vmcnt(4)
	ds_write_b128 v200, v[136:139] offset:2176
	s_waitcnt vmcnt(4)
	ds_write_b128 v200, v[140:143] offset:3264
	s_waitcnt vmcnt(4)
	ds_write_b128 v200, v[144:147] offset:4352
	s_waitcnt vmcnt(4)
	ds_write_b128 v200, v[148:151] offset:5440
	s_waitcnt vmcnt(4)
	ds_write_b128 v200, v[152:155] offset:6528
	s_waitcnt vmcnt(4)
	ds_write_b128 v200, v[156:159] offset:7616
	s_add_u32 s74, s64, 0x20000
	s_addc_u32 s75, s65, 0
	global_load_dwordx4 v[128:131], v202, s[74:75]
	s_add_u32 s74, s64, 0x24000
	s_addc_u32 s75, s65, 0
	global_load_dwordx4 v[132:135], v202, s[74:75]
	s_add_u32 s74, s64, 0x28000
	s_addc_u32 s75, s65, 0
	global_load_dwordx4 v[136:139], v202, s[74:75]
	s_add_u32 s74, s64, 0x2c000
	s_addc_u32 s75, s65, 0
	global_load_dwordx4 v[140:143], v202, s[74:75]
	s_add_u32 s74, s64, 0x30000
	s_addc_u32 s75, s65, 0
	global_load_dwordx4 v[144:147], v202, s[74:75]
	s_add_u32 s74, s64, 0x34000
	s_addc_u32 s75, s65, 0
	global_load_dwordx4 v[148:151], v202, s[74:75]
	s_add_u32 s74, s64, 0x38000
	s_addc_u32 s75, s65, 0
	global_load_dwordx4 v[152:155], v202, s[74:75]
	s_add_u32 s74, s64, 0x3c000
	s_addc_u32 s75, s65, 0
	global_load_dwordx4 v[156:159], v202, s[74:75]
	ds_read_b128 v[160:163], v192
	ds_read_b128 v[164:167], v192 offset:32
	ds_read_b128 v[168:171], v192 offset:64
	ds_read_b128 v[172:175], v192 offset:96
	ds_read_b128 v[176:179], v192 offset:128
	ds_read_b128 v[180:183], v192 offset:160
	ds_read_b128 v[184:187], v192 offset:192
	ds_read_b128 v[188:191], v192 offset:224
	s_waitcnt lgkmcnt(7)
	v_add_f32_e32 v80, v160, v80
	v_add_f32_e32 v81, v161, v81
	v_add_f32_e32 v82, v162, v82
	v_add_f32_e32 v83, v163, v83
	v_fmac_f32_e32 v205, v80, v80
	v_fmac_f32_e32 v205, v81, v81
	v_fmac_f32_e32 v205, v82, v82
	v_fmac_f32_e32 v205, v83, v83
	ds_write_b128 v192, v[80:83]
	s_waitcnt lgkmcnt(7)
	v_add_f32_e32 v84, v164, v84
	v_add_f32_e32 v85, v165, v85
	v_add_f32_e32 v86, v166, v86
	v_add_f32_e32 v87, v167, v87
	v_fmac_f32_e32 v205, v84, v84
	v_fmac_f32_e32 v205, v85, v85
	v_fmac_f32_e32 v205, v86, v86
	v_fmac_f32_e32 v205, v87, v87
	ds_write_b128 v192, v[84:87] offset:32
	s_waitcnt lgkmcnt(7)
	v_add_f32_e32 v88, v168, v88
	v_add_f32_e32 v89, v169, v89
	v_add_f32_e32 v90, v170, v90
	v_add_f32_e32 v91, v171, v91
	v_fmac_f32_e32 v205, v88, v88
	v_fmac_f32_e32 v205, v89, v89
	v_fmac_f32_e32 v205, v90, v90
	v_fmac_f32_e32 v205, v91, v91
	ds_write_b128 v192, v[88:91] offset:64
	s_waitcnt lgkmcnt(7)
; DI bfr f2bf(float a) { return (bfr)(pack2(a, 0.f) & 0xffffu); }
; DI int crow(int reg, int h) { return (reg & 3) + 8 * (reg >> 2) + 4 * h; }
; template <bool FIRST, bool HAS_H>
; DI void phase_gemm_resid(const Params& p, const bfr* A, const bfr* Wt, const float* gnext, float* ss, char* smem) {
;     ...
;         for (int jh = 0; jh < 2; ++jh) {
;           float xo[2][8];
; #pragma unroll
;           for (int jj = 0; jj < 2; ++jj)
; #pragma unroll
;             for (int q = 0; q < 8; ++q)
;               xo[jj][q] = xsrc[(rbase + i * 32 + crow(qh * 8 + q, 0)) * 1024 + cbase + (jh * 2 + jj) * 32];
; #pragma unroll
;           for (int q = 0; q < 8; ++q) {
;             const int o = (rbase + i * 32 + crow(qh * 8 + q, 0)) * 1024 + cbase;
; #pragma unroll
;             for (int jj = 0; jj < 2; ++jj) {
;               const int j = jh * 2 + jj;
;               const float xn = xo[jj][q] + acc[i][j][qh * 8 + q];
;               X[o + j * 32] = xn;
;               if (HAS_H) Hn[o + j * 32] = f2bf(xn * gnext[cbase + j * 32]);
;               rs[q] += xn * xn;
;             }
;           }
;         }
	v_add_f32_e32 v92, v172, v92
	v_add_f32_e32 v93, v173, v93
	v_add_f32_e32 v94, v174, v94
	v_add_f32_e32 v95, v175, v95
	v_fmac_f32_e32 v205, v92, v92
	v_fmac_f32_e32 v205, v93, v93
	v_fmac_f32_e32 v205, v94, v94
	v_fmac_f32_e32 v205, v95, v95
	ds_write_b128 v192, v[92:95] offset:96
	s_waitcnt lgkmcnt(7)
	v_add_f32_e32 v64, v176, v64
	v_add_f32_e32 v65, v177, v65
	v_add_f32_e32 v66, v178, v66
	v_add_f32_e32 v67, v179, v67
	v_fmac_f32_e32 v205, v64, v64
	v_fmac_f32_e32 v205, v65, v65
	v_fmac_f32_e32 v205, v66, v66
	v_fmac_f32_e32 v205, v67, v67
	ds_write_b128 v192, v[64:67] offset:128
	s_waitcnt lgkmcnt(7)
	v_add_f32_e32 v68, v180, v68
	v_add_f32_e32 v69, v181, v69
	v_add_f32_e32 v70, v182, v70
	v_add_f32_e32 v71, v183, v71
	v_fmac_f32_e32 v205, v68, v68
	v_fmac_f32_e32 v205, v69, v69
	v_fmac_f32_e32 v205, v70, v70
	v_fmac_f32_e32 v205, v71, v71
	ds_write_b128 v192, v[68:71] offset:160
	s_waitcnt lgkmcnt(7)
	v_add_f32_e32 v72, v184, v72
	v_add_f32_e32 v73, v185, v73
	v_add_f32_e32 v74, v186, v74
	v_add_f32_e32 v75, v187, v75
	v_fmac_f32_e32 v205, v72, v72
	v_fmac_f32_e32 v205, v73, v73
	v_fmac_f32_e32 v205, v74, v74
	v_fmac_f32_e32 v205, v75, v75
	ds_write_b128 v192, v[72:75] offset:192
	s_waitcnt lgkmcnt(7)
	v_add_f32_e32 v76, v188, v76
	v_add_f32_e32 v77, v189, v77
	v_add_f32_e32 v78, v190, v78
	v_add_f32_e32 v79, v191, v79
	v_fmac_f32_e32 v205, v76, v76
	v_fmac_f32_e32 v205, v77, v77
	v_fmac_f32_e32 v205, v78, v78
	v_fmac_f32_e32 v205, v79, v79
	ds_write_b128 v192, v[76:79] offset:224
	ds_read_b128 v[160:163], v200
	ds_read_b128 v[164:167], v200 offset:1088
	ds_read_b128 v[168:171], v200 offset:2176
	ds_read_b128 v[172:175], v200 offset:3264
	ds_read_b128 v[176:179], v200 offset:4352
	ds_read_b128 v[180:183], v200 offset:5440
	ds_read_b128 v[184:187], v200 offset:6528
	ds_read_b128 v[188:191], v200 offset:7616
	s_add_u32 s74, s66, 0x100
	s_addc_u32 s75, s67, 0
	s_waitcnt lgkmcnt(7)
	global_store_dwordx4 v202, v[160:163], s[74:75]
	s_add_u32 s74, s66, 0x4100
	s_addc_u32 s75, s67, 0
	s_waitcnt lgkmcnt(6)
	global_store_dwordx4 v202, v[164:167], s[74:75]
	s_add_u32 s74, s66, 0x8100
	s_addc_u32 s75, s67, 0
	s_waitcnt lgkmcnt(5)
	global_store_dwordx4 v202, v[168:171], s[74:75]
	s_add_u32 s74, s66, 0xc100
	s_addc_u32 s75, s67, 0
	s_waitcnt lgkmcnt(4)
	global_store_dwordx4 v202, v[172:175], s[74:75]
	s_add_u32 s74, s66, 0x10100
	s_addc_u32 s75, s67, 0
	s_waitcnt lgkmcnt(3)
	global_store_dwordx4 v202, v[176:179], s[74:75]
	s_add_u32 s74, s66, 0x14100
	s_addc_u32 s75, s67, 0
	s_waitcnt lgkmcnt(2)
	global_store_dwordx4 v202, v[180:183], s[74:75]
	s_add_u32 s74, s66, 0x18100
	s_addc_u32 s75, s67, 0
	s_waitcnt lgkmcnt(1)
	global_store_dwordx4 v202, v[184:187], s[74:75]
	s_add_u32 s74, s66, 0x1c100
	s_addc_u32 s75, s67, 0
	s_waitcnt lgkmcnt(0)
	global_store_dwordx4 v202, v[188:191], s[74:75]
	global_load_dwordx4 v[160:163], v204, s[70:71] offset:256
	global_load_dwordx4 v[164:167], v204, s[70:71] offset:288
	global_load_dwordx4 v[168:171], v204, s[70:71] offset:320
	global_load_dwordx4 v[172:175], v204, s[70:71] offset:352
	global_load_dwordx4 v[176:179], v204, s[70:71] offset:384
	global_load_dwordx4 v[180:183], v204, s[70:71] offset:416
	global_load_dwordx4 v[184:187], v204, s[70:71] offset:448
	global_load_dwordx4 v[188:191], v204, s[70:71] offset:480
	s_waitcnt vmcnt(7)
	v_mul_f32_e32 v80, v160, v80
	v_mul_f32_e32 v81, v161, v81
	v_mul_f32_e32 v82, v162, v82
	v_mul_f32_e32 v83, v163, v83
	v_cvt_pk_bf16_f32 v80, v80, v81
	v_cvt_pk_bf16_f32 v81, v82, v83
	ds_write_b64 v194, v[80:81]
	s_waitcnt vmcnt(6)
	v_mul_f32_e32 v84, v164, v84
	v_mul_f32_e32 v85, v165, v85
	v_mul_f32_e32 v86, v166, v86
	v_mul_f32_e32 v87, v167, v87
	v_cvt_pk_bf16_f32 v84, v84, v85
	v_cvt_pk_bf16_f32 v85, v86, v87
	ds_write_b64 v194, v[84:85] offset:16
	s_waitcnt vmcnt(5)
	v_mul_f32_e32 v88, v168, v88
	v_mul_f32_e32 v89, v169, v89
	v_mul_f32_e32 v90, v170, v90
	v_mul_f32_e32 v91, v171, v91
	v_cvt_pk_bf16_f32 v88, v88, v89
	v_cvt_pk_bf16_f32 v89, v90, v91
	ds_write_b64 v194, v[88:89] offset:32
	s_waitcnt vmcnt(4)
	v_mul_f32_e32 v92, v172, v92
	v_mul_f32_e32 v93, v173, v93
	v_mul_f32_e32 v94, v174, v94
	v_mul_f32_e32 v95, v175, v95
	v_cvt_pk_bf16_f32 v92, v92, v93
	v_cvt_pk_bf16_f32 v93, v94, v95
	ds_write_b64 v194, v[92:93] offset:48
	s_waitcnt vmcnt(3)
	v_mul_f32_e32 v64, v176, v64
	v_mul_f32_e32 v65, v177, v65
	v_mul_f32_e32 v66, v178, v66
	v_mul_f32_e32 v67, v179, v67
	v_cvt_pk_bf16_f32 v64, v64, v65
	v_cvt_pk_bf16_f32 v65, v66, v67
	ds_write_b64 v194, v[64:65] offset:64
	s_waitcnt vmcnt(2)
	v_mul_f32_e32 v68, v180, v68
	v_mul_f32_e32 v69, v181, v69
	v_mul_f32_e32 v70, v182, v70
	v_mul_f32_e32 v71, v183, v71
	v_cvt_pk_bf16_f32 v68, v68, v69
	v_cvt_pk_bf16_f32 v69, v70, v71
	ds_write_b64 v194, v[68:69] offset:80
	s_waitcnt vmcnt(1)
	v_mul_f32_e32 v72, v184, v72
	v_mul_f32_e32 v73, v185, v73
	v_mul_f32_e32 v74, v186, v74
	v_mul_f32_e32 v75, v187, v75
	v_cvt_pk_bf16_f32 v72, v72, v73
	v_cvt_pk_bf16_f32 v73, v74, v75
	ds_write_b64 v194, v[72:73] offset:96
	s_waitcnt vmcnt(0)
	v_mul_f32_e32 v76, v188, v76
	v_mul_f32_e32 v77, v189, v77
	v_mul_f32_e32 v78, v190, v78
	v_mul_f32_e32 v79, v191, v79
	v_cvt_pk_bf16_f32 v76, v76, v77
	v_cvt_pk_bf16_f32 v77, v78, v79
	ds_write_b64 v194, v[76:77] offset:112
	ds_read_b128 v[160:163], v201
	ds_read_b128 v[164:167], v201 offset:2176
	ds_read_b128 v[168:171], v201 offset:4352
	ds_read_b128 v[172:175], v201 offset:6528
	s_add_u32 s74, s68, 0x80
	s_addc_u32 s75, s69, 0
	s_waitcnt lgkmcnt(3)
	global_store_dwordx4 v203, v[160:163], s[74:75]
	s_add_u32 s74, s68, 0x4080
	s_addc_u32 s75, s69, 0
	s_waitcnt lgkmcnt(2)
; DI bfr f2bf(float a) { return (bfr)(pack2(a, 0.f) & 0xffffu); }
; DI int crow(int reg, int h) { return (reg & 3) + 8 * (reg >> 2) + 4 * h; }
; template <bool FIRST, bool HAS_H>
; DI void phase_gemm_resid(const Params& p, const bfr* A, const bfr* Wt, const float* gnext, float* ss, char* smem) {
;     ...
;         for (int jh = 0; jh < 2; ++jh) {
;           float xo[2][8];
; #pragma unroll
;           for (int jj = 0; jj < 2; ++jj)
; #pragma unroll
;             for (int q = 0; q < 8; ++q)
;               xo[jj][q] = xsrc[(rbase + i * 32 + crow(qh * 8 + q, 0)) * 1024 + cbase + (jh * 2 + jj) * 32];
; #pragma unroll
;           for (int q = 0; q < 8; ++q) {
;             const int o = (rbase + i * 32 + crow(qh * 8 + q, 0)) * 1024 + cbase;
; #pragma unroll
;             for (int jj = 0; jj < 2; ++jj) {
;               const int j = jh * 2 + jj;
;               const float xn = xo[jj][q] + acc[i][j][qh * 8 + q];
;               X[o + j * 32] = xn;
;               if (HAS_H) Hn[o + j * 32] = f2bf(xn * gnext[cbase + j * 32]);
;               rs[q] += xn * xn;
;             }
;           }
;         }
	global_store_dwordx4 v203, v[164:167], s[74:75]
	s_add_u32 s74, s68, 0x8080
	s_addc_u32 s75, s69, 0
	s_waitcnt lgkmcnt(1)
	global_store_dwordx4 v203, v[168:171], s[74:75]
	s_add_u32 s74, s68, 0xc080
	s_addc_u32 s75, s69, 0
	s_waitcnt lgkmcnt(0)
	global_store_dwordx4 v203, v[172:175], s[74:75]
	s_waitcnt vmcnt(4)
	ds_write_b128 v200, v[128:131]
	s_waitcnt vmcnt(4)
	ds_write_b128 v200, v[132:135] offset:1088
	s_waitcnt vmcnt(4)
	ds_write_b128 v200, v[136:139] offset:2176
	s_waitcnt vmcnt(4)
	ds_write_b128 v200, v[140:143] offset:3264
	s_waitcnt vmcnt(4)
	ds_write_b128 v200, v[144:147] offset:4352
	s_waitcnt vmcnt(4)
	ds_write_b128 v200, v[148:151] offset:5440
	s_waitcnt vmcnt(4)
	ds_write_b128 v200, v[152:155] offset:6528
	s_waitcnt vmcnt(4)
	ds_write_b128 v200, v[156:159] offset:7616
	s_add_u32 s74, s64, 0x20100
	s_addc_u32 s75, s65, 0
	global_load_dwordx4 v[128:131], v202, s[74:75]
	s_add_u32 s74, s64, 0x24100
	s_addc_u32 s75, s65, 0
	global_load_dwordx4 v[132:135], v202, s[74:75]
	s_add_u32 s74, s64, 0x28100
	s_addc_u32 s75, s65, 0
	global_load_dwordx4 v[136:139], v202, s[74:75]
	s_add_u32 s74, s64, 0x2c100
	s_addc_u32 s75, s65, 0
	global_load_dwordx4 v[140:143], v202, s[74:75]
	s_add_u32 s74, s64, 0x30100
	s_addc_u32 s75, s65, 0
	global_load_dwordx4 v[144:147], v202, s[74:75]
	s_add_u32 s74, s64, 0x34100
	s_addc_u32 s75, s65, 0
	global_load_dwordx4 v[148:151], v202, s[74:75]
	s_add_u32 s74, s64, 0x38100
	s_addc_u32 s75, s65, 0
	global_load_dwordx4 v[152:155], v202, s[74:75]
	s_add_u32 s74, s64, 0x3c100
	s_addc_u32 s75, s65, 0
	global_load_dwordx4 v[156:159], v202, s[74:75]
	ds_read_b128 v[160:163], v192
	ds_read_b128 v[164:167], v192 offset:32
	ds_read_b128 v[168:171], v192 offset:64
	ds_read_b128 v[172:175], v192 offset:96
	ds_read_b128 v[176:179], v192 offset:128
	ds_read_b128 v[180:183], v192 offset:160
	ds_read_b128 v[184:187], v192 offset:192
	ds_read_b128 v[188:191], v192 offset:224
	s_waitcnt lgkmcnt(7)
	v_add_f32_e32 v48, v160, v48
	v_add_f32_e32 v49, v161, v49
	v_add_f32_e32 v50, v162, v50
	v_add_f32_e32 v51, v163, v51
	v_fmac_f32_e32 v206, v48, v48
	v_fmac_f32_e32 v206, v49, v49
	v_fmac_f32_e32 v206, v50, v50
	v_fmac_f32_e32 v206, v51, v51
	ds_write_b128 v192, v[48:51]
	s_waitcnt lgkmcnt(7)
	v_add_f32_e32 v52, v164, v52
	v_add_f32_e32 v53, v165, v53
	v_add_f32_e32 v54, v166, v54
	v_add_f32_e32 v55, v167, v55
	v_fmac_f32_e32 v206, v52, v52
	v_fmac_f32_e32 v206, v53, v53
	v_fmac_f32_e32 v206, v54, v54
	v_fmac_f32_e32 v206, v55, v55
	ds_write_b128 v192, v[52:55] offset:32
	s_waitcnt lgkmcnt(7)
	v_add_f32_e32 v56, v168, v56
	v_add_f32_e32 v57, v169, v57
	v_add_f32_e32 v58, v170, v58
	v_add_f32_e32 v59, v171, v59
	v_fmac_f32_e32 v206, v56, v56
	v_fmac_f32_e32 v206, v57, v57
	v_fmac_f32_e32 v206, v58, v58
	v_fmac_f32_e32 v206, v59, v59
	ds_write_b128 v192, v[56:59] offset:64
	s_waitcnt lgkmcnt(7)
	v_add_f32_e32 v60, v172, v60
	v_add_f32_e32 v61, v173, v61
	v_add_f32_e32 v62, v174, v62
	v_add_f32_e32 v63, v175, v63
	v_fmac_f32_e32 v206, v60, v60
	v_fmac_f32_e32 v206, v61, v61
	v_fmac_f32_e32 v206, v62, v62
	v_fmac_f32_e32 v206, v63, v63
	ds_write_b128 v192, v[60:63] offset:96
	s_waitcnt lgkmcnt(7)
	v_add_f32_e32 v32, v176, v32
	v_add_f32_e32 v33, v177, v33
	v_add_f32_e32 v34, v178, v34
	v_add_f32_e32 v35, v179, v35
	v_fmac_f32_e32 v206, v32, v32
	v_fmac_f32_e32 v206, v33, v33
	v_fmac_f32_e32 v206, v34, v34
	v_fmac_f32_e32 v206, v35, v35
	ds_write_b128 v192, v[32:35] offset:128
	s_waitcnt lgkmcnt(7)
	v_add_f32_e32 v36, v180, v36
	v_add_f32_e32 v37, v181, v37
	v_add_f32_e32 v38, v182, v38
	v_add_f32_e32 v39, v183, v39
	v_fmac_f32_e32 v206, v36, v36
	v_fmac_f32_e32 v206, v37, v37
	v_fmac_f32_e32 v206, v38, v38
	v_fmac_f32_e32 v206, v39, v39
	ds_write_b128 v192, v[36:39] offset:160
	s_waitcnt lgkmcnt(7)
	v_add_f32_e32 v40, v184, v40
	v_add_f32_e32 v41, v185, v41
	v_add_f32_e32 v42, v186, v42
	v_add_f32_e32 v43, v187, v43
	v_fmac_f32_e32 v206, v40, v40
	v_fmac_f32_e32 v206, v41, v41
	v_fmac_f32_e32 v206, v42, v42
	v_fmac_f32_e32 v206, v43, v43
	ds_write_b128 v192, v[40:43] offset:192
	s_waitcnt lgkmcnt(7)
	v_add_f32_e32 v44, v188, v44
	v_add_f32_e32 v45, v189, v45
	v_add_f32_e32 v46, v190, v46
	v_add_f32_e32 v47, v191, v47
	v_fmac_f32_e32 v206, v44, v44
	v_fmac_f32_e32 v206, v45, v45
	v_fmac_f32_e32 v206, v46, v46
	v_fmac_f32_e32 v206, v47, v47
	ds_write_b128 v192, v[44:47] offset:224
	ds_read_b128 v[160:163], v200
	ds_read_b128 v[164:167], v200 offset:1088
	ds_read_b128 v[168:171], v200 offset:2176
	ds_read_b128 v[172:175], v200 offset:3264
	ds_read_b128 v[176:179], v200 offset:4352
	ds_read_b128 v[180:183], v200 offset:5440
	ds_read_b128 v[184:187], v200 offset:6528
	ds_read_b128 v[188:191], v200 offset:7616
	s_add_u32 s74, s66, 0x20000
	s_addc_u32 s75, s67, 0
	s_waitcnt lgkmcnt(7)
	global_store_dwordx4 v202, v[160:163], s[74:75]
	s_add_u32 s74, s66, 0x24000
	s_addc_u32 s75, s67, 0
	s_waitcnt lgkmcnt(6)
	global_store_dwordx4 v202, v[164:167], s[74:75]
	s_add_u32 s74, s66, 0x28000
	s_addc_u32 s75, s67, 0
	s_waitcnt lgkmcnt(5)
	global_store_dwordx4 v202, v[168:171], s[74:75]
	s_add_u32 s74, s66, 0x2c000
	s_addc_u32 s75, s67, 0
	s_waitcnt lgkmcnt(4)
	global_store_dwordx4 v202, v[172:175], s[74:75]
	s_add_u32 s74, s66, 0x30000
	s_addc_u32 s75, s67, 0
	s_waitcnt lgkmcnt(3)
	global_store_dwordx4 v202, v[176:179], s[74:75]
	s_add_u32 s74, s66, 0x34000
	s_addc_u32 s75, s67, 0
	s_waitcnt lgkmcnt(2)
	global_store_dwordx4 v202, v[180:183], s[74:75]
	s_add_u32 s74, s66, 0x38000
	s_addc_u32 s75, s67, 0
	s_waitcnt lgkmcnt(1)
	global_store_dwordx4 v202, v[184:187], s[74:75]
	s_add_u32 s74, s66, 0x3c000
	s_addc_u32 s75, s67, 0
	s_waitcnt lgkmcnt(0)
; DI bfr f2bf(float a) { return (bfr)(pack2(a, 0.f) & 0xffffu); }
; DI int crow(int reg, int h) { return (reg & 3) + 8 * (reg >> 2) + 4 * h; }
; template <bool FIRST, bool HAS_H>
; DI void phase_gemm_resid(const Params& p, const bfr* A, const bfr* Wt, const float* gnext, float* ss, char* smem) {
;     ...
;         for (int jh = 0; jh < 2; ++jh) {
;           float xo[2][8];
; #pragma unroll
;           for (int jj = 0; jj < 2; ++jj)
; #pragma unroll
;             for (int q = 0; q < 8; ++q)
;               xo[jj][q] = xsrc[(rbase + i * 32 + crow(qh * 8 + q, 0)) * 1024 + cbase + (jh * 2 + jj) * 32];
; #pragma unroll
;           for (int q = 0; q < 8; ++q) {
;             const int o = (rbase + i * 32 + crow(qh * 8 + q, 0)) * 1024 + cbase;
; #pragma unroll
;             for (int jj = 0; jj < 2; ++jj) {
;               const int j = jh * 2 + jj;
;               const float xn = xo[jj][q] + acc[i][j][qh * 8 + q];
;               X[o + j * 32] = xn;
;               if (HAS_H) Hn[o + j * 32] = f2bf(xn * gnext[cbase + j * 32]);
;               rs[q] += xn * xn;
;             }
;           }
;         }
	global_store_dwordx4 v202, v[188:191], s[74:75]
	global_load_dwordx4 v[160:163], v204, s[70:71]
	global_load_dwordx4 v[164:167], v204, s[70:71] offset:32
	global_load_dwordx4 v[168:171], v204, s[70:71] offset:64
	global_load_dwordx4 v[172:175], v204, s[70:71] offset:96
	global_load_dwordx4 v[176:179], v204, s[70:71] offset:128
	global_load_dwordx4 v[180:183], v204, s[70:71] offset:160
	global_load_dwordx4 v[184:187], v204, s[70:71] offset:192
	global_load_dwordx4 v[188:191], v204, s[70:71] offset:224
	s_waitcnt vmcnt(7)
	v_mul_f32_e32 v48, v160, v48
	v_mul_f32_e32 v49, v161, v49
	v_mul_f32_e32 v50, v162, v50
	v_mul_f32_e32 v51, v163, v51
	v_cvt_pk_bf16_f32 v48, v48, v49
	v_cvt_pk_bf16_f32 v49, v50, v51
	ds_write_b64 v194, v[48:49]
	s_waitcnt vmcnt(6)
	v_mul_f32_e32 v52, v164, v52
	v_mul_f32_e32 v53, v165, v53
	v_mul_f32_e32 v54, v166, v54
	v_mul_f32_e32 v55, v167, v55
	v_cvt_pk_bf16_f32 v52, v52, v53
	v_cvt_pk_bf16_f32 v53, v54, v55
	ds_write_b64 v194, v[52:53] offset:16
	s_waitcnt vmcnt(5)
	v_mul_f32_e32 v56, v168, v56
	v_mul_f32_e32 v57, v169, v57
	v_mul_f32_e32 v58, v170, v58
	v_mul_f32_e32 v59, v171, v59
	v_cvt_pk_bf16_f32 v56, v56, v57
	v_cvt_pk_bf16_f32 v57, v58, v59
	ds_write_b64 v194, v[56:57] offset:32
	s_waitcnt vmcnt(4)
	v_mul_f32_e32 v60, v172, v60
	v_mul_f32_e32 v61, v173, v61
	v_mul_f32_e32 v62, v174, v62
	v_mul_f32_e32 v63, v175, v63
	v_cvt_pk_bf16_f32 v60, v60, v61
	v_cvt_pk_bf16_f32 v61, v62, v63
	ds_write_b64 v194, v[60:61] offset:48
	s_waitcnt vmcnt(3)
	v_mul_f32_e32 v32, v176, v32
	v_mul_f32_e32 v33, v177, v33
	v_mul_f32_e32 v34, v178, v34
	v_mul_f32_e32 v35, v179, v35
	v_cvt_pk_bf16_f32 v32, v32, v33
	v_cvt_pk_bf16_f32 v33, v34, v35
	ds_write_b64 v194, v[32:33] offset:64
	s_waitcnt vmcnt(2)
	v_mul_f32_e32 v36, v180, v36
	v_mul_f32_e32 v37, v181, v37
	v_mul_f32_e32 v38, v182, v38
	v_mul_f32_e32 v39, v183, v39
	v_cvt_pk_bf16_f32 v36, v36, v37
	v_cvt_pk_bf16_f32 v37, v38, v39
	ds_write_b64 v194, v[36:37] offset:80
	s_waitcnt vmcnt(1)
	v_mul_f32_e32 v40, v184, v40
	v_mul_f32_e32 v41, v185, v41
	v_mul_f32_e32 v42, v186, v42
	v_mul_f32_e32 v43, v187, v43
	v_cvt_pk_bf16_f32 v40, v40, v41
	v_cvt_pk_bf16_f32 v41, v42, v43
	ds_write_b64 v194, v[40:41] offset:96
	s_waitcnt vmcnt(0)
	v_mul_f32_e32 v44, v188, v44
	v_mul_f32_e32 v45, v189, v45
	v_mul_f32_e32 v46, v190, v46
	v_mul_f32_e32 v47, v191, v47
	v_cvt_pk_bf16_f32 v44, v44, v45
	v_cvt_pk_bf16_f32 v45, v46, v47
	ds_write_b64 v194, v[44:45] offset:112
	ds_read_b128 v[160:163], v201
	ds_read_b128 v[164:167], v201 offset:2176
	ds_read_b128 v[168:171], v201 offset:4352
	ds_read_b128 v[172:175], v201 offset:6528
	s_add_u32 s74, s68, 0x10000
	s_addc_u32 s75, s69, 0
	s_waitcnt lgkmcnt(3)
	global_store_dwordx4 v203, v[160:163], s[74:75]
	s_add_u32 s74, s68, 0x14000
	s_addc_u32 s75, s69, 0
	s_waitcnt lgkmcnt(2)
	global_store_dwordx4 v203, v[164:167], s[74:75]
	s_add_u32 s74, s68, 0x18000
	s_addc_u32 s75, s69, 0
	s_waitcnt lgkmcnt(1)
	global_store_dwordx4 v203, v[168:171], s[74:75]
	s_add_u32 s74, s68, 0x1c000
	s_addc_u32 s75, s69, 0
	s_waitcnt lgkmcnt(0)
	global_store_dwordx4 v203, v[172:175], s[74:75]
	s_waitcnt vmcnt(4)
	ds_write_b128 v200, v[128:131]
	s_waitcnt vmcnt(4)
	ds_write_b128 v200, v[132:135] offset:1088
	s_waitcnt vmcnt(4)
	ds_write_b128 v200, v[136:139] offset:2176
	s_waitcnt vmcnt(4)
	ds_write_b128 v200, v[140:143] offset:3264
	s_waitcnt vmcnt(4)
	ds_write_b128 v200, v[144:147] offset:4352
	s_waitcnt vmcnt(4)
	ds_write_b128 v200, v[148:151] offset:5440
	s_waitcnt vmcnt(4)
	ds_write_b128 v200, v[152:155] offset:6528
	s_waitcnt vmcnt(4)
	ds_write_b128 v200, v[156:159] offset:7616
	ds_read_b128 v[160:163], v192
	ds_read_b128 v[164:167], v192 offset:32
	ds_read_b128 v[168:171], v192 offset:64
	ds_read_b128 v[172:175], v192 offset:96
	ds_read_b128 v[176:179], v192 offset:128
	ds_read_b128 v[180:183], v192 offset:160
	ds_read_b128 v[184:187], v192 offset:192
	ds_read_b128 v[188:191], v192 offset:224
	s_waitcnt lgkmcnt(7)
	v_add_f32_e32 v16, v160, v16
	v_add_f32_e32 v17, v161, v17
	v_add_f32_e32 v18, v162, v18
	v_add_f32_e32 v19, v163, v19
	v_fmac_f32_e32 v206, v16, v16
	v_fmac_f32_e32 v206, v17, v17
	v_fmac_f32_e32 v206, v18, v18
	v_fmac_f32_e32 v206, v19, v19
	ds_write_b128 v192, v[16:19]
	s_waitcnt lgkmcnt(7)
	v_add_f32_e32 v20, v164, v20
	v_add_f32_e32 v21, v165, v21
	v_add_f32_e32 v22, v166, v22
	v_add_f32_e32 v23, v167, v23
	v_fmac_f32_e32 v206, v20, v20
	v_fmac_f32_e32 v206, v21, v21
	v_fmac_f32_e32 v206, v22, v22
	v_fmac_f32_e32 v206, v23, v23
	ds_write_b128 v192, v[20:23] offset:32
	s_waitcnt lgkmcnt(7)
	v_add_f32_e32 v24, v168, v24
	v_add_f32_e32 v25, v169, v25
	v_add_f32_e32 v26, v170, v26
	v_add_f32_e32 v27, v171, v27
	v_fmac_f32_e32 v206, v24, v24
	v_fmac_f32_e32 v206, v25, v25
	v_fmac_f32_e32 v206, v26, v26
	v_fmac_f32_e32 v206, v27, v27
	ds_write_b128 v192, v[24:27] offset:64
	s_waitcnt lgkmcnt(7)
	v_add_f32_e32 v28, v172, v28
	v_add_f32_e32 v29, v173, v29
	v_add_f32_e32 v30, v174, v30
	v_add_f32_e32 v31, v175, v31
	v_fmac_f32_e32 v206, v28, v28
	v_fmac_f32_e32 v206, v29, v29
	v_fmac_f32_e32 v206, v30, v30
	v_fmac_f32_e32 v206, v31, v31
	ds_write_b128 v192, v[28:31] offset:96
	s_waitcnt lgkmcnt(7)
	v_add_f32_e32 v0, v176, v0
	v_add_f32_e32 v1, v177, v1
	v_add_f32_e32 v2, v178, v2
	v_add_f32_e32 v3, v179, v3
	v_fmac_f32_e32 v206, v0, v0
	v_fmac_f32_e32 v206, v1, v1
	v_fmac_f32_e32 v206, v2, v2
	v_fmac_f32_e32 v206, v3, v3
	ds_write_b128 v192, v[0:3] offset:128
	s_waitcnt lgkmcnt(7)
	v_add_f32_e32 v4, v180, v4
	v_add_f32_e32 v5, v181, v5
	v_add_f32_e32 v6, v182, v6
	v_add_f32_e32 v7, v183, v7
	v_fmac_f32_e32 v206, v4, v4
	v_fmac_f32_e32 v206, v5, v5
	v_fmac_f32_e32 v206, v6, v6
	v_fmac_f32_e32 v206, v7, v7
	ds_write_b128 v192, v[4:7] offset:160
	s_waitcnt lgkmcnt(7)
; DI bfr f2bf(float a) { return (bfr)(pack2(a, 0.f) & 0xffffu); }
; DI int crow(int reg, int h) { return (reg & 3) + 8 * (reg >> 2) + 4 * h; }
; template <bool FIRST, bool HAS_H>
; DI void phase_gemm_resid(const Params& p, const bfr* A, const bfr* Wt, const float* gnext, float* ss, char* smem) {
;     ...
;                       [=](int row, float s2) { unsafeAtomicAdd(ss + row, s2); });
;     ...
;           for (int q = 0; q < 8; ++q) {
;             const int o = (rbase + i * 32 + crow(qh * 8 + q, 0)) * 1024 + cbase;
; #pragma unroll
;             for (int jj = 0; jj < 2; ++jj) {
;               const int j = jh * 2 + jj;
;               const float xn = xo[jj][q] + acc[i][j][qh * 8 + q];
;               X[o + j * 32] = xn;
;               if (HAS_H) Hn[o + j * 32] = f2bf(xn * gnext[cbase + j * 32]);
;               rs[q] += xn * xn;
;             }
;           }
;         }
; #pragma unroll
;         for (int q = 0; q < 8; ++q) rs[q] = half32_sum_hi(rs[q]);
;         if (r == 31) {
; #pragma unroll
;           for (int q = 0; q < 8; ++q) unsafeAtomicAdd(ss + rbase + i * 32 + crow(qh * 8 + q, 0), rs[q]);
;         }
	v_add_f32_e32 v8, v184, v8
	v_add_f32_e32 v9, v185, v9
	v_add_f32_e32 v10, v186, v10
	v_add_f32_e32 v11, v187, v11
	v_fmac_f32_e32 v206, v8, v8
	v_fmac_f32_e32 v206, v9, v9
	v_fmac_f32_e32 v206, v10, v10
	v_fmac_f32_e32 v206, v11, v11
	ds_write_b128 v192, v[8:11] offset:192
	s_waitcnt lgkmcnt(7)
	v_add_f32_e32 v12, v188, v12
	v_add_f32_e32 v13, v189, v13
	v_add_f32_e32 v14, v190, v14
	v_add_f32_e32 v15, v191, v15
	v_fmac_f32_e32 v206, v12, v12
	v_fmac_f32_e32 v206, v13, v13
	v_fmac_f32_e32 v206, v14, v14
	v_fmac_f32_e32 v206, v15, v15
	ds_write_b128 v192, v[12:15] offset:224
	ds_read_b128 v[160:163], v200
	ds_read_b128 v[164:167], v200 offset:1088
	ds_read_b128 v[168:171], v200 offset:2176
	ds_read_b128 v[172:175], v200 offset:3264
	ds_read_b128 v[176:179], v200 offset:4352
	ds_read_b128 v[180:183], v200 offset:5440
	ds_read_b128 v[184:187], v200 offset:6528
	ds_read_b128 v[188:191], v200 offset:7616
	s_add_u32 s74, s66, 0x20100
	s_addc_u32 s75, s67, 0
	s_waitcnt lgkmcnt(7)
	global_store_dwordx4 v202, v[160:163], s[74:75]
	s_add_u32 s74, s66, 0x24100
	s_addc_u32 s75, s67, 0
	s_waitcnt lgkmcnt(6)
	global_store_dwordx4 v202, v[164:167], s[74:75]
	s_add_u32 s74, s66, 0x28100
	s_addc_u32 s75, s67, 0
	s_waitcnt lgkmcnt(5)
	global_store_dwordx4 v202, v[168:171], s[74:75]
	s_add_u32 s74, s66, 0x2c100
	s_addc_u32 s75, s67, 0
	s_waitcnt lgkmcnt(4)
	global_store_dwordx4 v202, v[172:175], s[74:75]
	s_add_u32 s74, s66, 0x30100
	s_addc_u32 s75, s67, 0
	s_waitcnt lgkmcnt(3)
	global_store_dwordx4 v202, v[176:179], s[74:75]
	s_add_u32 s74, s66, 0x34100
	s_addc_u32 s75, s67, 0
	s_waitcnt lgkmcnt(2)
	global_store_dwordx4 v202, v[180:183], s[74:75]
	s_add_u32 s74, s66, 0x38100
	s_addc_u32 s75, s67, 0
	s_waitcnt lgkmcnt(1)
	global_store_dwordx4 v202, v[184:187], s[74:75]
	s_add_u32 s74, s66, 0x3c100
	s_addc_u32 s75, s67, 0
	s_waitcnt lgkmcnt(0)
	global_store_dwordx4 v202, v[188:191], s[74:75]
	global_load_dwordx4 v[160:163], v204, s[70:71] offset:256
	global_load_dwordx4 v[164:167], v204, s[70:71] offset:288
	global_load_dwordx4 v[168:171], v204, s[70:71] offset:320
	global_load_dwordx4 v[172:175], v204, s[70:71] offset:352
	global_load_dwordx4 v[176:179], v204, s[70:71] offset:384
	global_load_dwordx4 v[180:183], v204, s[70:71] offset:416
	global_load_dwordx4 v[184:187], v204, s[70:71] offset:448
	global_load_dwordx4 v[188:191], v204, s[70:71] offset:480
	s_waitcnt vmcnt(7)
	v_mul_f32_e32 v16, v160, v16
	v_mul_f32_e32 v17, v161, v17
	v_mul_f32_e32 v18, v162, v18
	v_mul_f32_e32 v19, v163, v19
	v_cvt_pk_bf16_f32 v16, v16, v17
	v_cvt_pk_bf16_f32 v17, v18, v19
	ds_write_b64 v194, v[16:17]
	s_waitcnt vmcnt(6)
	v_mul_f32_e32 v20, v164, v20
	v_mul_f32_e32 v21, v165, v21
	v_mul_f32_e32 v22, v166, v22
	v_mul_f32_e32 v23, v167, v23
	v_cvt_pk_bf16_f32 v20, v20, v21
	v_cvt_pk_bf16_f32 v21, v22, v23
	ds_write_b64 v194, v[20:21] offset:16
	s_waitcnt vmcnt(5)
	v_mul_f32_e32 v24, v168, v24
	v_mul_f32_e32 v25, v169, v25
	v_mul_f32_e32 v26, v170, v26
	v_mul_f32_e32 v27, v171, v27
	v_cvt_pk_bf16_f32 v24, v24, v25
	v_cvt_pk_bf16_f32 v25, v26, v27
	ds_write_b64 v194, v[24:25] offset:32
	s_waitcnt vmcnt(4)
	v_mul_f32_e32 v28, v172, v28
	v_mul_f32_e32 v29, v173, v29
	v_mul_f32_e32 v30, v174, v30
	v_mul_f32_e32 v31, v175, v31
	v_cvt_pk_bf16_f32 v28, v28, v29
	v_cvt_pk_bf16_f32 v29, v30, v31
	ds_write_b64 v194, v[28:29] offset:48
	s_waitcnt vmcnt(3)
	v_mul_f32_e32 v0, v176, v0
	v_mul_f32_e32 v1, v177, v1
	v_mul_f32_e32 v2, v178, v2
	v_mul_f32_e32 v3, v179, v3
	v_cvt_pk_bf16_f32 v0, v0, v1
	v_cvt_pk_bf16_f32 v1, v2, v3
	ds_write_b64 v194, v[0:1] offset:64
	s_waitcnt vmcnt(2)
	v_mul_f32_e32 v4, v180, v4
	v_mul_f32_e32 v5, v181, v5
	v_mul_f32_e32 v6, v182, v6
	v_mul_f32_e32 v7, v183, v7
	v_cvt_pk_bf16_f32 v4, v4, v5
	v_cvt_pk_bf16_f32 v5, v6, v7
	ds_write_b64 v194, v[4:5] offset:80
	s_waitcnt vmcnt(1)
	v_mul_f32_e32 v8, v184, v8
	v_mul_f32_e32 v9, v185, v9
	v_mul_f32_e32 v10, v186, v10
	v_mul_f32_e32 v11, v187, v11
	v_cvt_pk_bf16_f32 v8, v8, v9
	v_cvt_pk_bf16_f32 v9, v10, v11
	ds_write_b64 v194, v[8:9] offset:96
	s_waitcnt vmcnt(0)
	v_mul_f32_e32 v12, v188, v12
	v_mul_f32_e32 v13, v189, v13
	v_mul_f32_e32 v14, v190, v14
	v_mul_f32_e32 v15, v191, v15
	v_cvt_pk_bf16_f32 v12, v12, v13
	v_cvt_pk_bf16_f32 v13, v14, v15
	ds_write_b64 v194, v[12:13] offset:112
	ds_read_b128 v[160:163], v201
	ds_read_b128 v[164:167], v201 offset:2176
	ds_read_b128 v[168:171], v201 offset:4352
	ds_read_b128 v[172:175], v201 offset:6528
	s_add_u32 s74, s68, 0x10080
	s_addc_u32 s75, s69, 0
	s_waitcnt lgkmcnt(3)
	global_store_dwordx4 v203, v[160:163], s[74:75]
	s_add_u32 s74, s68, 0x14080
	s_addc_u32 s75, s69, 0
	s_waitcnt lgkmcnt(2)
	global_store_dwordx4 v203, v[164:167], s[74:75]
	s_add_u32 s74, s68, 0x18080
	s_addc_u32 s75, s69, 0
	s_waitcnt lgkmcnt(1)
	global_store_dwordx4 v203, v[168:171], s[74:75]
	s_add_u32 s74, s68, 0x1c080
	s_addc_u32 s75, s69, 0
	s_waitcnt lgkmcnt(0)
	global_store_dwordx4 v203, v[172:175], s[74:75]
	s_load_dwordx2 s[64:65], s[92:93], 0x140
	ds_bpermute_b32 v210, v208, v205
	ds_bpermute_b32 v211, v208, v206
	s_waitcnt lgkmcnt(0)
	s_add_u32 s64, s64, 0x20400
	s_addc_u32 s65, s65, 0
	v_add_f32_e32 v210, v210, v205
	v_add_f32_e32 v211, v211, v206
	s_mov_b32 exec_hi, 0
	s_nop 1
	global_atomic_add_f32 v207, v210, s[64:65]
	global_atomic_add_f32 v207, v211, s[64:65] offset:128
	s_mov_b64 exec, -1
	v_readlane_b32 s64, v209, 0
	v_readlane_b32 s65, v209, 1
	v_readlane_b32 s66, v209, 2
	v_readlane_b32 s67, v209, 3
	v_readlane_b32 s68, v209, 4
	v_readlane_b32 s69, v209, 5
	v_readlane_b32 s70, v209, 6
	v_readlane_b32 s71, v209, 7
	v_readlane_b32 s72, v209, 8
	v_readlane_b32 s73, v209, 9
	v_readlane_b32 s74, v209, 10
	v_readlane_b32 s75, v209, 11
	v_readlane_b32 s76, v209, 12
	v_readlane_b32 s77, v209, 13
	v_readlane_b32 s78, v209, 14
	v_readlane_b32 s79, v209, 15
	s_nop 7
	s_branch .LBB0_1463

; #define GA_LOAD(pr_) do { _Pragma("unroll") for (int i = 0; i < 4; ++i) ra[i] = *(const u32x4*)(Ab + (i * 32) * lda + (pr_) * 64); } while (0)
; #define GB_LOAD(kt_) do { const bfr* bk_ = Bb + (kt_) * NB * 32; \
;     _Pragma("unroll") for (int i = 0; i < 4; ++i) rb[i] = *(const u32x4*)(bk_ + (i * 64) * 32); } while (0)
; #define G_STORE(kt_) do { bfr* as_ = S0 + ((kt_) & 1) * GSTAGE; bfr* bs_ = as_ + 128 * 40; \
;     if (apar == ((kt_) & 1)) { _Pragma("unroll") for (int i = 0; i < 4; ++i) *(u32x4*)(as_ + asoff + i * 32 * 40) = ra[i]; } \
;     _Pragma("unroll") for (int i = 0; i < 4; ++i) *(u32x4*)(bs_ + bsoff + i * 64 * 40) = rb[i]; } while (0)
; template <int lda>
; DI void gemm_mainloop(const bfr* __restrict__ A, const bfr* __restrict__ Bt, int NB, int K, int m0, int n0, char* smem, f32x16 (&acc)[2][4]) {
;     ...
;   const int nk = K >> 5;
;   const int arow = tid >> 3, ac8 = tid & 7, apar = ac8 >> 2;
;   const bfr* Ab = A + (m0 + arow) * lda + ac8 * 8;
;   const int asoff = arow * 40 + (ac8 & 3) * 8;
;   const int brow = tid >> 2, bc4 = tid & 3;
;   const bfr* Bb = Bt + (n0 + brow) * 32 + bc4 * 8;
;   const int bsoff = brow * 40 + bc4 * 8;
;     ...
;   GA_LOAD(0);
;   GB_LOAD(0);
;   G_STORE(0);
;   GB_LOAD(1);
;   __syncthreads();
; template <bool FIRST, bool HAS_H>
; DI void phase_gemm_resid(const Params& p, const bfr* A, const bfr* Wt, const float* gnext, float* ss, char* smem) {
;     ...
;   for (int t0 = blockIdx.x; t0 < 128 * 4; t0 += gridDim.x) {
;     const int t = ((gridDim.x & 7) == 0) ? xcd_tile(t0, 4) : t0;
;     const int mt = t >> 2, nt = t & 3, m0 = mt * 128, n0 = nt * 256;
;     f32x16 acc[2][4];
;     gemm_mainloop<1024>(A, Wt, 1024, 1024, m0, n0, smem, acc);
.LBB0_1721:
	s_lshl_b32 s5, s4, 5
	s_and_b32 s59, s5, 0xffffff80
	s_lshl_b32 s4, s4, 8
	s_and_b32 s58, s4, 0x300
	s_mov_b32 s60, 0
	s_mov_b64 s[16:17], 0
	s_lshl_b32 s98, s59, 11
	s_add_u32 s98, s6, s98
	s_addc_u32 s99, s7, 0
	s_lshl_b32 s100, s58, 6
	s_add_u32 s100, s2, s100
	s_addc_u32 s101, s3, 0
	v_writelane_b32 v209, s64, 0
	v_writelane_b32 v209, s65, 1
	v_writelane_b32 v209, s66, 2
	v_writelane_b32 v209, s67, 3
	v_writelane_b32 v209, s68, 4
	v_writelane_b32 v209, s69, 5
	v_writelane_b32 v209, s70, 6
	v_writelane_b32 v209, s71, 7
	v_writelane_b32 v209, s72, 8
	v_writelane_b32 v209, s73, 9
	v_writelane_b32 v209, s74, 10
	v_writelane_b32 v209, s75, 11
	v_writelane_b32 v209, s76, 12
	v_writelane_b32 v209, s77, 13
	v_writelane_b32 v209, s78, 14
	v_writelane_b32 v209, s79, 15
	s_mov_b32 s77, s59
	s_mov_b32 s78, s58
	v_lshrrev_b32_e32 v210, 6, v196
	v_and_b32_e32 v211, 63, v196
	v_readfirstlane_b32 s73, v210
	v_lshrrev_b32_e32 v212, 2, v211
	v_bfe_u32 v213, v211, 4, 2
	v_and_b32_e32 v210, 3, v211
	v_xor_b32_e32 v210, v210, v213
	v_lshlrev_b32_e32 v210, 4, v210
	v_lshl_add_u32 v180, v212, 11, v210
	v_add_u32_e32 v182, 0x8000, v180
	v_lshl_add_u32 v183, v212, 6, v210
	v_and_b32_e32 v212, 31, v211
	v_lshrrev_b32_e32 v213, 5, v211
	v_bfe_u32 v210, v211, 2, 2
	v_xor_b32_e32 v210, v210, v213
	v_lshlrev_b32_e32 v210, 4, v210
	v_lshl_add_u32 v192, v212, 6, v210
	s_lshr_b32 s74, s73, 1
	s_lshl_b32 s74, s74, 12
	s_and_b32 s75, s73, 1
	s_lshl_b32 s75, s75, 13
	v_add_u32_e32 v194, s75, v192
	v_add_u32_e32 v192, s74, v192
	v_xor_b32_e32 v204, 32, v194
	v_xor_b32_e32 v193, 32, v192
	s_lshl_b32 s74, s73, 16
	s_add_u32 s64, s98, s74
	s_addc_u32 s65, s99, 0
	s_lshl_b32 s74, s73, 12
	s_add_u32 s66, s100, s74
	s_addc_u32 s67, s101, 0
	s_lshl_b32 s68, s73, 11
	s_lshl_b32 s69, s73, 12
	s_mov_b32 s70, 0
	s_mov_b32 s71, 0
	s_mov_b32 s72, 0
	s_waitcnt lgkmcnt(0)
	s_barrier
	s_mul_i32 s74, s70, 0x6000
	s_add_u32 s75, s74, s68
	s_mov_b32 m0, s75
	s_add_u32 s76, s74, 0x2000
	s_cmp_eq_u32 s70, 2
	s_cselect_b32 s76, 0x10000, s76
	global_load_lds_dwordx4 v180, s[64:65]
	s_add_u32 m0, s75, 0x400
	s_add_u32 s76, s76, s69
	global_load_lds_dwordx4 v182, s[64:65]
	s_mov_b32 m0, s76
	s_add_u32 s64, s64, 64
	s_addc_u32 s65, s65, 0
	global_load_lds_dwordx4 v183, s[66:67]
	global_load_lds_dwordx4 v183, s[66:67] offset:1024
	global_load_lds_dwordx4 v183, s[66:67] offset:2048
	global_load_lds_dwordx4 v183, s[66:67] offset:3072
	s_add_u32 s66, s66, 0x10000
	s_addc_u32 s67, s67, 0
	s_add_u32 s70, s70, 1
	s_cmp_eq_u32 s70, 3
	s_cselect_b32 s70, 0, s70
	s_mul_i32 s74, s70, 0x6000
	s_add_u32 s75, s74, s68
	s_mov_b32 m0, s75
	s_add_u32 s76, s74, 0x2000
	s_cmp_eq_u32 s70, 2
	s_cselect_b32 s76, 0x10000, s76
	global_load_lds_dwordx4 v180, s[64:65]
	s_add_u32 m0, s75, 0x400
	s_add_u32 s76, s76, s69
	global_load_lds_dwordx4 v182, s[64:65]
	s_mov_b32 m0, s76
	s_add_u32 s64, s64, 64
	s_addc_u32 s65, s65, 0
	global_load_lds_dwordx4 v183, s[66:67]
	global_load_lds_dwordx4 v183, s[66:67] offset:1024
	global_load_lds_dwordx4 v183, s[66:67] offset:2048
	global_load_lds_dwordx4 v183, s[66:67] offset:3072
	s_add_u32 s66, s66, 0x10000
	s_addc_u32 s67, s67, 0
	s_add_u32 s70, s70, 1
	s_cmp_eq_u32 s70, 3
	s_cselect_b32 s70, 0, s70
	s_cmp_lt_u32 s46, 0x100
	s_cbranch_scc1 .Lp19_nostag
	s_sleep 8

; #define MFMA32(a, b, c) __builtin_amdgcn_mfma_f32_32x32x16_bf16((a), (b), (c), 0, 0, 0)
; #define GA_LOAD(pr_) do { _Pragma("unroll") for (int i = 0; i < 4; ++i) ra[i] = *(const u32x4*)(Ab + (i * 32) * lda + (pr_) * 64); } while (0)
; #define GB_LOAD(kt_) do { const bfr* bk_ = Bb + (kt_) * NB * 32; \
;     _Pragma("unroll") for (int i = 0; i < 4; ++i) rb[i] = *(const u32x4*)(bk_ + (i * 64) * 32); } while (0)
; #define G_STORE(kt_) do { bfr* as_ = S0 + ((kt_) & 1) * GSTAGE; bfr* bs_ = as_ + 128 * 40; \
;     if (apar == ((kt_) & 1)) { _Pragma("unroll") for (int i = 0; i < 4; ++i) *(u32x4*)(as_ + asoff + i * 32 * 40) = ra[i]; } \
;     _Pragma("unroll") for (int i = 0; i < 4; ++i) *(u32x4*)(bs_ + bsoff + i * 64 * 40) = rb[i]; } while (0)
; template <int lda>
; DI void gemm_mainloop(const bfr* __restrict__ A, const bfr* __restrict__ Bt, int NB, int K, int m0, int n0, char* smem, f32x16 (&acc)[2][4]) {
;     ...
;   for (int kt = 0; kt < nk; ++kt) {
;     if (kt + 1 < nk) G_STORE(kt + 1);
;     if (kt + 2 < nk) {
;       GB_LOAD(kt + 2);
;       if ((kt & 1) == 0) GA_LOAD((kt >> 1) + 1);
;     }
;     const bfr* As = S0 + (kt & 1) * GSTAGE;
;     const bfr* Bs = As + 128 * 40;
; #pragma unroll
;     for (int ks = 0; ks < 2; ++ks) {
;       bf16x8 af[2], bfg[4];
; #pragma unroll
;       for (int i = 0; i < 2; ++i) af[i] = *(const bf16x8*)(As + (wr * 64 + i * 32 + r) * 40 + ks * 16 + hl * 8);
; #pragma unroll
;       for (int j = 0; j < 4; ++j) bfg[j] = *(const bf16x8*)(Bs + (wc * 128 + j * 32 + r) * 40 + ks * 16 + hl * 8);
; #pragma unroll
;       for (int i = 0; i < 2; ++i)
; #pragma unroll
;         for (int j = 0; j < 4; ++j) acc[i][j] = MFMA32(af[i], bfg[j], acc[i][j]);
;     }
;     __syncthreads();
;   }
.Lp19_loop:
	s_waitcnt vmcnt(6)
	s_barrier
	s_mul_i32 s74, s71, 0x6000
	s_add_u32 s75, s74, 0x2000
	s_cmp_eq_u32 s71, 2
	s_cselect_b32 s75, 0x10000, s75
	v_add_u32_e32 v205, s74, v192
	v_add_u32_e32 v207, s75, v194
	v_add_u32_e32 v206, s74, v193
	v_add_u32_e32 v208, s75, v204
	ds_read_b128 v[128:131], v205
	ds_read_b128 v[144:147], v207
	ds_read_b128 v[148:151], v207 offset:2048
	ds_read_b128 v[152:155], v207 offset:4096
	ds_read_b128 v[156:159], v207 offset:6144
	ds_read_b128 v[132:135], v205 offset:2048
	ds_read_b128 v[136:139], v206
	ds_read_b128 v[160:163], v208
	ds_read_b128 v[164:167], v208 offset:2048
	ds_read_b128 v[168:171], v208 offset:4096
	ds_read_b128 v[172:175], v208 offset:6144
	ds_read_b128 v[140:143], v206 offset:2048
	s_add_u32 s71, s71, 1
	s_cmp_eq_u32 s71, 3
	s_cselect_b32 s71, 0, s71
	s_waitcnt lgkmcnt(10)
	v_mfma_f32_32x32x16_bf16 v[112:127], v[144:147], v[128:131], v[112:127]
	s_mul_i32 s74, s70, 0x6000
	s_add_u32 s75, s74, s68
	s_mov_b32 m0, s75
	s_add_u32 s76, s74, 0x2000
	s_cmp_eq_u32 s70, 2
	s_cselect_b32 s76, 0x10000, s76
	global_load_lds_dwordx4 v180, s[64:65]
	s_waitcnt lgkmcnt(9)
	v_mfma_f32_32x32x16_bf16 v[96:111], v[148:151], v[128:131], v[96:111]
	s_add_u32 m0, s75, 0x400
	s_add_u32 s76, s76, s69
	global_load_lds_dwordx4 v182, s[64:65]
	s_waitcnt lgkmcnt(8)
	v_mfma_f32_32x32x16_bf16 v[80:95], v[152:155], v[128:131], v[80:95]
	s_mov_b32 m0, s76
	s_add_u32 s64, s64, 64
	s_addc_u32 s65, s65, 0
	global_load_lds_dwordx4 v183, s[66:67]
	s_waitcnt lgkmcnt(7)
	v_mfma_f32_32x32x16_bf16 v[64:79], v[156:159], v[128:131], v[64:79]
	global_load_lds_dwordx4 v183, s[66:67] offset:1024
	s_waitcnt lgkmcnt(6)
	v_mfma_f32_32x32x16_bf16 v[48:63], v[144:147], v[132:135], v[48:63]
	global_load_lds_dwordx4 v183, s[66:67] offset:2048
	v_mfma_f32_32x32x16_bf16 v[32:47], v[148:151], v[132:135], v[32:47]
	global_load_lds_dwordx4 v183, s[66:67] offset:3072
	s_add_u32 s66, s66, 0x10000
	s_addc_u32 s67, s67, 0
	v_mfma_f32_32x32x16_bf16 v[16:31], v[152:155], v[132:135], v[16:31]
	s_add_u32 s70, s70, 1
	s_cmp_eq_u32 s70, 3
	s_cselect_b32 s70, 0, s70
	v_mfma_f32_32x32x16_bf16 v[0:15], v[156:159], v[132:135], v[0:15]
	s_waitcnt lgkmcnt(4)
	v_mfma_f32_32x32x16_bf16 v[112:127], v[160:163], v[136:139], v[112:127]
	s_waitcnt lgkmcnt(3)
	v_mfma_f32_32x32x16_bf16 v[96:111], v[164:167], v[136:139], v[96:111]
	s_waitcnt lgkmcnt(2)
	v_mfma_f32_32x32x16_bf16 v[80:95], v[168:171], v[136:139], v[80:95]
	s_waitcnt lgkmcnt(1)
	v_mfma_f32_32x32x16_bf16 v[64:79], v[172:175], v[136:139], v[64:79]
	s_waitcnt lgkmcnt(0)
	v_mfma_f32_32x32x16_bf16 v[48:63], v[160:163], v[140:143], v[48:63]
	v_mfma_f32_32x32x16_bf16 v[32:47], v[164:167], v[140:143], v[32:47]
	v_mfma_f32_32x32x16_bf16 v[16:31], v[168:171], v[140:143], v[16:31]
	v_mfma_f32_32x32x16_bf16 v[0:15], v[172:175], v[140:143], v[0:15]
	s_add_u32 s72, s72, 1
	s_cmp_lt_u32 s72, 30
	s_cbranch_scc1 .Lp19_loop
	s_waitcnt vmcnt(6)
	s_barrier
	s_mul_i32 s74, s71, 0x6000
	s_add_u32 s75, s74, 0x2000
	s_cmp_eq_u32 s71, 2
	s_cselect_b32 s75, 0x10000, s75
	v_add_u32_e32 v205, s74, v192
	v_add_u32_e32 v207, s75, v194
	v_add_u32_e32 v206, s74, v193
	v_add_u32_e32 v208, s75, v204
	ds_read_b128 v[128:131], v205
	ds_read_b128 v[144:147], v207
	ds_read_b128 v[148:151], v207 offset:2048
	ds_read_b128 v[152:155], v207 offset:4096
	ds_read_b128 v[156:159], v207 offset:6144
	ds_read_b128 v[132:135], v205 offset:2048
	ds_read_b128 v[136:139], v206
	ds_read_b128 v[160:163], v208
	ds_read_b128 v[164:167], v208 offset:2048
	ds_read_b128 v[168:171], v208 offset:4096
	ds_read_b128 v[172:175], v208 offset:6144
	ds_read_b128 v[140:143], v206 offset:2048
	s_add_u32 s71, s71, 1
	s_cmp_eq_u32 s71, 3
	s_cselect_b32 s71, 0, s71
	s_waitcnt lgkmcnt(10)
	v_mfma_f32_32x32x16_bf16 v[112:127], v[144:147], v[128:131], v[112:127]
	s_waitcnt lgkmcnt(9)
	v_mfma_f32_32x32x16_bf16 v[96:111], v[148:151], v[128:131], v[96:111]
	s_waitcnt lgkmcnt(8)
	v_mfma_f32_32x32x16_bf16 v[80:95], v[152:155], v[128:131], v[80:95]
	s_waitcnt lgkmcnt(7)
	v_mfma_f32_32x32x16_bf16 v[64:79], v[156:159], v[128:131], v[64:79]
	s_waitcnt lgkmcnt(6)
	v_mfma_f32_32x32x16_bf16 v[48:63], v[144:147], v[132:135], v[48:63]
	v_mfma_f32_32x32x16_bf16 v[32:47], v[148:151], v[132:135], v[32:47]
	v_mfma_f32_32x32x16_bf16 v[16:31], v[152:155], v[132:135], v[16:31]
	v_mfma_f32_32x32x16_bf16 v[0:15], v[156:159], v[132:135], v[0:15]
	s_waitcnt lgkmcnt(4)
	v_mfma_f32_32x32x16_bf16 v[112:127], v[160:163], v[136:139], v[112:127]
	s_waitcnt lgkmcnt(3)
	v_mfma_f32_32x32x16_bf16 v[96:111], v[164:167], v[136:139], v[96:111]
	s_waitcnt lgkmcnt(2)
	v_mfma_f32_32x32x16_bf16 v[80:95], v[168:171], v[136:139], v[80:95]
	s_waitcnt lgkmcnt(1)
	v_mfma_f32_32x32x16_bf16 v[64:79], v[172:175], v[136:139], v[64:79]
	s_waitcnt lgkmcnt(0)
	v_mfma_f32_32x32x16_bf16 v[48:63], v[160:163], v[140:143], v[48:63]
	v_mfma_f32_32x32x16_bf16 v[32:47], v[164:167], v[140:143], v[32:47]
	v_mfma_f32_32x32x16_bf16 v[16:31], v[168:171], v[140:143], v[16:31]
	v_mfma_f32_32x32x16_bf16 v[0:15], v[172:175], v[140:143], v[0:15]
	s_waitcnt vmcnt(0)
	s_barrier
; #define MFMA32(a, b, c) __builtin_amdgcn_mfma_f32_32x32x16_bf16((a), (b), (c), 0, 0, 0)
; DI int crow(int reg, int h) { return (reg & 3) + 8 * (reg >> 2) + 4 * h; }
; template <int lda>
; DI void gemm_mainloop(const bfr* __restrict__ A, const bfr* __restrict__ Bt, int NB, int K, int m0, int n0, char* smem, f32x16 (&acc)[2][4]) {
;     ...
;     const bfr* As = S0 + (kt & 1) * GSTAGE;
;     const bfr* Bs = As + 128 * 40;
; #pragma unroll
;     for (int ks = 0; ks < 2; ++ks) {
;       bf16x8 af[2], bfg[4];
; #pragma unroll
;       for (int i = 0; i < 2; ++i) af[i] = *(const bf16x8*)(As + (wr * 64 + i * 32 + r) * 40 + ks * 16 + hl * 8);
; #pragma unroll
;       for (int j = 0; j < 4; ++j) bfg[j] = *(const bf16x8*)(Bs + (wc * 128 + j * 32 + r) * 40 + ks * 16 + hl * 8);
; #pragma unroll
;       for (int i = 0; i < 2; ++i)
; #pragma unroll
;         for (int j = 0; j < 4; ++j) acc[i][j] = MFMA32(af[i], bfg[j], acc[i][j]);
; template <bool FIRST, bool HAS_H>
; DI void phase_gemm_resid(const Params& p, const bfr* A, const bfr* Wt, const float* gnext, float* ss, char* smem) {
;     ...
;     int tid2 = threadIdx.x;
;     asm volatile("" : "+v"(tid2));
;     const int lane = tid2 & 63, wid = tid2 >> 6, wr = wid >> 1, wc = wid & 1, r = lane & 31, hl = lane >> 5;
;     const float* xsrc = FIRST ? p.x_prompt : X;
;     const int rbase = m0 + wr * 64 + 4 * hl, cbase = n0 + wc * 128 + r;
; #pragma unroll
;     for (int i = 0; i < 2; ++i) {
; #pragma unroll
;       for (int qh = 0; qh < 2; ++qh) {
;         float rs[8];
; #pragma unroll
;         for (int q = 0; q < 8; ++q) rs[q] = 0.f;
; #pragma unroll
;         for (int jh = 0; jh < 2; ++jh) {
;           float xo[2][8];
; #pragma unroll
;           for (int jj = 0; jj < 2; ++jj)
; #pragma unroll
;             for (int q = 0; q < 8; ++q)
;               xo[jj][q] = xsrc[(rbase + i * 32 + crow(qh * 8 + q, 0)) * 1024 + cbase + (jh * 2 + jj) * 32];
	s_mul_i32 s74, s71, 0x6000
	s_add_u32 s75, s74, 0x2000
	s_cmp_eq_u32 s71, 2
	s_cselect_b32 s75, 0x10000, s75
	v_add_u32_e32 v205, s74, v192
	v_add_u32_e32 v207, s75, v194
	v_add_u32_e32 v206, s74, v193
	v_add_u32_e32 v208, s75, v204
	ds_read_b128 v[128:131], v205
	ds_read_b128 v[144:147], v207
	ds_read_b128 v[148:151], v207 offset:2048
	ds_read_b128 v[152:155], v207 offset:4096
	ds_read_b128 v[156:159], v207 offset:6144
	ds_read_b128 v[132:135], v205 offset:2048
	ds_read_b128 v[136:139], v206
	ds_read_b128 v[160:163], v208
	ds_read_b128 v[164:167], v208 offset:2048
	ds_read_b128 v[168:171], v208 offset:4096
	ds_read_b128 v[172:175], v208 offset:6144
	ds_read_b128 v[140:143], v206 offset:2048
	s_add_u32 s71, s71, 1
	s_cmp_eq_u32 s71, 3
	s_cselect_b32 s71, 0, s71
	s_waitcnt lgkmcnt(10)
	v_mfma_f32_32x32x16_bf16 v[112:127], v[144:147], v[128:131], v[112:127]
	s_waitcnt lgkmcnt(9)
	v_mfma_f32_32x32x16_bf16 v[96:111], v[148:151], v[128:131], v[96:111]
	s_waitcnt lgkmcnt(8)
	v_mfma_f32_32x32x16_bf16 v[80:95], v[152:155], v[128:131], v[80:95]
	s_waitcnt lgkmcnt(7)
	v_mfma_f32_32x32x16_bf16 v[64:79], v[156:159], v[128:131], v[64:79]
	s_waitcnt lgkmcnt(6)
	v_mfma_f32_32x32x16_bf16 v[48:63], v[144:147], v[132:135], v[48:63]
	v_mfma_f32_32x32x16_bf16 v[32:47], v[148:151], v[132:135], v[32:47]
	v_mfma_f32_32x32x16_bf16 v[16:31], v[152:155], v[132:135], v[16:31]
	v_mfma_f32_32x32x16_bf16 v[0:15], v[156:159], v[132:135], v[0:15]
	s_waitcnt lgkmcnt(4)
	v_mfma_f32_32x32x16_bf16 v[112:127], v[160:163], v[136:139], v[112:127]
	s_waitcnt lgkmcnt(3)
	v_mfma_f32_32x32x16_bf16 v[96:111], v[164:167], v[136:139], v[96:111]
	s_waitcnt lgkmcnt(2)
	v_mfma_f32_32x32x16_bf16 v[80:95], v[168:171], v[136:139], v[80:95]
	s_waitcnt lgkmcnt(1)
	v_mfma_f32_32x32x16_bf16 v[64:79], v[172:175], v[136:139], v[64:79]
	s_waitcnt lgkmcnt(0)
	v_mfma_f32_32x32x16_bf16 v[48:63], v[160:163], v[140:143], v[48:63]
	v_mfma_f32_32x32x16_bf16 v[32:47], v[164:167], v[140:143], v[32:47]
	v_mfma_f32_32x32x16_bf16 v[16:31], v[168:171], v[140:143], v[16:31]
	v_mfma_f32_32x32x16_bf16 v[0:15], v[172:175], v[140:143], v[0:15]
	s_nop 7
	s_nop 3
	s_load_dwordx2 s[64:65], s[92:93], 0x100
	s_load_dwordx2 s[66:67], s[92:93], 0x100
	s_mul_i32 s76, s73, 8704
	s_lshr_b32 s74, s73, 1
	s_lshl_b32 s74, s74, 6
	s_add_u32 s74, s74, s77
	s_and_b32 s75, s73, 1
	s_lshl_b32 s75, s75, 7
	s_add_u32 s75, s75, s78
	v_and_b32_e32 v210, 31, v196
	v_bfe_u32 v211, v196, 5, 1
	v_mul_u32_u24_e32 v212, 272, v210
	v_add_u32_e32 v212, s76, v212
	v_lshl_add_u32 v180, v211, 4, v212
	v_lshl_add_u32 v182, v211, 3, v212
	v_lshlrev_b32_e32 v212, 2, v211
	v_add_lshl_u32 v204, v212, s75, 2
	v_add_lshl_u32 v207, v210, s74, 2
	v_and_b32_e32 v212, 63, v196
	v_xor_b32_e32 v212, 32, v212
	v_lshlrev_b32_e32 v208, 2, v212
	v_bfe_u32 v210, v196, 4, 2
	v_and_b32_e32 v211, 15, v196
	v_mul_u32_u24_e32 v212, 272, v210
	v_lshl_add_u32 v212, v211, 4, v212
	v_add_u32_e32 v183, s76, v212
	v_add_u32_e32 v212, s74, v210
	v_lshlrev_b32_e32 v212, 10, v212
	v_lshl_add_u32 v212, v211, 2, v212
	v_add_lshl_u32 v193, v212, s75, 2
	s_mov_b32 s79, s74
	s_mov_b32 s72, s75
	s_waitcnt lgkmcnt(0)
	s_add_u32 s74, s64, 0x0
	s_addc_u32 s75, s65, 0
	global_load_dwordx4 v[128:131], v193, s[74:75]
	s_add_u32 s74, s64, 0x4000
	s_addc_u32 s75, s65, 0
	global_load_dwordx4 v[132:135], v193, s[74:75]
	s_add_u32 s74, s64, 0x8000
	s_addc_u32 s75, s65, 0
	global_load_dwordx4 v[136:139], v193, s[74:75]
	s_add_u32 s74, s64, 0xc000
	s_addc_u32 s75, s65, 0
	global_load_dwordx4 v[140:143], v193, s[74:75]
	s_add_u32 s74, s64, 0x10000
	s_addc_u32 s75, s65, 0
	global_load_dwordx4 v[144:147], v193, s[74:75]
	s_add_u32 s74, s64, 0x14000
	s_addc_u32 s75, s65, 0
	global_load_dwordx4 v[148:151], v193, s[74:75]
	s_add_u32 s74, s64, 0x18000
	s_addc_u32 s75, s65, 0
	global_load_dwordx4 v[152:155], v193, s[74:75]
	s_add_u32 s74, s64, 0x1c000
	s_addc_u32 s75, s65, 0
	global_load_dwordx4 v[156:159], v193, s[74:75]
	s_mov_b32 s74, s79
	s_mov_b32 s75, s72
	v_bfe_u32 v210, v196, 3, 3
	v_and_b32_e32 v211, 7, v196
	v_mul_u32_u24_e32 v212, 272, v210
	v_lshl_add_u32 v212, v211, 4, v212
	v_add_u32_e32 v192, s76, v212
	v_add_u32_e32 v212, s74, v210
	v_lshlrev_b32_e32 v212, 10, v212
	v_lshl_add_u32 v212, v211, 3, v212
	v_add_lshl_u32 v194, v212, s75, 1
	v_mov_b32_e32 v205, 0
	v_mov_b32_e32 v206, 0
	s_waitcnt lgkmcnt(0)
	s_barrier
; DI bfr f2bf(float a) { return (bfr)(pack2(a, 0.f) & 0xffffu); }
; DI int crow(int reg, int h) { return (reg & 3) + 8 * (reg >> 2) + 4 * h; }
; template <bool FIRST, bool HAS_H>
; DI void phase_gemm_resid(const Params& p, const bfr* A, const bfr* Wt, const float* gnext, float* ss, char* smem) {
;     ...
;         for (int jh = 0; jh < 2; ++jh) {
;           float xo[2][8];
; #pragma unroll
;           for (int jj = 0; jj < 2; ++jj)
; #pragma unroll
;             for (int q = 0; q < 8; ++q)
;               xo[jj][q] = xsrc[(rbase + i * 32 + crow(qh * 8 + q, 0)) * 1024 + cbase + (jh * 2 + jj) * 32];
; #pragma unroll
;           for (int q = 0; q < 8; ++q) {
;             const int o = (rbase + i * 32 + crow(qh * 8 + q, 0)) * 1024 + cbase;
; #pragma unroll
;             for (int jj = 0; jj < 2; ++jj) {
;               const int j = jh * 2 + jj;
;               const float xn = xo[jj][q] + acc[i][j][qh * 8 + q];
;               X[o + j * 32] = xn;
;               if (HAS_H) Hn[o + j * 32] = f2bf(xn * gnext[cbase + j * 32]);
;               rs[q] += xn * xn;
;             }
;           }
	s_waitcnt vmcnt(7)
	ds_write_b128 v183, v[128:131]
	s_waitcnt vmcnt(6)
	ds_write_b128 v183, v[132:135] offset:1088
	s_waitcnt vmcnt(5)
	ds_write_b128 v183, v[136:139] offset:2176
	s_waitcnt vmcnt(4)
	ds_write_b128 v183, v[140:143] offset:3264
	s_waitcnt vmcnt(3)
	ds_write_b128 v183, v[144:147] offset:4352
	s_waitcnt vmcnt(2)
	ds_write_b128 v183, v[148:151] offset:5440
	s_waitcnt vmcnt(1)
	ds_write_b128 v183, v[152:155] offset:6528
	s_waitcnt vmcnt(0)
	ds_write_b128 v183, v[156:159] offset:7616
	s_add_u32 s74, s64, 0x100
	s_addc_u32 s75, s65, 0
	global_load_dwordx4 v[128:131], v193, s[74:75]
	s_add_u32 s74, s64, 0x4100
	s_addc_u32 s75, s65, 0
	global_load_dwordx4 v[132:135], v193, s[74:75]
	s_add_u32 s74, s64, 0x8100
	s_addc_u32 s75, s65, 0
	global_load_dwordx4 v[136:139], v193, s[74:75]
	s_add_u32 s74, s64, 0xc100
	s_addc_u32 s75, s65, 0
	global_load_dwordx4 v[140:143], v193, s[74:75]
	s_add_u32 s74, s64, 0x10100
	s_addc_u32 s75, s65, 0
	global_load_dwordx4 v[144:147], v193, s[74:75]
	s_add_u32 s74, s64, 0x14100
	s_addc_u32 s75, s65, 0
	global_load_dwordx4 v[148:151], v193, s[74:75]
	s_add_u32 s74, s64, 0x18100
	s_addc_u32 s75, s65, 0
	global_load_dwordx4 v[152:155], v193, s[74:75]
	s_add_u32 s74, s64, 0x1c100
	s_addc_u32 s75, s65, 0
	global_load_dwordx4 v[156:159], v193, s[74:75]
	ds_read_b128 v[160:163], v180
	ds_read_b128 v[164:167], v180 offset:32
	ds_read_b128 v[168:171], v180 offset:64
	ds_read_b128 v[172:175], v180 offset:96
	ds_read_b128 v[176:179], v180 offset:128
	ds_read_b128 v[184:187], v180 offset:160
	ds_read_b128 v[188:191], v180 offset:192
	ds_read_b128 v[200:203], v180 offset:224
	s_waitcnt lgkmcnt(7)
	v_add_f32_e32 v112, v160, v112
	v_add_f32_e32 v113, v161, v113
	v_add_f32_e32 v114, v162, v114
	v_add_f32_e32 v115, v163, v115
	v_fmac_f32_e32 v205, v112, v112
	v_fmac_f32_e32 v205, v113, v113
	v_fmac_f32_e32 v205, v114, v114
	v_fmac_f32_e32 v205, v115, v115
	ds_write_b128 v180, v[112:115]
	s_waitcnt lgkmcnt(7)
	v_add_f32_e32 v116, v164, v116
	v_add_f32_e32 v117, v165, v117
	v_add_f32_e32 v118, v166, v118
	v_add_f32_e32 v119, v167, v119
	v_fmac_f32_e32 v205, v116, v116
	v_fmac_f32_e32 v205, v117, v117
	v_fmac_f32_e32 v205, v118, v118
	v_fmac_f32_e32 v205, v119, v119
	ds_write_b128 v180, v[116:119] offset:32
	s_waitcnt lgkmcnt(7)
	v_add_f32_e32 v120, v168, v120
	v_add_f32_e32 v121, v169, v121
	v_add_f32_e32 v122, v170, v122
	v_add_f32_e32 v123, v171, v123
	v_fmac_f32_e32 v205, v120, v120
	v_fmac_f32_e32 v205, v121, v121
	v_fmac_f32_e32 v205, v122, v122
	v_fmac_f32_e32 v205, v123, v123
	ds_write_b128 v180, v[120:123] offset:64
	s_waitcnt lgkmcnt(7)
	v_add_f32_e32 v124, v172, v124
	v_add_f32_e32 v125, v173, v125
	v_add_f32_e32 v126, v174, v126
	v_add_f32_e32 v127, v175, v127
	v_fmac_f32_e32 v205, v124, v124
	v_fmac_f32_e32 v205, v125, v125
	v_fmac_f32_e32 v205, v126, v126
	v_fmac_f32_e32 v205, v127, v127
	ds_write_b128 v180, v[124:127] offset:96
	s_waitcnt lgkmcnt(7)
	v_add_f32_e32 v96, v176, v96
	v_add_f32_e32 v97, v177, v97
	v_add_f32_e32 v98, v178, v98
	v_add_f32_e32 v99, v179, v99
	v_fmac_f32_e32 v205, v96, v96
	v_fmac_f32_e32 v205, v97, v97
	v_fmac_f32_e32 v205, v98, v98
	v_fmac_f32_e32 v205, v99, v99
	ds_write_b128 v180, v[96:99] offset:128
	s_waitcnt lgkmcnt(7)
	v_add_f32_e32 v100, v184, v100
	v_add_f32_e32 v101, v185, v101
	v_add_f32_e32 v102, v186, v102
	v_add_f32_e32 v103, v187, v103
	v_fmac_f32_e32 v205, v100, v100
	v_fmac_f32_e32 v205, v101, v101
	v_fmac_f32_e32 v205, v102, v102
	v_fmac_f32_e32 v205, v103, v103
	ds_write_b128 v180, v[100:103] offset:160
	s_waitcnt lgkmcnt(7)
	v_add_f32_e32 v104, v188, v104
	v_add_f32_e32 v105, v189, v105
	v_add_f32_e32 v106, v190, v106
	v_add_f32_e32 v107, v191, v107
	v_fmac_f32_e32 v205, v104, v104
	v_fmac_f32_e32 v205, v105, v105
	v_fmac_f32_e32 v205, v106, v106
	v_fmac_f32_e32 v205, v107, v107
	ds_write_b128 v180, v[104:107] offset:192
	s_waitcnt lgkmcnt(7)
	v_add_f32_e32 v108, v200, v108
	v_add_f32_e32 v109, v201, v109
	v_add_f32_e32 v110, v202, v110
	v_add_f32_e32 v111, v203, v111
	v_fmac_f32_e32 v205, v108, v108
	v_fmac_f32_e32 v205, v109, v109
	v_fmac_f32_e32 v205, v110, v110
	v_fmac_f32_e32 v205, v111, v111
	ds_write_b128 v180, v[108:111] offset:224
	ds_read_b128 v[160:163], v183
	ds_read_b128 v[164:167], v183 offset:1088
	ds_read_b128 v[168:171], v183 offset:2176
	ds_read_b128 v[172:175], v183 offset:3264
	ds_read_b128 v[176:179], v183 offset:4352
	ds_read_b128 v[184:187], v183 offset:5440
	ds_read_b128 v[188:191], v183 offset:6528
	ds_read_b128 v[200:203], v183 offset:7616
	s_add_u32 s74, s66, 0x0
	s_addc_u32 s75, s67, 0
	s_waitcnt lgkmcnt(7)
	global_store_dwordx4 v193, v[160:163], s[74:75]
	s_add_u32 s74, s66, 0x4000
	s_addc_u32 s75, s67, 0
	s_waitcnt lgkmcnt(6)
	global_store_dwordx4 v193, v[164:167], s[74:75]
	s_add_u32 s74, s66, 0x8000
	s_addc_u32 s75, s67, 0
	s_waitcnt lgkmcnt(5)
	global_store_dwordx4 v193, v[168:171], s[74:75]
	s_add_u32 s74, s66, 0xc000
	s_addc_u32 s75, s67, 0
	s_waitcnt lgkmcnt(4)
	global_store_dwordx4 v193, v[172:175], s[74:75]
	s_add_u32 s74, s66, 0x10000
	s_addc_u32 s75, s67, 0
	s_waitcnt lgkmcnt(3)
	global_store_dwordx4 v193, v[176:179], s[74:75]
	s_add_u32 s74, s66, 0x14000
	s_addc_u32 s75, s67, 0
	s_waitcnt lgkmcnt(2)
	global_store_dwordx4 v193, v[184:187], s[74:75]
	s_add_u32 s74, s66, 0x18000
	s_addc_u32 s75, s67, 0
	s_waitcnt lgkmcnt(1)
	global_store_dwordx4 v193, v[188:191], s[74:75]
	s_add_u32 s74, s66, 0x1c000
	s_addc_u32 s75, s67, 0
	s_waitcnt lgkmcnt(0)
	global_store_dwordx4 v193, v[200:203], s[74:75]
	s_waitcnt vmcnt(15)
	ds_write_b128 v183, v[128:131]
	s_waitcnt vmcnt(14)
	ds_write_b128 v183, v[132:135] offset:1088
	s_waitcnt vmcnt(13)
; DI bfr f2bf(float a) { return (bfr)(pack2(a, 0.f) & 0xffffu); }
; DI int crow(int reg, int h) { return (reg & 3) + 8 * (reg >> 2) + 4 * h; }
; template <bool FIRST, bool HAS_H>
; DI void phase_gemm_resid(const Params& p, const bfr* A, const bfr* Wt, const float* gnext, float* ss, char* smem) {
;     ...
;         for (int jh = 0; jh < 2; ++jh) {
;           float xo[2][8];
; #pragma unroll
;           for (int jj = 0; jj < 2; ++jj)
; #pragma unroll
;             for (int q = 0; q < 8; ++q)
;               xo[jj][q] = xsrc[(rbase + i * 32 + crow(qh * 8 + q, 0)) * 1024 + cbase + (jh * 2 + jj) * 32];
; #pragma unroll
;           for (int q = 0; q < 8; ++q) {
;             const int o = (rbase + i * 32 + crow(qh * 8 + q, 0)) * 1024 + cbase;
; #pragma unroll
;             for (int jj = 0; jj < 2; ++jj) {
;               const int j = jh * 2 + jj;
;               const float xn = xo[jj][q] + acc[i][j][qh * 8 + q];
;               X[o + j * 32] = xn;
;               if (HAS_H) Hn[o + j * 32] = f2bf(xn * gnext[cbase + j * 32]);
;               rs[q] += xn * xn;
;             }
;           }
	ds_write_b128 v183, v[136:139] offset:2176
	s_waitcnt vmcnt(12)
	ds_write_b128 v183, v[140:143] offset:3264
	s_waitcnt vmcnt(11)
	ds_write_b128 v183, v[144:147] offset:4352
	s_waitcnt vmcnt(10)
	ds_write_b128 v183, v[148:151] offset:5440
	s_waitcnt vmcnt(9)
	ds_write_b128 v183, v[152:155] offset:6528
	s_waitcnt vmcnt(8)
	ds_write_b128 v183, v[156:159] offset:7616
	s_add_u32 s74, s64, 0x20000
	s_addc_u32 s75, s65, 0
	global_load_dwordx4 v[128:131], v193, s[74:75]
	s_add_u32 s74, s64, 0x24000
	s_addc_u32 s75, s65, 0
	global_load_dwordx4 v[132:135], v193, s[74:75]
	s_add_u32 s74, s64, 0x28000
	s_addc_u32 s75, s65, 0
	global_load_dwordx4 v[136:139], v193, s[74:75]
	s_add_u32 s74, s64, 0x2c000
	s_addc_u32 s75, s65, 0
	global_load_dwordx4 v[140:143], v193, s[74:75]
	s_add_u32 s74, s64, 0x30000
	s_addc_u32 s75, s65, 0
	global_load_dwordx4 v[144:147], v193, s[74:75]
	s_add_u32 s74, s64, 0x34000
	s_addc_u32 s75, s65, 0
	global_load_dwordx4 v[148:151], v193, s[74:75]
	s_add_u32 s74, s64, 0x38000
	s_addc_u32 s75, s65, 0
	global_load_dwordx4 v[152:155], v193, s[74:75]
	s_add_u32 s74, s64, 0x3c000
	s_addc_u32 s75, s65, 0
	global_load_dwordx4 v[156:159], v193, s[74:75]
	ds_read_b128 v[160:163], v180
	ds_read_b128 v[164:167], v180 offset:32
	ds_read_b128 v[168:171], v180 offset:64
	ds_read_b128 v[172:175], v180 offset:96
	ds_read_b128 v[176:179], v180 offset:128
	ds_read_b128 v[184:187], v180 offset:160
	ds_read_b128 v[188:191], v180 offset:192
	ds_read_b128 v[200:203], v180 offset:224
	s_waitcnt lgkmcnt(7)
	v_add_f32_e32 v80, v160, v80
	v_add_f32_e32 v81, v161, v81
	v_add_f32_e32 v82, v162, v82
	v_add_f32_e32 v83, v163, v83
	v_fmac_f32_e32 v205, v80, v80
	v_fmac_f32_e32 v205, v81, v81
	v_fmac_f32_e32 v205, v82, v82
	v_fmac_f32_e32 v205, v83, v83
	ds_write_b128 v180, v[80:83]
	s_waitcnt lgkmcnt(7)
	v_add_f32_e32 v84, v164, v84
	v_add_f32_e32 v85, v165, v85
	v_add_f32_e32 v86, v166, v86
	v_add_f32_e32 v87, v167, v87
	v_fmac_f32_e32 v205, v84, v84
	v_fmac_f32_e32 v205, v85, v85
	v_fmac_f32_e32 v205, v86, v86
	v_fmac_f32_e32 v205, v87, v87
	ds_write_b128 v180, v[84:87] offset:32
	s_waitcnt lgkmcnt(7)
	v_add_f32_e32 v88, v168, v88
	v_add_f32_e32 v89, v169, v89
	v_add_f32_e32 v90, v170, v90
	v_add_f32_e32 v91, v171, v91
	v_fmac_f32_e32 v205, v88, v88
	v_fmac_f32_e32 v205, v89, v89
	v_fmac_f32_e32 v205, v90, v90
	v_fmac_f32_e32 v205, v91, v91
	ds_write_b128 v180, v[88:91] offset:64
	s_waitcnt lgkmcnt(7)
	v_add_f32_e32 v92, v172, v92
	v_add_f32_e32 v93, v173, v93
	v_add_f32_e32 v94, v174, v94
	v_add_f32_e32 v95, v175, v95
	v_fmac_f32_e32 v205, v92, v92
	v_fmac_f32_e32 v205, v93, v93
	v_fmac_f32_e32 v205, v94, v94
	v_fmac_f32_e32 v205, v95, v95
	ds_write_b128 v180, v[92:95] offset:96
	s_waitcnt lgkmcnt(7)
	v_add_f32_e32 v64, v176, v64
	v_add_f32_e32 v65, v177, v65
	v_add_f32_e32 v66, v178, v66
	v_add_f32_e32 v67, v179, v67
	v_fmac_f32_e32 v205, v64, v64
	v_fmac_f32_e32 v205, v65, v65
	v_fmac_f32_e32 v205, v66, v66
	v_fmac_f32_e32 v205, v67, v67
	ds_write_b128 v180, v[64:67] offset:128
	s_waitcnt lgkmcnt(7)
	v_add_f32_e32 v68, v184, v68
	v_add_f32_e32 v69, v185, v69
	v_add_f32_e32 v70, v186, v70
	v_add_f32_e32 v71, v187, v71
	v_fmac_f32_e32 v205, v68, v68
	v_fmac_f32_e32 v205, v69, v69
	v_fmac_f32_e32 v205, v70, v70
	v_fmac_f32_e32 v205, v71, v71
	ds_write_b128 v180, v[68:71] offset:160
	s_waitcnt lgkmcnt(7)
	v_add_f32_e32 v72, v188, v72
	v_add_f32_e32 v73, v189, v73
	v_add_f32_e32 v74, v190, v74
	v_add_f32_e32 v75, v191, v75
	v_fmac_f32_e32 v205, v72, v72
	v_fmac_f32_e32 v205, v73, v73
	v_fmac_f32_e32 v205, v74, v74
	v_fmac_f32_e32 v205, v75, v75
	ds_write_b128 v180, v[72:75] offset:192
	s_waitcnt lgkmcnt(7)
	v_add_f32_e32 v76, v200, v76
	v_add_f32_e32 v77, v201, v77
	v_add_f32_e32 v78, v202, v78
	v_add_f32_e32 v79, v203, v79
	v_fmac_f32_e32 v205, v76, v76
	v_fmac_f32_e32 v205, v77, v77
	v_fmac_f32_e32 v205, v78, v78
	v_fmac_f32_e32 v205, v79, v79
	ds_write_b128 v180, v[76:79] offset:224
	ds_read_b128 v[160:163], v183
	ds_read_b128 v[164:167], v183 offset:1088
	ds_read_b128 v[168:171], v183 offset:2176
	ds_read_b128 v[172:175], v183 offset:3264
	ds_read_b128 v[176:179], v183 offset:4352
	ds_read_b128 v[184:187], v183 offset:5440
	ds_read_b128 v[188:191], v183 offset:6528
	ds_read_b128 v[200:203], v183 offset:7616
	s_add_u32 s74, s66, 0x100
	s_addc_u32 s75, s67, 0
	s_waitcnt lgkmcnt(7)
	global_store_dwordx4 v193, v[160:163], s[74:75]
	s_add_u32 s74, s66, 0x4100
	s_addc_u32 s75, s67, 0
	s_waitcnt lgkmcnt(6)
	global_store_dwordx4 v193, v[164:167], s[74:75]
	s_add_u32 s74, s66, 0x8100
	s_addc_u32 s75, s67, 0
	s_waitcnt lgkmcnt(5)
	global_store_dwordx4 v193, v[168:171], s[74:75]
	s_add_u32 s74, s66, 0xc100
	s_addc_u32 s75, s67, 0
	s_waitcnt lgkmcnt(4)
	global_store_dwordx4 v193, v[172:175], s[74:75]
	s_add_u32 s74, s66, 0x10100
	s_addc_u32 s75, s67, 0
	s_waitcnt lgkmcnt(3)
	global_store_dwordx4 v193, v[176:179], s[74:75]
	s_add_u32 s74, s66, 0x14100
	s_addc_u32 s75, s67, 0
	s_waitcnt lgkmcnt(2)
	global_store_dwordx4 v193, v[184:187], s[74:75]
	s_add_u32 s74, s66, 0x18100
	s_addc_u32 s75, s67, 0
	s_waitcnt lgkmcnt(1)
	global_store_dwordx4 v193, v[188:191], s[74:75]
	s_add_u32 s74, s66, 0x1c100
	s_addc_u32 s75, s67, 0
	s_waitcnt lgkmcnt(0)
	global_store_dwordx4 v193, v[200:203], s[74:75]
	s_waitcnt vmcnt(15)
	ds_write_b128 v183, v[128:131]
	s_waitcnt vmcnt(14)
	ds_write_b128 v183, v[132:135] offset:1088
	s_waitcnt vmcnt(13)
	ds_write_b128 v183, v[136:139] offset:2176
	s_waitcnt vmcnt(12)
	ds_write_b128 v183, v[140:143] offset:3264
	s_waitcnt vmcnt(11)
	ds_write_b128 v183, v[144:147] offset:4352
	s_waitcnt vmcnt(10)
	ds_write_b128 v183, v[148:151] offset:5440
	s_waitcnt vmcnt(9)
; DI bfr f2bf(float a) { return (bfr)(pack2(a, 0.f) & 0xffffu); }
; DI int crow(int reg, int h) { return (reg & 3) + 8 * (reg >> 2) + 4 * h; }
; template <bool FIRST, bool HAS_H>
; DI void phase_gemm_resid(const Params& p, const bfr* A, const bfr* Wt, const float* gnext, float* ss, char* smem) {
;     ...
;         for (int jh = 0; jh < 2; ++jh) {
;           float xo[2][8];
; #pragma unroll
;           for (int jj = 0; jj < 2; ++jj)
; #pragma unroll
;             for (int q = 0; q < 8; ++q)
;               xo[jj][q] = xsrc[(rbase + i * 32 + crow(qh * 8 + q, 0)) * 1024 + cbase + (jh * 2 + jj) * 32];
; #pragma unroll
;           for (int q = 0; q < 8; ++q) {
;             const int o = (rbase + i * 32 + crow(qh * 8 + q, 0)) * 1024 + cbase;
; #pragma unroll
;             for (int jj = 0; jj < 2; ++jj) {
;               const int j = jh * 2 + jj;
;               const float xn = xo[jj][q] + acc[i][j][qh * 8 + q];
;               X[o + j * 32] = xn;
;               if (HAS_H) Hn[o + j * 32] = f2bf(xn * gnext[cbase + j * 32]);
;               rs[q] += xn * xn;
;             }
;           }
	ds_write_b128 v183, v[152:155] offset:6528
	s_waitcnt vmcnt(8)
	ds_write_b128 v183, v[156:159] offset:7616
	s_add_u32 s74, s64, 0x20100
	s_addc_u32 s75, s65, 0
	global_load_dwordx4 v[128:131], v193, s[74:75]
	s_add_u32 s74, s64, 0x24100
	s_addc_u32 s75, s65, 0
	global_load_dwordx4 v[132:135], v193, s[74:75]
	s_add_u32 s74, s64, 0x28100
	s_addc_u32 s75, s65, 0
	global_load_dwordx4 v[136:139], v193, s[74:75]
	s_add_u32 s74, s64, 0x2c100
	s_addc_u32 s75, s65, 0
	global_load_dwordx4 v[140:143], v193, s[74:75]
	s_add_u32 s74, s64, 0x30100
	s_addc_u32 s75, s65, 0
	global_load_dwordx4 v[144:147], v193, s[74:75]
	s_add_u32 s74, s64, 0x34100
	s_addc_u32 s75, s65, 0
	global_load_dwordx4 v[148:151], v193, s[74:75]
	s_add_u32 s74, s64, 0x38100
	s_addc_u32 s75, s65, 0
	global_load_dwordx4 v[152:155], v193, s[74:75]
	s_add_u32 s74, s64, 0x3c100
	s_addc_u32 s75, s65, 0
	global_load_dwordx4 v[156:159], v193, s[74:75]
	ds_read_b128 v[160:163], v180
	ds_read_b128 v[164:167], v180 offset:32
	ds_read_b128 v[168:171], v180 offset:64
	ds_read_b128 v[172:175], v180 offset:96
	ds_read_b128 v[176:179], v180 offset:128
	ds_read_b128 v[184:187], v180 offset:160
	ds_read_b128 v[188:191], v180 offset:192
	ds_read_b128 v[200:203], v180 offset:224
	s_waitcnt lgkmcnt(7)
	v_add_f32_e32 v48, v160, v48
	v_add_f32_e32 v49, v161, v49
	v_add_f32_e32 v50, v162, v50
	v_add_f32_e32 v51, v163, v51
	v_fmac_f32_e32 v206, v48, v48
	v_fmac_f32_e32 v206, v49, v49
	v_fmac_f32_e32 v206, v50, v50
	v_fmac_f32_e32 v206, v51, v51
	ds_write_b128 v180, v[48:51]
	s_waitcnt lgkmcnt(7)
	v_add_f32_e32 v52, v164, v52
	v_add_f32_e32 v53, v165, v53
	v_add_f32_e32 v54, v166, v54
	v_add_f32_e32 v55, v167, v55
	v_fmac_f32_e32 v206, v52, v52
	v_fmac_f32_e32 v206, v53, v53
	v_fmac_f32_e32 v206, v54, v54
	v_fmac_f32_e32 v206, v55, v55
	ds_write_b128 v180, v[52:55] offset:32
	s_waitcnt lgkmcnt(7)
	v_add_f32_e32 v56, v168, v56
	v_add_f32_e32 v57, v169, v57
	v_add_f32_e32 v58, v170, v58
	v_add_f32_e32 v59, v171, v59
	v_fmac_f32_e32 v206, v56, v56
	v_fmac_f32_e32 v206, v57, v57
	v_fmac_f32_e32 v206, v58, v58
	v_fmac_f32_e32 v206, v59, v59
	ds_write_b128 v180, v[56:59] offset:64
	s_waitcnt lgkmcnt(7)
	v_add_f32_e32 v60, v172, v60
	v_add_f32_e32 v61, v173, v61
	v_add_f32_e32 v62, v174, v62
	v_add_f32_e32 v63, v175, v63
	v_fmac_f32_e32 v206, v60, v60
	v_fmac_f32_e32 v206, v61, v61
	v_fmac_f32_e32 v206, v62, v62
	v_fmac_f32_e32 v206, v63, v63
	ds_write_b128 v180, v[60:63] offset:96
	s_waitcnt lgkmcnt(7)
	v_add_f32_e32 v32, v176, v32
	v_add_f32_e32 v33, v177, v33
	v_add_f32_e32 v34, v178, v34
	v_add_f32_e32 v35, v179, v35
	v_fmac_f32_e32 v206, v32, v32
	v_fmac_f32_e32 v206, v33, v33
	v_fmac_f32_e32 v206, v34, v34
	v_fmac_f32_e32 v206, v35, v35
	ds_write_b128 v180, v[32:35] offset:128
	s_waitcnt lgkmcnt(7)
	v_add_f32_e32 v36, v184, v36
	v_add_f32_e32 v37, v185, v37
	v_add_f32_e32 v38, v186, v38
	v_add_f32_e32 v39, v187, v39
	v_fmac_f32_e32 v206, v36, v36
	v_fmac_f32_e32 v206, v37, v37
	v_fmac_f32_e32 v206, v38, v38
	v_fmac_f32_e32 v206, v39, v39
	ds_write_b128 v180, v[36:39] offset:160
	s_waitcnt lgkmcnt(7)
	v_add_f32_e32 v40, v188, v40
	v_add_f32_e32 v41, v189, v41
	v_add_f32_e32 v42, v190, v42
	v_add_f32_e32 v43, v191, v43
	v_fmac_f32_e32 v206, v40, v40
	v_fmac_f32_e32 v206, v41, v41
	v_fmac_f32_e32 v206, v42, v42
	v_fmac_f32_e32 v206, v43, v43
	ds_write_b128 v180, v[40:43] offset:192
	s_waitcnt lgkmcnt(7)
	v_add_f32_e32 v44, v200, v44
	v_add_f32_e32 v45, v201, v45
	v_add_f32_e32 v46, v202, v46
	v_add_f32_e32 v47, v203, v47
	v_fmac_f32_e32 v206, v44, v44
	v_fmac_f32_e32 v206, v45, v45
	v_fmac_f32_e32 v206, v46, v46
	v_fmac_f32_e32 v206, v47, v47
	ds_write_b128 v180, v[44:47] offset:224
	ds_read_b128 v[160:163], v183
	ds_read_b128 v[164:167], v183 offset:1088
	ds_read_b128 v[168:171], v183 offset:2176
	ds_read_b128 v[172:175], v183 offset:3264
	ds_read_b128 v[176:179], v183 offset:4352
	ds_read_b128 v[184:187], v183 offset:5440
	ds_read_b128 v[188:191], v183 offset:6528
	ds_read_b128 v[200:203], v183 offset:7616
	s_add_u32 s74, s66, 0x20000
	s_addc_u32 s75, s67, 0
	s_waitcnt lgkmcnt(7)
	global_store_dwordx4 v193, v[160:163], s[74:75]
	s_add_u32 s74, s66, 0x24000
	s_addc_u32 s75, s67, 0
	s_waitcnt lgkmcnt(6)
	global_store_dwordx4 v193, v[164:167], s[74:75]
	s_add_u32 s74, s66, 0x28000
	s_addc_u32 s75, s67, 0
	s_waitcnt lgkmcnt(5)
	global_store_dwordx4 v193, v[168:171], s[74:75]
	s_add_u32 s74, s66, 0x2c000
	s_addc_u32 s75, s67, 0
	s_waitcnt lgkmcnt(4)
	global_store_dwordx4 v193, v[172:175], s[74:75]
	s_add_u32 s74, s66, 0x30000
	s_addc_u32 s75, s67, 0
	s_waitcnt lgkmcnt(3)
	global_store_dwordx4 v193, v[176:179], s[74:75]
	s_add_u32 s74, s66, 0x34000
	s_addc_u32 s75, s67, 0
	s_waitcnt lgkmcnt(2)
	global_store_dwordx4 v193, v[184:187], s[74:75]
	s_add_u32 s74, s66, 0x38000
	s_addc_u32 s75, s67, 0
	s_waitcnt lgkmcnt(1)
	global_store_dwordx4 v193, v[188:191], s[74:75]
	s_add_u32 s74, s66, 0x3c000
	s_addc_u32 s75, s67, 0
	s_waitcnt lgkmcnt(0)
	global_store_dwordx4 v193, v[200:203], s[74:75]
	s_waitcnt vmcnt(15)
	ds_write_b128 v183, v[128:131]
	s_waitcnt vmcnt(14)
	ds_write_b128 v183, v[132:135] offset:1088
	s_waitcnt vmcnt(13)
	ds_write_b128 v183, v[136:139] offset:2176
	s_waitcnt vmcnt(12)
; DI bfr f2bf(float a) { return (bfr)(pack2(a, 0.f) & 0xffffu); }
; DI int crow(int reg, int h) { return (reg & 3) + 8 * (reg >> 2) + 4 * h; }
; template <bool FIRST, bool HAS_H>
; DI void phase_gemm_resid(const Params& p, const bfr* A, const bfr* Wt, const float* gnext, float* ss, char* smem) {
;     ...
;     const float* xsrc = FIRST ? p.x_prompt : X;
;     const int rbase = m0 + wr * 64 + 4 * hl, cbase = n0 + wc * 128 + r;
; #pragma unroll
;     for (int i = 0; i < 2; ++i) {
; #pragma unroll
;       for (int qh = 0; qh < 2; ++qh) {
;         float rs[8];
; #pragma unroll
;         for (int q = 0; q < 8; ++q) rs[q] = 0.f;
; #pragma unroll
;         for (int jh = 0; jh < 2; ++jh) {
;           float xo[2][8];
; #pragma unroll
;           for (int jj = 0; jj < 2; ++jj)
; #pragma unroll
;             for (int q = 0; q < 8; ++q)
;               xo[jj][q] = xsrc[(rbase + i * 32 + crow(qh * 8 + q, 0)) * 1024 + cbase + (jh * 2 + jj) * 32];
; #pragma unroll
;           for (int q = 0; q < 8; ++q) {
;             const int o = (rbase + i * 32 + crow(qh * 8 + q, 0)) * 1024 + cbase;
; #pragma unroll
;             for (int jj = 0; jj < 2; ++jj) {
;               const int j = jh * 2 + jj;
;               const float xn = xo[jj][q] + acc[i][j][qh * 8 + q];
;               X[o + j * 32] = xn;
;               if (HAS_H) Hn[o + j * 32] = f2bf(xn * gnext[cbase + j * 32]);
;               rs[q] += xn * xn;
;             }
;           }
;         }
; #pragma unroll
;         for (int q = 0; q < 8; ++q) rs[q] = half32_sum_hi(rs[q]);
;         if (r == 31) {
; #pragma unroll
;           for (int q = 0; q < 8; ++q) unsafeAtomicAdd(ss + rbase + i * 32 + crow(qh * 8 + q, 0), rs[q]);
;         }
;       }
;     }
;   }
	ds_write_b128 v183, v[140:143] offset:3264
	s_waitcnt vmcnt(11)
	ds_write_b128 v183, v[144:147] offset:4352
	s_waitcnt vmcnt(10)
	ds_write_b128 v183, v[148:151] offset:5440
	s_waitcnt vmcnt(9)
	ds_write_b128 v183, v[152:155] offset:6528
	s_waitcnt vmcnt(8)
	ds_write_b128 v183, v[156:159] offset:7616
	ds_read_b128 v[160:163], v180
	ds_read_b128 v[164:167], v180 offset:32
	ds_read_b128 v[168:171], v180 offset:64
	ds_read_b128 v[172:175], v180 offset:96
	ds_read_b128 v[176:179], v180 offset:128
	ds_read_b128 v[184:187], v180 offset:160
	ds_read_b128 v[188:191], v180 offset:192
	ds_read_b128 v[200:203], v180 offset:224
	s_waitcnt lgkmcnt(7)
	v_add_f32_e32 v16, v160, v16
	v_add_f32_e32 v17, v161, v17
	v_add_f32_e32 v18, v162, v18
	v_add_f32_e32 v19, v163, v19
	v_fmac_f32_e32 v206, v16, v16
	v_fmac_f32_e32 v206, v17, v17
	v_fmac_f32_e32 v206, v18, v18
	v_fmac_f32_e32 v206, v19, v19
	ds_write_b128 v180, v[16:19]
	s_waitcnt lgkmcnt(7)
	v_add_f32_e32 v20, v164, v20
	v_add_f32_e32 v21, v165, v21
	v_add_f32_e32 v22, v166, v22
	v_add_f32_e32 v23, v167, v23
	v_fmac_f32_e32 v206, v20, v20
	v_fmac_f32_e32 v206, v21, v21
	v_fmac_f32_e32 v206, v22, v22
	v_fmac_f32_e32 v206, v23, v23
	ds_write_b128 v180, v[20:23] offset:32
	s_waitcnt lgkmcnt(7)
	v_add_f32_e32 v24, v168, v24
	v_add_f32_e32 v25, v169, v25
	v_add_f32_e32 v26, v170, v26
	v_add_f32_e32 v27, v171, v27
	v_fmac_f32_e32 v206, v24, v24
	v_fmac_f32_e32 v206, v25, v25
	v_fmac_f32_e32 v206, v26, v26
	v_fmac_f32_e32 v206, v27, v27
	ds_write_b128 v180, v[24:27] offset:64
	s_waitcnt lgkmcnt(7)
	v_add_f32_e32 v28, v172, v28
	v_add_f32_e32 v29, v173, v29
	v_add_f32_e32 v30, v174, v30
	v_add_f32_e32 v31, v175, v31
	v_fmac_f32_e32 v206, v28, v28
	v_fmac_f32_e32 v206, v29, v29
	v_fmac_f32_e32 v206, v30, v30
	v_fmac_f32_e32 v206, v31, v31
	ds_write_b128 v180, v[28:31] offset:96
	s_waitcnt lgkmcnt(7)
	v_add_f32_e32 v0, v176, v0
	v_add_f32_e32 v1, v177, v1
	v_add_f32_e32 v2, v178, v2
	v_add_f32_e32 v3, v179, v3
	v_fmac_f32_e32 v206, v0, v0
	v_fmac_f32_e32 v206, v1, v1
	v_fmac_f32_e32 v206, v2, v2
	v_fmac_f32_e32 v206, v3, v3
	ds_write_b128 v180, v[0:3] offset:128
	s_waitcnt lgkmcnt(7)
	v_add_f32_e32 v4, v184, v4
	v_add_f32_e32 v5, v185, v5
	v_add_f32_e32 v6, v186, v6
	v_add_f32_e32 v7, v187, v7
	v_fmac_f32_e32 v206, v4, v4
	v_fmac_f32_e32 v206, v5, v5
	v_fmac_f32_e32 v206, v6, v6
	v_fmac_f32_e32 v206, v7, v7
	ds_write_b128 v180, v[4:7] offset:160
	s_waitcnt lgkmcnt(7)
	v_add_f32_e32 v8, v188, v8
	v_add_f32_e32 v9, v189, v9
	v_add_f32_e32 v10, v190, v10
	v_add_f32_e32 v11, v191, v11
	v_fmac_f32_e32 v206, v8, v8
	v_fmac_f32_e32 v206, v9, v9
	v_fmac_f32_e32 v206, v10, v10
	v_fmac_f32_e32 v206, v11, v11
	ds_write_b128 v180, v[8:11] offset:192
	s_waitcnt lgkmcnt(7)
	v_add_f32_e32 v12, v200, v12
	v_add_f32_e32 v13, v201, v13
	v_add_f32_e32 v14, v202, v14
	v_add_f32_e32 v15, v203, v15
	v_fmac_f32_e32 v206, v12, v12
	v_fmac_f32_e32 v206, v13, v13
	v_fmac_f32_e32 v206, v14, v14
	v_fmac_f32_e32 v206, v15, v15
	ds_write_b128 v180, v[12:15] offset:224
	ds_read_b128 v[160:163], v183
	ds_read_b128 v[164:167], v183 offset:1088
	ds_read_b128 v[168:171], v183 offset:2176
	ds_read_b128 v[172:175], v183 offset:3264
	ds_read_b128 v[176:179], v183 offset:4352
	ds_read_b128 v[184:187], v183 offset:5440
	ds_read_b128 v[188:191], v183 offset:6528
	ds_read_b128 v[200:203], v183 offset:7616
	s_add_u32 s74, s66, 0x20100
	s_addc_u32 s75, s67, 0
	s_waitcnt lgkmcnt(7)
	global_store_dwordx4 v193, v[160:163], s[74:75]
	s_add_u32 s74, s66, 0x24100
	s_addc_u32 s75, s67, 0
	s_waitcnt lgkmcnt(6)
	global_store_dwordx4 v193, v[164:167], s[74:75]
	s_add_u32 s74, s66, 0x28100
	s_addc_u32 s75, s67, 0
	s_waitcnt lgkmcnt(5)
	global_store_dwordx4 v193, v[168:171], s[74:75]
	s_add_u32 s74, s66, 0x2c100
	s_addc_u32 s75, s67, 0
	s_waitcnt lgkmcnt(4)
	global_store_dwordx4 v193, v[172:175], s[74:75]
	s_add_u32 s74, s66, 0x30100
	s_addc_u32 s75, s67, 0
	s_waitcnt lgkmcnt(3)
	global_store_dwordx4 v193, v[176:179], s[74:75]
	s_add_u32 s74, s66, 0x34100
	s_addc_u32 s75, s67, 0
	s_waitcnt lgkmcnt(2)
	global_store_dwordx4 v193, v[184:187], s[74:75]
	s_add_u32 s74, s66, 0x38100
	s_addc_u32 s75, s67, 0
	s_waitcnt lgkmcnt(1)
	global_store_dwordx4 v193, v[188:191], s[74:75]
	s_add_u32 s74, s66, 0x3c100
	s_addc_u32 s75, s67, 0
	s_waitcnt lgkmcnt(0)
	global_store_dwordx4 v193, v[200:203], s[74:75]
	s_load_dwordx2 s[64:65], s[92:93], 0x140
	ds_bpermute_b32 v210, v208, v205
	ds_bpermute_b32 v211, v208, v206
	s_waitcnt lgkmcnt(0)
	s_add_u32 s64, s64, 0x30600
	s_addc_u32 s65, s65, 0
	v_add_f32_e32 v210, v210, v205
	v_add_f32_e32 v211, v211, v206
	s_mov_b32 exec_hi, 0
	s_nop 1
	global_atomic_add_f32 v207, v210, s[64:65]
	global_atomic_add_f32 v207, v211, s[64:65] offset:128
	s_mov_b64 exec, -1
	v_readlane_b32 s64, v209, 0
	v_readlane_b32 s65, v209, 1
	v_readlane_b32 s66, v209, 2
	v_readlane_b32 s67, v209, 3
	v_readlane_b32 s68, v209, 4
	v_readlane_b32 s69, v209, 5
	v_readlane_b32 s70, v209, 6
	v_readlane_b32 s71, v209, 7
	v_readlane_b32 s72, v209, 8
	v_readlane_b32 s73, v209, 9
	v_readlane_b32 s74, v209, 10
	v_readlane_b32 s75, v209, 11
	v_readlane_b32 s76, v209, 12
	v_readlane_b32 s77, v209, 13
	v_readlane_b32 s78, v209, 14
	v_readlane_b32 s79, v209, 15
	s_nop 7
	s_branch .LBB0_1718
